# K-loop first iteration peeled in all 14 GEMM instances (first MFMA per accumulator quad takes C=0): per-tile accumulator zero-init removed
# speedup vs baseline: 1.0353x; 1.0026x over previous
; #define PG8_STAGE(bufoff, gbase, voff) do { _Pragma("unroll") for (int _i = 0; _i < 2; ++_i) \
;         __builtin_amdgcn_global_load_lds((const unsigned*)((const char*)(gbase) + (voff)[_i]), (PG8_LAS unsigned*)(lds + (bufoff) + ldsw + _i * 8192), 16, 0, 0); } while (0)
; #define PG8_LDA(dst, b, h) do { _Pragma("unroll") for (int m = 0; m < 4; ++m) _Pragma("unroll") for (int k = 0; k < 2; ++k) dst[m][k] = *(const PG8_LAS bf16x8*)(lds + PG8_SA(b, h) + aoff + m * 2048 + k * 1024); } while (0)
; #define PG8_LDB(dst, b, h) do { _Pragma("unroll") for (int n = 0; n < 2; ++n) _Pragma("unroll") for (int k = 0; k < 2; ++k) dst[n][k] = *(const PG8_LAS bf16x8*)(lds + PG8_SB(b, h) + boff + n * 2048 + k * 1024); } while (0)
; #define PG8_MMA(ai, bj, At, Bt) do { __builtin_amdgcn_s_setprio(1); _Pragma("unroll") for (int m = 0; m < 4; ++m) _Pragma("unroll") for (int n = 0; n < 2; ++n) _Pragma("unroll") for (int k = 0; k < 2; ++k) \
;         acc[ai][bj][m][n] = __builtin_amdgcn_mfma_f32_16x16x32_bf16(Bt[n][k], At[m][k], acc[ai][bj][m][n], 0, 0, 0); __builtin_amdgcn_s_setprio(0); } while (0)
; #define PG8_WAIT_V(n) asm volatile("s_waitcnt vmcnt(" #n ")" ::: "memory")
; #define PG8_BAR __builtin_amdgcn_s_barrier()
; template <class Epi, class Sched, bool ALIGN_EPI = false, bool SP2 = false>
; __device__ __forceinline__ void gemm_phase(PG8_LAS unsigned char* lds, const Gemm g, const Sched& S, const Epi& E) {
;     ...
;         for (int t = 0; t < nt; t += 2) {
;             const bool last = (t == nt - 2);
;             const char* a1 = cA + (size_t)(t + 1) * kstep;
;             const char* a2 = last ? nA : cA + (size_t)(t + 2) * kstep; const char* b2 = last ? nB : cB + (size_t)(t + 2) * kstep;
;             const char* a3 = a2 + kstep; const char* b3 = b2 + kstep;
;             if (last && has_next) S.a_ready(nxt);
;             if constexpr (SP2) {
;             PG8_LDB(B0, 0, 0); PG8_LDB(B1, 0, 1); PG8_SCHED; PG8_LDA(At, 0, 0); PG8_STAGE(PG8_SA(1, 1), a1 + hstep, voffA);
;             PG8_WAIT_V(8); PG8_WAIT_L(0); PG8_BAR; PG8_MMA(0, 0, At, B0); PG8_MMA(0, 1, At, B1); PG8_BAR; PG8_SCHED;
;             PG8_LDA(At, 0, 1); PG8_STAGE(PG8_SB(0, 0), b2, voffB); PG8_STAGE(PG8_SB(0, 1), b2 + hstep, voffB); PG8_STAGE(PG8_SA(0, 0), a2, voffA);
;             PG8_WAIT_V(8); PG8_WAIT_L(0); PG8_BAR; PG8_MMA(1, 0, At, B0); PG8_MMA(1, 1, At, B1); PG8_BAR; PG8_SCHED;
.LBB0_371:
	s_andn2_b64 vcc, exec, s[14:15]
	s_cbranch_vccnz .LBB0_374
	s_add_u32 s24, s24, 0x80
	s_addc_u32 s25, s25, 0
	s_add_u32 s62, s26, 0x100
	s_addc_u32 s63, s27, 0
	s_mov_b32 s26, 0
	ds_read_b128 v[154:157], v149
	ds_read_b128 v[158:161], v149 offset:1024
	ds_read_b128 v[162:165], v149 offset:2048
	ds_read_b128 v[166:169], v149 offset:3072
	ds_read_b128 v[170:173], v150
	ds_read_b128 v[174:177], v150 offset:1024
	ds_read_b128 v[180:183], v150 offset:2048
	ds_read_b128 v[184:187], v150 offset:3072
	s_add_i32 s64, s26, 2
	s_add_u32 s65, s24, 0x80
	s_addc_u32 s27, s25, 0
	s_cmp_eq_u32 s37, s26
	s_cselect_b32 s26, s0, s65
	s_cselect_b32 s27, s1, s27
	s_cselect_b32 s67, s23, s63
	s_cselect_b32 s66, s22, s62
	v_lshl_add_u64 v[144:145], s[24:25], 0, v[136:137]
	s_add_i32 m0, s28, 0xc000
	ds_read_b128 v[188:191], v151
	ds_read_b128 v[192:195], v151 offset:1024
	ds_read_b128 v[196:199], v151 offset:2048
	ds_read_b128 v[200:203], v151 offset:3072
	ds_read_b128 v[204:207], v151 offset:4096
	ds_read_b128 v[208:211], v151 offset:5120
	ds_read_b128 v[212:215], v151 offset:6144
	ds_read_b128 v[216:219], v151 offset:7168
	global_load_lds_dwordx4 v[144:145], off
	v_lshl_add_u64 v[144:145], s[24:25], 0, v[138:139]
	s_add_i32 m0, s28, 0xe000
	s_nop 0
	global_load_lds_dwordx4 v[144:145], off
	s_waitcnt vmcnt(8)
	s_waitcnt lgkmcnt(0)
	s_barrier
	s_setprio 1
	s_waitcnt lgkmcnt(0)
	v_mfma_f32_16x16x32_bf16 v[116:119], v[154:157], v[188:191], 0
	v_mfma_f32_16x16x32_bf16 v[112:115], v[162:165], v[188:191], 0
	v_mfma_f32_16x16x32_bf16 v[100:103], v[154:157], v[196:199], 0
	v_mfma_f32_16x16x32_bf16 v[96:99], v[162:165], v[196:199], 0
	v_mfma_f32_16x16x32_bf16 v[84:87], v[154:157], v[204:207], 0
	v_mfma_f32_16x16x32_bf16 v[80:83], v[162:165], v[204:207], 0
	v_mfma_f32_16x16x32_bf16 v[68:71], v[154:157], v[212:215], 0
	v_mfma_f32_16x16x32_bf16 v[64:67], v[162:165], v[212:215], 0
	v_mfma_f32_16x16x32_bf16 v[116:119], v[158:161], v[192:195], v[116:119]
	v_mfma_f32_16x16x32_bf16 v[112:115], v[166:169], v[192:195], v[112:115]
	v_mfma_f32_16x16x32_bf16 v[100:103], v[158:161], v[200:203], v[100:103]
	v_mfma_f32_16x16x32_bf16 v[96:99], v[166:169], v[200:203], v[96:99]
	v_mfma_f32_16x16x32_bf16 v[84:87], v[158:161], v[208:211], v[84:87]
	v_mfma_f32_16x16x32_bf16 v[80:83], v[166:169], v[208:211], v[80:83]
	v_mfma_f32_16x16x32_bf16 v[68:71], v[158:161], v[216:219], v[68:71]
	v_mfma_f32_16x16x32_bf16 v[64:67], v[166:169], v[216:219], v[64:67]
	s_setprio 0
	s_setprio 1
	v_mfma_f32_16x16x32_bf16 v[124:127], v[170:173], v[188:191], 0
	v_mfma_f32_16x16x32_bf16 v[120:123], v[180:183], v[188:191], 0
	v_mfma_f32_16x16x32_bf16 v[108:111], v[170:173], v[196:199], 0
	v_mfma_f32_16x16x32_bf16 v[104:107], v[180:183], v[196:199], 0
	v_mfma_f32_16x16x32_bf16 v[92:95], v[170:173], v[204:207], 0
	v_mfma_f32_16x16x32_bf16 v[88:91], v[180:183], v[204:207], 0
	v_mfma_f32_16x16x32_bf16 v[76:79], v[170:173], v[212:215], 0
	v_mfma_f32_16x16x32_bf16 v[72:75], v[180:183], v[212:215], 0
	v_mfma_f32_16x16x32_bf16 v[124:127], v[174:177], v[192:195], v[124:127]
	v_mfma_f32_16x16x32_bf16 v[120:123], v[184:187], v[192:195], v[120:123]
	v_mfma_f32_16x16x32_bf16 v[108:111], v[174:177], v[200:203], v[108:111]
	v_mfma_f32_16x16x32_bf16 v[104:107], v[184:187], v[200:203], v[104:107]
	v_mfma_f32_16x16x32_bf16 v[92:95], v[174:177], v[208:211], v[92:95]
	v_mfma_f32_16x16x32_bf16 v[88:91], v[184:187], v[208:211], v[88:91]
	v_mfma_f32_16x16x32_bf16 v[76:79], v[174:177], v[216:219], v[76:79]
	v_mfma_f32_16x16x32_bf16 v[72:75], v[184:187], v[216:219], v[72:75]
	s_setprio 0
	s_barrier
	s_add_i32 s65, s40, s16
	v_lshl_add_u64 v[144:145], s[66:67], 0, v[132:133]
	s_mov_b32 m0, s65
	ds_read_b128 v[188:191], v151 offset:16384
	ds_read_b128 v[192:195], v151 offset:17408
	ds_read_b128 v[196:199], v151 offset:18432
	ds_read_b128 v[200:203], v151 offset:19456
	ds_read_b128 v[204:207], v151 offset:20480
	ds_read_b128 v[208:211], v151 offset:21504
	ds_read_b128 v[212:215], v151 offset:22528
	ds_read_b128 v[216:219], v151 offset:23552
	global_load_lds_dwordx4 v[144:145], off
	s_add_i32 m0, s65, 0x2000
	v_lshl_add_u64 v[178:179], s[66:67], 0, v[128:129]
	s_add_u32 s66, s66, s6
	s_addc_u32 s67, s67, s7
	s_add_i32 s65, s41, s16
	global_load_lds_dwordx4 v[178:179], off
	v_lshl_add_u64 v[220:221], s[66:67], 0, v[132:133]
	s_mov_b32 m0, s65
	v_lshl_add_u64 v[222:223], s[66:67], 0, v[128:129]
	global_load_lds_dwordx4 v[220:221], off
	s_add_i32 m0, s65, 0x2000
	v_lshl_add_u64 v[224:225], s[26:27], 0, v[134:135]
	global_load_lds_dwordx4 v[222:223], off
	s_mov_b32 m0, s28
	v_lshl_add_u64 v[226:227], s[26:27], 0, v[130:131]
	global_load_lds_dwordx4 v[224:225], off
	s_mov_b32 m0, s29
	s_nop 0
	global_load_lds_dwordx4 v[226:227], off
	s_waitcnt vmcnt(8)
	s_waitcnt lgkmcnt(0)
	s_barrier
; #define PG8_STAGE(bufoff, gbase, voff) do { _Pragma("unroll") for (int _i = 0; _i < 2; ++_i) \
;         __builtin_amdgcn_global_load_lds((const unsigned*)((const char*)(gbase) + (voff)[_i]), (PG8_LAS unsigned*)(lds + (bufoff) + ldsw + _i * 8192), 16, 0, 0); } while (0)
; #define PG8_LDA(dst, b, h) do { _Pragma("unroll") for (int m = 0; m < 4; ++m) _Pragma("unroll") for (int k = 0; k < 2; ++k) dst[m][k] = *(const PG8_LAS bf16x8*)(lds + PG8_SA(b, h) + aoff + m * 2048 + k * 1024); } while (0)
; #define PG8_LDB(dst, b, h) do { _Pragma("unroll") for (int n = 0; n < 2; ++n) _Pragma("unroll") for (int k = 0; k < 2; ++k) dst[n][k] = *(const PG8_LAS bf16x8*)(lds + PG8_SB(b, h) + boff + n * 2048 + k * 1024); } while (0)
; #define PG8_MMA(ai, bj, At, Bt) do { __builtin_amdgcn_s_setprio(1); _Pragma("unroll") for (int m = 0; m < 4; ++m) _Pragma("unroll") for (int n = 0; n < 2; ++n) _Pragma("unroll") for (int k = 0; k < 2; ++k) \
;         acc[ai][bj][m][n] = __builtin_amdgcn_mfma_f32_16x16x32_bf16(Bt[n][k], At[m][k], acc[ai][bj][m][n], 0, 0, 0); __builtin_amdgcn_s_setprio(0); } while (0)
; #define PG8_WAIT_V(n) asm volatile("s_waitcnt vmcnt(" #n ")" ::: "memory")
; #define PG8_WAIT_L(n) asm volatile("s_waitcnt lgkmcnt(" #n ")" ::: "memory")
; #define PG8_BAR __builtin_amdgcn_s_barrier()
; #define PG8_SCHED __builtin_amdgcn_sched_barrier(0)
; template <class Epi, class Sched, bool ALIGN_EPI = false, bool SP2 = false>
; __device__ __forceinline__ void gemm_phase(PG8_LAS unsigned char* lds, const Gemm g, const Sched& S, const Epi& E) {
;     ...
;             PG8_WAIT_V(8); PG8_WAIT_L(0); PG8_BAR; PG8_MMA(1, 0, At, B0); PG8_MMA(1, 1, At, B1); PG8_BAR; PG8_SCHED;
;             PG8_LDB(B0, 1, 0); PG8_LDB(B1, 1, 1); PG8_SCHED; PG8_LDA(At, 1, 0); PG8_STAGE(PG8_SA(0, 1), a2 + hstep, voffA);
;             PG8_WAIT_V(8); PG8_WAIT_L(0); PG8_BAR; PG8_MMA(0, 0, At, B0); PG8_MMA(0, 1, At, B1); PG8_BAR; PG8_SCHED;
	s_setprio 1
	s_waitcnt lgkmcnt(0)
	v_mfma_f32_16x16x32_bf16 v[52:55], v[154:157], v[188:191], 0
	v_mfma_f32_16x16x32_bf16 v[48:51], v[162:165], v[188:191], 0
	v_mfma_f32_16x16x32_bf16 v[36:39], v[154:157], v[196:199], 0
	v_mfma_f32_16x16x32_bf16 v[32:35], v[162:165], v[196:199], 0
	v_mfma_f32_16x16x32_bf16 v[20:23], v[154:157], v[204:207], 0
	v_mfma_f32_16x16x32_bf16 v[16:19], v[162:165], v[204:207], 0
	v_mfma_f32_16x16x32_bf16 v[4:7], v[154:157], v[212:215], 0
	v_mfma_f32_16x16x32_bf16 v[0:3], v[162:165], v[212:215], 0
	v_mfma_f32_16x16x32_bf16 v[52:55], v[158:161], v[192:195], v[52:55]
	v_mfma_f32_16x16x32_bf16 v[48:51], v[166:169], v[192:195], v[48:51]
	v_mfma_f32_16x16x32_bf16 v[36:39], v[158:161], v[200:203], v[36:39]
	v_mfma_f32_16x16x32_bf16 v[32:35], v[166:169], v[200:203], v[32:35]
	v_mfma_f32_16x16x32_bf16 v[20:23], v[158:161], v[208:211], v[20:23]
	v_mfma_f32_16x16x32_bf16 v[16:19], v[166:169], v[208:211], v[16:19]
	v_mfma_f32_16x16x32_bf16 v[4:7], v[158:161], v[216:219], v[4:7]
	v_mfma_f32_16x16x32_bf16 v[0:3], v[166:169], v[216:219], v[0:3]
	s_setprio 0
	s_setprio 1
	v_mfma_f32_16x16x32_bf16 v[60:63], v[170:173], v[188:191], 0
	v_mfma_f32_16x16x32_bf16 v[56:59], v[180:183], v[188:191], 0
	v_mfma_f32_16x16x32_bf16 v[44:47], v[170:173], v[196:199], 0
	v_mfma_f32_16x16x32_bf16 v[40:43], v[180:183], v[196:199], 0
	v_mfma_f32_16x16x32_bf16 v[28:31], v[170:173], v[204:207], 0
	v_mfma_f32_16x16x32_bf16 v[24:27], v[180:183], v[204:207], 0
	v_mfma_f32_16x16x32_bf16 v[12:15], v[170:173], v[212:215], 0
	v_mfma_f32_16x16x32_bf16 v[8:11], v[180:183], v[212:215], 0
	v_mfma_f32_16x16x32_bf16 v[60:63], v[174:177], v[192:195], v[60:63]
	v_mfma_f32_16x16x32_bf16 v[56:59], v[184:187], v[192:195], v[56:59]
	v_mfma_f32_16x16x32_bf16 v[44:47], v[174:177], v[200:203], v[44:47]
	v_mfma_f32_16x16x32_bf16 v[40:43], v[184:187], v[200:203], v[40:43]
	v_mfma_f32_16x16x32_bf16 v[28:31], v[174:177], v[208:211], v[28:31]
	v_mfma_f32_16x16x32_bf16 v[24:27], v[184:187], v[208:211], v[24:27]
	v_mfma_f32_16x16x32_bf16 v[12:15], v[174:177], v[216:219], v[12:15]
	v_mfma_f32_16x16x32_bf16 v[8:11], v[184:187], v[216:219], v[8:11]
	s_setprio 0
	s_barrier
	s_add_i32 s65, 0, 0x18000
	v_add_u32_e32 v153, s65, v147
	s_add_i32 s66, 0, 0x1c000
	ds_read_b128 v[154:157], v153
	ds_read_b128 v[158:161], v153 offset:1024
	ds_read_b128 v[162:165], v153 offset:2048
	ds_read_b128 v[166:169], v153 offset:3072
	v_add_u32_e32 v153, s66, v147
	ds_read_b128 v[170:173], v153
	ds_read_b128 v[174:177], v153 offset:1024
	ds_read_b128 v[180:183], v153 offset:2048
	ds_read_b128 v[184:187], v153 offset:3072
	s_add_u32 s26, s26, s6
	s_addc_u32 s27, s27, s7
	s_mov_b32 m0, s30
	v_lshl_add_u64 v[228:229], s[26:27], 0, v[134:135]
	ds_read_b128 v[188:191], v151 offset:32768
	ds_read_b128 v[192:195], v151 offset:33792
	ds_read_b128 v[196:199], v151 offset:34816
	ds_read_b128 v[200:203], v151 offset:35840
	ds_read_b128 v[204:207], v151 offset:36864
	ds_read_b128 v[208:211], v151 offset:37888
	ds_read_b128 v[212:215], v151 offset:38912
	ds_read_b128 v[216:219], v151 offset:39936
	global_load_lds_dwordx4 v[228:229], off
	v_lshl_add_u64 v[228:229], s[26:27], 0, v[130:131]
	s_mov_b32 m0, s31
	s_nop 0
	global_load_lds_dwordx4 v[228:229], off
	s_waitcnt vmcnt(8)
	s_waitcnt lgkmcnt(0)
	s_barrier
	s_setprio 1
	s_waitcnt lgkmcnt(0)
	v_mfma_f32_16x16x32_bf16 v[116:119], v[154:157], v[188:191], v[116:119]
	v_mfma_f32_16x16x32_bf16 v[112:115], v[162:165], v[188:191], v[112:115]
	v_mfma_f32_16x16x32_bf16 v[100:103], v[154:157], v[196:199], v[100:103]
	v_mfma_f32_16x16x32_bf16 v[96:99], v[162:165], v[196:199], v[96:99]
	v_mfma_f32_16x16x32_bf16 v[84:87], v[154:157], v[204:207], v[84:87]
	v_mfma_f32_16x16x32_bf16 v[80:83], v[162:165], v[204:207], v[80:83]
	v_mfma_f32_16x16x32_bf16 v[68:71], v[154:157], v[212:215], v[68:71]
	v_mfma_f32_16x16x32_bf16 v[64:67], v[162:165], v[212:215], v[64:67]
	v_mfma_f32_16x16x32_bf16 v[116:119], v[158:161], v[192:195], v[116:119]
	v_mfma_f32_16x16x32_bf16 v[112:115], v[166:169], v[192:195], v[112:115]
	v_mfma_f32_16x16x32_bf16 v[100:103], v[158:161], v[200:203], v[100:103]
	v_mfma_f32_16x16x32_bf16 v[96:99], v[166:169], v[200:203], v[96:99]
	v_mfma_f32_16x16x32_bf16 v[84:87], v[158:161], v[208:211], v[84:87]
	v_mfma_f32_16x16x32_bf16 v[80:83], v[166:169], v[208:211], v[80:83]
	v_mfma_f32_16x16x32_bf16 v[68:71], v[158:161], v[216:219], v[68:71]
	v_mfma_f32_16x16x32_bf16 v[64:67], v[166:169], v[216:219], v[64:67]
	s_setprio 0
	s_setprio 1
	v_mfma_f32_16x16x32_bf16 v[124:127], v[170:173], v[188:191], v[124:127]
	v_mfma_f32_16x16x32_bf16 v[120:123], v[180:183], v[188:191], v[120:123]
	v_mfma_f32_16x16x32_bf16 v[108:111], v[170:173], v[196:199], v[108:111]
	v_mfma_f32_16x16x32_bf16 v[104:107], v[180:183], v[196:199], v[104:107]
	v_mfma_f32_16x16x32_bf16 v[92:95], v[170:173], v[204:207], v[92:95]
	v_mfma_f32_16x16x32_bf16 v[88:91], v[180:183], v[204:207], v[88:91]
	v_mfma_f32_16x16x32_bf16 v[76:79], v[170:173], v[212:215], v[76:79]
	v_mfma_f32_16x16x32_bf16 v[72:75], v[180:183], v[212:215], v[72:75]
	v_mfma_f32_16x16x32_bf16 v[124:127], v[174:177], v[192:195], v[124:127]
	v_mfma_f32_16x16x32_bf16 v[120:123], v[184:187], v[192:195], v[120:123]
	v_mfma_f32_16x16x32_bf16 v[108:111], v[174:177], v[200:203], v[108:111]
	v_mfma_f32_16x16x32_bf16 v[104:107], v[184:187], v[200:203], v[104:107]
	v_mfma_f32_16x16x32_bf16 v[92:95], v[174:177], v[208:211], v[92:95]
	v_mfma_f32_16x16x32_bf16 v[88:91], v[184:187], v[208:211], v[88:91]
	v_mfma_f32_16x16x32_bf16 v[76:79], v[174:177], v[216:219], v[76:79]
	v_mfma_f32_16x16x32_bf16 v[72:75], v[184:187], v[216:219], v[72:75]
	s_setprio 0
	s_barrier
; #define PG8_STAGE(bufoff, gbase, voff) do { _Pragma("unroll") for (int _i = 0; _i < 2; ++_i) \
;         __builtin_amdgcn_global_load_lds((const unsigned*)((const char*)(gbase) + (voff)[_i]), (PG8_LAS unsigned*)(lds + (bufoff) + ldsw + _i * 8192), 16, 0, 0); } while (0)
; #define PG8_LDA(dst, b, h) do { _Pragma("unroll") for (int m = 0; m < 4; ++m) _Pragma("unroll") for (int k = 0; k < 2; ++k) dst[m][k] = *(const PG8_LAS bf16x8*)(lds + PG8_SA(b, h) + aoff + m * 2048 + k * 1024); } while (0)
; #define PG8_MMA(ai, bj, At, Bt) do { __builtin_amdgcn_s_setprio(1); _Pragma("unroll") for (int m = 0; m < 4; ++m) _Pragma("unroll") for (int n = 0; n < 2; ++n) _Pragma("unroll") for (int k = 0; k < 2; ++k) \
;         acc[ai][bj][m][n] = __builtin_amdgcn_mfma_f32_16x16x32_bf16(Bt[n][k], At[m][k], acc[ai][bj][m][n], 0, 0, 0); __builtin_amdgcn_s_setprio(0); } while (0)
; #define PG8_WAIT_V(n) asm volatile("s_waitcnt vmcnt(" #n ")" ::: "memory")
; #define PG8_WAIT_L(n) asm volatile("s_waitcnt lgkmcnt(" #n ")" ::: "memory")
; #define PG8_BAR __builtin_amdgcn_s_barrier()
; #define PG8_SCHED __builtin_amdgcn_sched_barrier(0)
; template <class Epi, class Sched, bool ALIGN_EPI = false, bool SP2 = false>
; __device__ __forceinline__ void gemm_phase(PG8_LAS unsigned char* lds, const Gemm g, const Sched& S, const Epi& E) {
;     ...
;             PG8_LDA(At, 1, 1); PG8_STAGE(PG8_SB(1, 0), b3, voffB); PG8_STAGE(PG8_SB(1, 1), b3 + hstep, voffB); PG8_STAGE(PG8_SA(1, 0), a3, voffA);
;             PG8_WAIT_V(8); PG8_WAIT_L(0); PG8_BAR; PG8_MMA(1, 0, At, B0); PG8_MMA(1, 1, At, B1); PG8_BAR; PG8_SCHED;
	s_add_i32 s26, s65, s16
	v_lshl_add_u64 v[144:145], v[144:145], 0, s[12:13]
	s_mov_b32 m0, s26
	ds_read_b128 v[188:191], v151 offset:49152
	ds_read_b128 v[192:195], v151 offset:50176
	ds_read_b128 v[196:199], v151 offset:51200
	ds_read_b128 v[200:203], v151 offset:52224
	ds_read_b128 v[204:207], v151 offset:53248
	ds_read_b128 v[208:211], v151 offset:54272
	ds_read_b128 v[212:215], v151 offset:55296
	ds_read_b128 v[216:219], v151 offset:56320
	global_load_lds_dwordx4 v[144:145], off
	v_lshl_add_u64 v[144:145], v[178:179], 0, s[12:13]
	s_add_i32 m0, s26, 0x2000
	s_add_i32 s26, s66, s16
	global_load_lds_dwordx4 v[144:145], off
	v_lshl_add_u64 v[144:145], v[220:221], 0, s[12:13]
	s_mov_b32 m0, s26
	s_nop 0
	global_load_lds_dwordx4 v[144:145], off
	v_lshl_add_u64 v[144:145], v[222:223], 0, s[12:13]
	s_add_i32 m0, s26, 0x2000
	s_nop 0
	global_load_lds_dwordx4 v[144:145], off
	v_lshl_add_u64 v[144:145], v[224:225], 0, s[12:13]
	s_mov_b32 m0, s34
	s_nop 0
	global_load_lds_dwordx4 v[144:145], off
	v_lshl_add_u64 v[144:145], v[226:227], 0, s[12:13]
	s_mov_b32 m0, s35
	s_nop 0
	global_load_lds_dwordx4 v[144:145], off
	s_waitcnt vmcnt(8)
	s_waitcnt lgkmcnt(0)
	s_barrier
	s_setprio 1
	s_waitcnt lgkmcnt(0)
	v_mfma_f32_16x16x32_bf16 v[52:55], v[154:157], v[188:191], v[52:55]
	v_mfma_f32_16x16x32_bf16 v[48:51], v[162:165], v[188:191], v[48:51]
	v_mfma_f32_16x16x32_bf16 v[36:39], v[154:157], v[196:199], v[36:39]
	v_mfma_f32_16x16x32_bf16 v[32:35], v[162:165], v[196:199], v[32:35]
	v_mfma_f32_16x16x32_bf16 v[20:23], v[154:157], v[204:207], v[20:23]
	v_mfma_f32_16x16x32_bf16 v[16:19], v[162:165], v[204:207], v[16:19]
	v_mfma_f32_16x16x32_bf16 v[4:7], v[154:157], v[212:215], v[4:7]
	v_mfma_f32_16x16x32_bf16 v[0:3], v[162:165], v[212:215], v[0:3]
	v_mfma_f32_16x16x32_bf16 v[52:55], v[158:161], v[192:195], v[52:55]
	v_mfma_f32_16x16x32_bf16 v[48:51], v[166:169], v[192:195], v[48:51]
	v_mfma_f32_16x16x32_bf16 v[36:39], v[158:161], v[200:203], v[36:39]
	v_mfma_f32_16x16x32_bf16 v[32:35], v[166:169], v[200:203], v[32:35]
	v_mfma_f32_16x16x32_bf16 v[20:23], v[158:161], v[208:211], v[20:23]
	v_mfma_f32_16x16x32_bf16 v[16:19], v[166:169], v[208:211], v[16:19]
	v_mfma_f32_16x16x32_bf16 v[4:7], v[158:161], v[216:219], v[4:7]
	v_mfma_f32_16x16x32_bf16 v[0:3], v[166:169], v[216:219], v[0:3]
	s_setprio 0
	s_setprio 1
	v_mfma_f32_16x16x32_bf16 v[60:63], v[170:173], v[188:191], v[60:63]
	v_mfma_f32_16x16x32_bf16 v[56:59], v[180:183], v[188:191], v[56:59]
	v_mfma_f32_16x16x32_bf16 v[44:47], v[170:173], v[196:199], v[44:47]
	v_mfma_f32_16x16x32_bf16 v[40:43], v[180:183], v[196:199], v[40:43]
	v_mfma_f32_16x16x32_bf16 v[28:31], v[170:173], v[204:207], v[28:31]
	v_mfma_f32_16x16x32_bf16 v[24:27], v[180:183], v[204:207], v[24:27]
	v_mfma_f32_16x16x32_bf16 v[12:15], v[170:173], v[212:215], v[12:15]
	v_mfma_f32_16x16x32_bf16 v[8:11], v[180:183], v[212:215], v[8:11]
	v_mfma_f32_16x16x32_bf16 v[60:63], v[174:177], v[192:195], v[60:63]
	v_mfma_f32_16x16x32_bf16 v[56:59], v[184:187], v[192:195], v[56:59]
	v_mfma_f32_16x16x32_bf16 v[44:47], v[174:177], v[200:203], v[44:47]
	v_mfma_f32_16x16x32_bf16 v[40:43], v[184:187], v[200:203], v[40:43]
	v_mfma_f32_16x16x32_bf16 v[28:31], v[174:177], v[208:211], v[28:31]
	v_mfma_f32_16x16x32_bf16 v[24:27], v[184:187], v[208:211], v[24:27]
	v_mfma_f32_16x16x32_bf16 v[12:15], v[174:177], v[216:219], v[12:15]
	v_mfma_f32_16x16x32_bf16 v[8:11], v[184:187], v[216:219], v[8:11]
	s_setprio 0
	s_barrier
	s_add_u32 s24, s24, 0x100
	s_addc_u32 s25, s25, 0
	s_add_u32 s62, s62, 0x100
	s_addc_u32 s63, s63, 0
	s_cmp_ge_i32 s64, s36
	s_mov_b32 s26, s64
	s_cbranch_scc0 .LBB0_373
	s_branch .Lpeel_x0

; #define PG8_BAR __builtin_amdgcn_s_barrier()
; template <class Epi, class Sched, bool ALIGN_EPI = false, bool SP2 = false>
; __device__ __forceinline__ void gemm_phase(PG8_LAS unsigned char* lds, const Gemm g, const Sched& S, const Epi& E) {
;     ...
;         }
;         if constexpr (ALIGN_EPI) { if (wr == 0) PG8_BAR; }
.Lpeel_x0:
.LBB0_374:
	s_and_b64 vcc, exec, s[20:21]
	s_cbranch_vccz .LBB0_376
	s_barrier

; #define PG8_STAGE(bufoff, gbase, voff) do { _Pragma("unroll") for (int _i = 0; _i < 2; ++_i) \
;         __builtin_amdgcn_global_load_lds((const unsigned*)((const char*)(gbase) + (voff)[_i]), (PG8_LAS unsigned*)(lds + (bufoff) + ldsw + _i * 8192), 16, 0, 0); } while (0)
; #define PG8_LDA(dst, b, h) do { _Pragma("unroll") for (int m = 0; m < 4; ++m) _Pragma("unroll") for (int k = 0; k < 2; ++k) dst[m][k] = *(const PG8_LAS bf16x8*)(lds + PG8_SA(b, h) + aoff + m * 2048 + k * 1024); } while (0)
; #define PG8_LDB(dst, b, h) do { _Pragma("unroll") for (int n = 0; n < 2; ++n) _Pragma("unroll") for (int k = 0; k < 2; ++k) dst[n][k] = *(const PG8_LAS bf16x8*)(lds + PG8_SB(b, h) + boff + n * 2048 + k * 1024); } while (0)
; #define PG8_MMA(ai, bj, At, Bt) do { __builtin_amdgcn_s_setprio(1); _Pragma("unroll") for (int m = 0; m < 4; ++m) _Pragma("unroll") for (int n = 0; n < 2; ++n) _Pragma("unroll") for (int k = 0; k < 2; ++k) \
;         acc[ai][bj][m][n] = __builtin_amdgcn_mfma_f32_16x16x32_bf16(Bt[n][k], At[m][k], acc[ai][bj][m][n], 0, 0, 0); __builtin_amdgcn_s_setprio(0); } while (0)
; #define PG8_WAIT_V(n) asm volatile("s_waitcnt vmcnt(" #n ")" ::: "memory")
; #define PG8_BAR __builtin_amdgcn_s_barrier()
; template <class Epi, class Sched, bool ALIGN_EPI = false, bool SP2 = false>
; __device__ __forceinline__ void gemm_phase(PG8_LAS unsigned char* lds, const Gemm g, const Sched& S, const Epi& E) {
;     ...
;         for (int t = 0; t < nt; t += 2) {
;             const bool last = (t == nt - 2);
;             const char* a1 = cA + (size_t)(t + 1) * kstep;
;             const char* a2 = last ? nA : cA + (size_t)(t + 2) * kstep; const char* b2 = last ? nB : cB + (size_t)(t + 2) * kstep;
;             const char* a3 = a2 + kstep; const char* b3 = b2 + kstep;
;             if (last && has_next) S.a_ready(nxt);
;             if constexpr (SP2) {
;             PG8_LDB(B0, 0, 0); PG8_LDB(B1, 0, 1); PG8_SCHED; PG8_LDA(At, 0, 0); PG8_STAGE(PG8_SA(1, 1), a1 + hstep, voffA);
;             PG8_WAIT_V(8); PG8_WAIT_L(0); PG8_BAR; PG8_MMA(0, 0, At, B0); PG8_MMA(0, 1, At, B1); PG8_BAR; PG8_SCHED;
;             PG8_LDA(At, 0, 1); PG8_STAGE(PG8_SB(0, 0), b2, voffB); PG8_STAGE(PG8_SB(0, 1), b2 + hstep, voffB); PG8_STAGE(PG8_SA(0, 0), a2, voffA);
;             PG8_WAIT_V(8); PG8_WAIT_L(0); PG8_BAR; PG8_MMA(1, 0, At, B0); PG8_MMA(1, 1, At, B1); PG8_BAR; PG8_SCHED;
.LBB0_465:
	v_mov_b32_e32 v151, 0
	s_andn2_b64 vcc, exec, s[24:25]
	v_mov_b32_e32 v150, 0
	v_mov_b32_e32 v155, 0
	v_mov_b32_e32 v154, 0
	v_mov_b32_e32 v153, 0
	v_mov_b32_e32 v152, 0
	v_mov_b32_e32 v149, 0
	v_mov_b32_e32 v148, 0
	v_mov_b32_e32 v145, 0
	v_mov_b32_e32 v144, 0
	v_mov_b32_e32 v147, 0
	v_mov_b32_e32 v146, 0
	s_waitcnt lgkmcnt(0)
	s_cbranch_vccnz .LBB0_469
	s_add_u32 s30, s30, 0x80
	s_addc_u32 s31, s31, 0
	s_add_u32 s65, s34, 0x100
	s_addc_u32 s66, s35, 0
	s_mov_b32 s34, 0
	ds_read_b128 v[144:147], v159
	ds_read_b128 v[148:151], v159 offset:1024
	ds_read_b128 v[152:155], v159 offset:2048
	ds_read_b128 v[164:167], v159 offset:3072
	ds_read_b128 v[168:171], v160
	ds_read_b128 v[172:175], v160 offset:1024
	ds_read_b128 v[180:183], v160 offset:2048
	ds_read_b128 v[184:187], v160 offset:3072
	s_add_i32 s67, s34, 2
	s_add_u32 s68, s30, 0x80
	s_addc_u32 s35, s31, 0
	s_cmp_eq_u32 s41, s34
	s_cselect_b32 s34, s0, s68
	s_cselect_b32 s35, s1, s35
	s_cselect_b32 s69, s29, s66
	s_cselect_b32 s68, s28, s65
	v_lshl_add_u64 v[176:177], s[30:31], 0, v[136:137]
	s_add_i32 m0, s17, 0xc000
	ds_read_b128 v[188:191], v161
	ds_read_b128 v[192:195], v161 offset:1024
	ds_read_b128 v[196:199], v161 offset:2048
	ds_read_b128 v[200:203], v161 offset:3072
	ds_read_b128 v[204:207], v161 offset:4096
	ds_read_b128 v[208:211], v161 offset:5120
	ds_read_b128 v[212:215], v161 offset:6144
	ds_read_b128 v[216:219], v161 offset:7168
	global_load_lds_dwordx4 v[176:177], off
	v_lshl_add_u64 v[176:177], s[30:31], 0, v[138:139]
	s_add_i32 m0, s17, 0xe000
	s_nop 0
	global_load_lds_dwordx4 v[176:177], off
	s_waitcnt vmcnt(8)
	s_waitcnt lgkmcnt(0)
	s_barrier
	s_setprio 1
	s_waitcnt lgkmcnt(0)
	v_mfma_f32_16x16x32_bf16 v[124:127], v[144:147], v[188:191], 0
	v_mfma_f32_16x16x32_bf16 v[120:123], v[152:155], v[188:191], 0
	v_mfma_f32_16x16x32_bf16 v[116:119], v[144:147], v[196:199], 0
	v_mfma_f32_16x16x32_bf16 v[112:115], v[152:155], v[196:199], 0
	v_mfma_f32_16x16x32_bf16 v[104:107], v[144:147], v[204:207], 0
	v_mfma_f32_16x16x32_bf16 v[96:99], v[152:155], v[204:207], 0
	v_mfma_f32_16x16x32_bf16 v[88:91], v[144:147], v[212:215], 0
	v_mfma_f32_16x16x32_bf16 v[80:83], v[152:155], v[212:215], 0
	v_mfma_f32_16x16x32_bf16 v[124:127], v[148:151], v[192:195], v[124:127]
	v_mfma_f32_16x16x32_bf16 v[120:123], v[164:167], v[192:195], v[120:123]
	v_mfma_f32_16x16x32_bf16 v[116:119], v[148:151], v[200:203], v[116:119]
	v_mfma_f32_16x16x32_bf16 v[112:115], v[164:167], v[200:203], v[112:115]
	v_mfma_f32_16x16x32_bf16 v[104:107], v[148:151], v[208:211], v[104:107]
	v_mfma_f32_16x16x32_bf16 v[96:99], v[164:167], v[208:211], v[96:99]
	v_mfma_f32_16x16x32_bf16 v[88:91], v[148:151], v[216:219], v[88:91]
	v_mfma_f32_16x16x32_bf16 v[80:83], v[164:167], v[216:219], v[80:83]
	s_setprio 0
	s_setprio 1
	v_mfma_f32_16x16x32_bf16 v[108:111], v[168:171], v[188:191], 0
	v_mfma_f32_16x16x32_bf16 v[100:103], v[180:183], v[188:191], 0
	v_mfma_f32_16x16x32_bf16 v[92:95], v[168:171], v[196:199], 0
	v_mfma_f32_16x16x32_bf16 v[84:87], v[180:183], v[196:199], 0
	v_mfma_f32_16x16x32_bf16 v[76:79], v[168:171], v[204:207], 0
	v_mfma_f32_16x16x32_bf16 v[72:75], v[180:183], v[204:207], 0
	v_mfma_f32_16x16x32_bf16 v[68:71], v[168:171], v[212:215], 0
	v_mfma_f32_16x16x32_bf16 v[64:67], v[180:183], v[212:215], 0
	v_mfma_f32_16x16x32_bf16 v[108:111], v[172:175], v[192:195], v[108:111]
	v_mfma_f32_16x16x32_bf16 v[100:103], v[184:187], v[192:195], v[100:103]
	v_mfma_f32_16x16x32_bf16 v[92:95], v[172:175], v[200:203], v[92:95]
	v_mfma_f32_16x16x32_bf16 v[84:87], v[184:187], v[200:203], v[84:87]
	v_mfma_f32_16x16x32_bf16 v[76:79], v[172:175], v[208:211], v[76:79]
	v_mfma_f32_16x16x32_bf16 v[72:75], v[184:187], v[208:211], v[72:75]
	v_mfma_f32_16x16x32_bf16 v[68:71], v[172:175], v[216:219], v[68:71]
	v_mfma_f32_16x16x32_bf16 v[64:67], v[184:187], v[216:219], v[64:67]
	s_setprio 0
	s_barrier
	s_add_i32 s70, s59, s16
	v_lshl_add_u64 v[176:177], s[68:69], 0, v[130:131]
	s_mov_b32 m0, s70
	ds_read_b128 v[188:191], v161 offset:16384
	ds_read_b128 v[192:195], v161 offset:17408
	ds_read_b128 v[196:199], v161 offset:18432
	ds_read_b128 v[200:203], v161 offset:19456
	ds_read_b128 v[204:207], v161 offset:20480
	ds_read_b128 v[208:211], v161 offset:21504
	ds_read_b128 v[212:215], v161 offset:22528
	ds_read_b128 v[216:219], v161 offset:23552
	global_load_lds_dwordx4 v[176:177], off
	s_add_i32 m0, s70, 0x2000
	v_lshl_add_u64 v[178:179], s[68:69], 0, v[134:135]
	s_add_u32 s68, s68, s6
	s_addc_u32 s69, s69, s7
	s_add_i32 s70, s60, s16
	global_load_lds_dwordx4 v[178:179], off
	v_lshl_add_u64 v[220:221], s[68:69], 0, v[130:131]
	s_mov_b32 m0, s70
	v_lshl_add_u64 v[222:223], s[68:69], 0, v[134:135]
	global_load_lds_dwordx4 v[220:221], off
	s_add_i32 m0, s70, 0x2000
	v_lshl_add_u64 v[224:225], s[34:35], 0, v[128:129]
	global_load_lds_dwordx4 v[222:223], off
	s_mov_b32 m0, s17
	v_lshl_add_u64 v[226:227], s[34:35], 0, v[132:133]
	global_load_lds_dwordx4 v[224:225], off
	s_mov_b32 m0, s19
	s_nop 0
	global_load_lds_dwordx4 v[226:227], off
	s_waitcnt vmcnt(8)
	s_waitcnt lgkmcnt(0)
	s_barrier
; #define PG8_STAGE(bufoff, gbase, voff) do { _Pragma("unroll") for (int _i = 0; _i < 2; ++_i) \
;         __builtin_amdgcn_global_load_lds((const unsigned*)((const char*)(gbase) + (voff)[_i]), (PG8_LAS unsigned*)(lds + (bufoff) + ldsw + _i * 8192), 16, 0, 0); } while (0)
; #define PG8_LDA(dst, b, h) do { _Pragma("unroll") for (int m = 0; m < 4; ++m) _Pragma("unroll") for (int k = 0; k < 2; ++k) dst[m][k] = *(const PG8_LAS bf16x8*)(lds + PG8_SA(b, h) + aoff + m * 2048 + k * 1024); } while (0)
; #define PG8_LDB(dst, b, h) do { _Pragma("unroll") for (int n = 0; n < 2; ++n) _Pragma("unroll") for (int k = 0; k < 2; ++k) dst[n][k] = *(const PG8_LAS bf16x8*)(lds + PG8_SB(b, h) + boff + n * 2048 + k * 1024); } while (0)
; #define PG8_MMA(ai, bj, At, Bt) do { __builtin_amdgcn_s_setprio(1); _Pragma("unroll") for (int m = 0; m < 4; ++m) _Pragma("unroll") for (int n = 0; n < 2; ++n) _Pragma("unroll") for (int k = 0; k < 2; ++k) \
;         acc[ai][bj][m][n] = __builtin_amdgcn_mfma_f32_16x16x32_bf16(Bt[n][k], At[m][k], acc[ai][bj][m][n], 0, 0, 0); __builtin_amdgcn_s_setprio(0); } while (0)
; #define PG8_WAIT_V(n) asm volatile("s_waitcnt vmcnt(" #n ")" ::: "memory")
; #define PG8_WAIT_L(n) asm volatile("s_waitcnt lgkmcnt(" #n ")" ::: "memory")
; #define PG8_BAR __builtin_amdgcn_s_barrier()
; #define PG8_SCHED __builtin_amdgcn_sched_barrier(0)
; template <class Epi, class Sched, bool ALIGN_EPI = false, bool SP2 = false>
; __device__ __forceinline__ void gemm_phase(PG8_LAS unsigned char* lds, const Gemm g, const Sched& S, const Epi& E) {
;     ...
;             PG8_WAIT_V(8); PG8_WAIT_L(0); PG8_BAR; PG8_MMA(1, 0, At, B0); PG8_MMA(1, 1, At, B1); PG8_BAR; PG8_SCHED;
;             PG8_LDB(B0, 1, 0); PG8_LDB(B1, 1, 1); PG8_SCHED; PG8_LDA(At, 1, 0); PG8_STAGE(PG8_SA(0, 1), a2 + hstep, voffA);
;             PG8_WAIT_V(8); PG8_WAIT_L(0); PG8_BAR; PG8_MMA(0, 0, At, B0); PG8_MMA(0, 1, At, B1); PG8_BAR; PG8_SCHED;
	s_setprio 1
	s_waitcnt lgkmcnt(0)
	v_mfma_f32_16x16x32_bf16 v[60:63], v[144:147], v[188:191], 0
	v_mfma_f32_16x16x32_bf16 v[56:59], v[152:155], v[188:191], 0
	v_mfma_f32_16x16x32_bf16 v[52:55], v[144:147], v[196:199], 0
	v_mfma_f32_16x16x32_bf16 v[48:51], v[152:155], v[196:199], 0
	v_mfma_f32_16x16x32_bf16 v[40:43], v[144:147], v[204:207], 0
	v_mfma_f32_16x16x32_bf16 v[32:35], v[152:155], v[204:207], 0
	v_mfma_f32_16x16x32_bf16 v[24:27], v[144:147], v[212:215], 0
	v_mfma_f32_16x16x32_bf16 v[16:19], v[152:155], v[212:215], 0
	v_mfma_f32_16x16x32_bf16 v[60:63], v[148:151], v[192:195], v[60:63]
	v_mfma_f32_16x16x32_bf16 v[56:59], v[164:167], v[192:195], v[56:59]
	v_mfma_f32_16x16x32_bf16 v[52:55], v[148:151], v[200:203], v[52:55]
	v_mfma_f32_16x16x32_bf16 v[48:51], v[164:167], v[200:203], v[48:51]
	v_mfma_f32_16x16x32_bf16 v[40:43], v[148:151], v[208:211], v[40:43]
	v_mfma_f32_16x16x32_bf16 v[32:35], v[164:167], v[208:211], v[32:35]
	v_mfma_f32_16x16x32_bf16 v[24:27], v[148:151], v[216:219], v[24:27]
	v_mfma_f32_16x16x32_bf16 v[16:19], v[164:167], v[216:219], v[16:19]
	s_setprio 0
	s_setprio 1
	v_mfma_f32_16x16x32_bf16 v[44:47], v[168:171], v[188:191], 0
	v_mfma_f32_16x16x32_bf16 v[36:39], v[180:183], v[188:191], 0
	v_mfma_f32_16x16x32_bf16 v[28:31], v[168:171], v[196:199], 0
	v_mfma_f32_16x16x32_bf16 v[20:23], v[180:183], v[196:199], 0
	v_mfma_f32_16x16x32_bf16 v[12:15], v[168:171], v[204:207], 0
	v_mfma_f32_16x16x32_bf16 v[8:11], v[180:183], v[204:207], 0
	v_mfma_f32_16x16x32_bf16 v[4:7], v[168:171], v[212:215], 0
	v_mfma_f32_16x16x32_bf16 v[0:3], v[180:183], v[212:215], 0
	v_mfma_f32_16x16x32_bf16 v[44:47], v[172:175], v[192:195], v[44:47]
	v_mfma_f32_16x16x32_bf16 v[36:39], v[184:187], v[192:195], v[36:39]
	v_mfma_f32_16x16x32_bf16 v[28:31], v[172:175], v[200:203], v[28:31]
	v_mfma_f32_16x16x32_bf16 v[20:23], v[184:187], v[200:203], v[20:23]
	v_mfma_f32_16x16x32_bf16 v[12:15], v[172:175], v[208:211], v[12:15]
	v_mfma_f32_16x16x32_bf16 v[8:11], v[184:187], v[208:211], v[8:11]
	v_mfma_f32_16x16x32_bf16 v[4:7], v[172:175], v[216:219], v[4:7]
	v_mfma_f32_16x16x32_bf16 v[0:3], v[184:187], v[216:219], v[0:3]
	s_setprio 0
	s_barrier
	s_add_i32 s68, 0, 0x18000
	v_add_u32_e32 v163, s68, v157
	s_add_i32 s69, 0, 0x1c000
	ds_read_b128 v[144:147], v163
	ds_read_b128 v[148:151], v163 offset:1024
	ds_read_b128 v[152:155], v163 offset:2048
	ds_read_b128 v[164:167], v163 offset:3072
	v_add_u32_e32 v163, s69, v157
	ds_read_b128 v[168:171], v163
	ds_read_b128 v[172:175], v163 offset:1024
	ds_read_b128 v[180:183], v163 offset:2048
	ds_read_b128 v[184:187], v163 offset:3072
	s_add_u32 s34, s34, s6
	s_addc_u32 s35, s35, s7
	s_mov_b32 m0, s33
	v_lshl_add_u64 v[228:229], s[34:35], 0, v[128:129]
	ds_read_b128 v[188:191], v161 offset:32768
	ds_read_b128 v[192:195], v161 offset:33792
	ds_read_b128 v[196:199], v161 offset:34816
	ds_read_b128 v[200:203], v161 offset:35840
	ds_read_b128 v[204:207], v161 offset:36864
	ds_read_b128 v[208:211], v161 offset:37888
	ds_read_b128 v[212:215], v161 offset:38912
	ds_read_b128 v[216:219], v161 offset:39936
	global_load_lds_dwordx4 v[228:229], off
	v_lshl_add_u64 v[228:229], s[34:35], 0, v[132:133]
	s_mov_b32 m0, s36
	s_nop 0
	global_load_lds_dwordx4 v[228:229], off
	s_waitcnt vmcnt(8)
	s_waitcnt lgkmcnt(0)
	s_barrier
	s_setprio 1
	s_waitcnt lgkmcnt(0)
	v_mfma_f32_16x16x32_bf16 v[124:127], v[144:147], v[188:191], v[124:127]
	v_mfma_f32_16x16x32_bf16 v[120:123], v[152:155], v[188:191], v[120:123]
	v_mfma_f32_16x16x32_bf16 v[116:119], v[144:147], v[196:199], v[116:119]
	v_mfma_f32_16x16x32_bf16 v[112:115], v[152:155], v[196:199], v[112:115]
	v_mfma_f32_16x16x32_bf16 v[104:107], v[144:147], v[204:207], v[104:107]
	v_mfma_f32_16x16x32_bf16 v[96:99], v[152:155], v[204:207], v[96:99]
	v_mfma_f32_16x16x32_bf16 v[88:91], v[144:147], v[212:215], v[88:91]
	v_mfma_f32_16x16x32_bf16 v[80:83], v[152:155], v[212:215], v[80:83]
	v_mfma_f32_16x16x32_bf16 v[124:127], v[148:151], v[192:195], v[124:127]
	v_mfma_f32_16x16x32_bf16 v[120:123], v[164:167], v[192:195], v[120:123]
	v_mfma_f32_16x16x32_bf16 v[116:119], v[148:151], v[200:203], v[116:119]
	v_mfma_f32_16x16x32_bf16 v[112:115], v[164:167], v[200:203], v[112:115]
	v_mfma_f32_16x16x32_bf16 v[104:107], v[148:151], v[208:211], v[104:107]
	v_mfma_f32_16x16x32_bf16 v[96:99], v[164:167], v[208:211], v[96:99]
	v_mfma_f32_16x16x32_bf16 v[88:91], v[148:151], v[216:219], v[88:91]
	v_mfma_f32_16x16x32_bf16 v[80:83], v[164:167], v[216:219], v[80:83]
	s_setprio 0
	s_setprio 1
	v_mfma_f32_16x16x32_bf16 v[108:111], v[168:171], v[188:191], v[108:111]
	v_mfma_f32_16x16x32_bf16 v[100:103], v[180:183], v[188:191], v[100:103]
	v_mfma_f32_16x16x32_bf16 v[92:95], v[168:171], v[196:199], v[92:95]
	v_mfma_f32_16x16x32_bf16 v[84:87], v[180:183], v[196:199], v[84:87]
	v_mfma_f32_16x16x32_bf16 v[76:79], v[168:171], v[204:207], v[76:79]
	v_mfma_f32_16x16x32_bf16 v[72:75], v[180:183], v[204:207], v[72:75]
	v_mfma_f32_16x16x32_bf16 v[68:71], v[168:171], v[212:215], v[68:71]
	v_mfma_f32_16x16x32_bf16 v[64:67], v[180:183], v[212:215], v[64:67]
	v_mfma_f32_16x16x32_bf16 v[108:111], v[172:175], v[192:195], v[108:111]
	v_mfma_f32_16x16x32_bf16 v[100:103], v[184:187], v[192:195], v[100:103]
	v_mfma_f32_16x16x32_bf16 v[92:95], v[172:175], v[200:203], v[92:95]
	v_mfma_f32_16x16x32_bf16 v[84:87], v[184:187], v[200:203], v[84:87]
	v_mfma_f32_16x16x32_bf16 v[76:79], v[172:175], v[208:211], v[76:79]
	v_mfma_f32_16x16x32_bf16 v[72:75], v[184:187], v[208:211], v[72:75]
	v_mfma_f32_16x16x32_bf16 v[68:71], v[172:175], v[216:219], v[68:71]
	v_mfma_f32_16x16x32_bf16 v[64:67], v[184:187], v[216:219], v[64:67]
	s_setprio 0
	s_barrier
; #define PG8_STAGE(bufoff, gbase, voff) do { _Pragma("unroll") for (int _i = 0; _i < 2; ++_i) \
;         __builtin_amdgcn_global_load_lds((const unsigned*)((const char*)(gbase) + (voff)[_i]), (PG8_LAS unsigned*)(lds + (bufoff) + ldsw + _i * 8192), 16, 0, 0); } while (0)
; #define PG8_LDA(dst, b, h) do { _Pragma("unroll") for (int m = 0; m < 4; ++m) _Pragma("unroll") for (int k = 0; k < 2; ++k) dst[m][k] = *(const PG8_LAS bf16x8*)(lds + PG8_SA(b, h) + aoff + m * 2048 + k * 1024); } while (0)
; #define PG8_MMA(ai, bj, At, Bt) do { __builtin_amdgcn_s_setprio(1); _Pragma("unroll") for (int m = 0; m < 4; ++m) _Pragma("unroll") for (int n = 0; n < 2; ++n) _Pragma("unroll") for (int k = 0; k < 2; ++k) \
;         acc[ai][bj][m][n] = __builtin_amdgcn_mfma_f32_16x16x32_bf16(Bt[n][k], At[m][k], acc[ai][bj][m][n], 0, 0, 0); __builtin_amdgcn_s_setprio(0); } while (0)
; #define PG8_WAIT_V(n) asm volatile("s_waitcnt vmcnt(" #n ")" ::: "memory")
; #define PG8_WAIT_L(n) asm volatile("s_waitcnt lgkmcnt(" #n ")" ::: "memory")
; #define PG8_BAR __builtin_amdgcn_s_barrier()
; #define PG8_SCHED __builtin_amdgcn_sched_barrier(0)
; template <class Epi, class Sched, bool ALIGN_EPI = false, bool SP2 = false>
; __device__ __forceinline__ void gemm_phase(PG8_LAS unsigned char* lds, const Gemm g, const Sched& S, const Epi& E) {
;     ...
;             PG8_LDA(At, 1, 1); PG8_STAGE(PG8_SB(1, 0), b3, voffB); PG8_STAGE(PG8_SB(1, 1), b3 + hstep, voffB); PG8_STAGE(PG8_SA(1, 0), a3, voffA);
;             PG8_WAIT_V(8); PG8_WAIT_L(0); PG8_BAR; PG8_MMA(1, 0, At, B0); PG8_MMA(1, 1, At, B1); PG8_BAR; PG8_SCHED;
	s_add_i32 s34, s68, s16
	v_lshl_add_u64 v[176:177], v[176:177], 0, s[22:23]
	s_mov_b32 m0, s34
	ds_read_b128 v[188:191], v161 offset:49152
	ds_read_b128 v[192:195], v161 offset:50176
	ds_read_b128 v[196:199], v161 offset:51200
	ds_read_b128 v[200:203], v161 offset:52224
	ds_read_b128 v[204:207], v161 offset:53248
	ds_read_b128 v[208:211], v161 offset:54272
	ds_read_b128 v[212:215], v161 offset:55296
	ds_read_b128 v[216:219], v161 offset:56320
	global_load_lds_dwordx4 v[176:177], off
	v_lshl_add_u64 v[176:177], v[178:179], 0, s[22:23]
	s_add_i32 m0, s34, 0x2000
	s_add_i32 s34, s69, s16
	global_load_lds_dwordx4 v[176:177], off
	v_lshl_add_u64 v[176:177], v[220:221], 0, s[22:23]
	s_mov_b32 m0, s34
	s_nop 0
	global_load_lds_dwordx4 v[176:177], off
	v_lshl_add_u64 v[176:177], v[222:223], 0, s[22:23]
	s_add_i32 m0, s34, 0x2000
	s_nop 0
	global_load_lds_dwordx4 v[176:177], off
	v_lshl_add_u64 v[176:177], v[224:225], 0, s[22:23]
	s_mov_b32 m0, s37
	s_nop 0
	global_load_lds_dwordx4 v[176:177], off
	v_lshl_add_u64 v[176:177], v[226:227], 0, s[22:23]
	s_mov_b32 m0, s38
	s_nop 0
	global_load_lds_dwordx4 v[176:177], off
	s_waitcnt vmcnt(8)
	s_waitcnt lgkmcnt(0)
	s_barrier
	s_setprio 1
	s_waitcnt lgkmcnt(0)
	v_mfma_f32_16x16x32_bf16 v[60:63], v[144:147], v[188:191], v[60:63]
	v_mfma_f32_16x16x32_bf16 v[56:59], v[152:155], v[188:191], v[56:59]
	v_mfma_f32_16x16x32_bf16 v[52:55], v[144:147], v[196:199], v[52:55]
	v_mfma_f32_16x16x32_bf16 v[48:51], v[152:155], v[196:199], v[48:51]
	v_mfma_f32_16x16x32_bf16 v[40:43], v[144:147], v[204:207], v[40:43]
	v_mfma_f32_16x16x32_bf16 v[32:35], v[152:155], v[204:207], v[32:35]
	v_mfma_f32_16x16x32_bf16 v[24:27], v[144:147], v[212:215], v[24:27]
	v_mfma_f32_16x16x32_bf16 v[16:19], v[152:155], v[212:215], v[16:19]
	v_mfma_f32_16x16x32_bf16 v[60:63], v[148:151], v[192:195], v[60:63]
	v_mfma_f32_16x16x32_bf16 v[56:59], v[164:167], v[192:195], v[56:59]
	v_mfma_f32_16x16x32_bf16 v[52:55], v[148:151], v[200:203], v[52:55]
	v_mfma_f32_16x16x32_bf16 v[48:51], v[164:167], v[200:203], v[48:51]
	v_mfma_f32_16x16x32_bf16 v[40:43], v[148:151], v[208:211], v[40:43]
	v_mfma_f32_16x16x32_bf16 v[32:35], v[164:167], v[208:211], v[32:35]
	v_mfma_f32_16x16x32_bf16 v[24:27], v[148:151], v[216:219], v[24:27]
	v_mfma_f32_16x16x32_bf16 v[16:19], v[164:167], v[216:219], v[16:19]
	s_setprio 0
	s_setprio 1
	v_mfma_f32_16x16x32_bf16 v[44:47], v[168:171], v[188:191], v[44:47]
	v_mfma_f32_16x16x32_bf16 v[36:39], v[180:183], v[188:191], v[36:39]
	v_mfma_f32_16x16x32_bf16 v[28:31], v[168:171], v[196:199], v[28:31]
	v_mfma_f32_16x16x32_bf16 v[20:23], v[180:183], v[196:199], v[20:23]
	v_mfma_f32_16x16x32_bf16 v[12:15], v[168:171], v[204:207], v[12:15]
	v_mfma_f32_16x16x32_bf16 v[8:11], v[180:183], v[204:207], v[8:11]
	v_mfma_f32_16x16x32_bf16 v[4:7], v[168:171], v[212:215], v[4:7]
	v_mfma_f32_16x16x32_bf16 v[0:3], v[180:183], v[212:215], v[0:3]
	v_mfma_f32_16x16x32_bf16 v[44:47], v[172:175], v[192:195], v[44:47]
	v_mfma_f32_16x16x32_bf16 v[36:39], v[184:187], v[192:195], v[36:39]
	v_mfma_f32_16x16x32_bf16 v[28:31], v[172:175], v[200:203], v[28:31]
	v_mfma_f32_16x16x32_bf16 v[20:23], v[184:187], v[200:203], v[20:23]
	v_mfma_f32_16x16x32_bf16 v[12:15], v[172:175], v[208:211], v[12:15]
	v_mfma_f32_16x16x32_bf16 v[8:11], v[184:187], v[208:211], v[8:11]
	v_mfma_f32_16x16x32_bf16 v[4:7], v[172:175], v[216:219], v[4:7]
	v_mfma_f32_16x16x32_bf16 v[0:3], v[184:187], v[216:219], v[0:3]
	s_setprio 0
	s_barrier
	s_add_u32 s30, s30, 0x100
	s_addc_u32 s31, s31, 0
	s_add_u32 s65, s65, 0x100
	s_addc_u32 s66, s66, 0
	s_cmp_ge_i32 s67, s40
	s_mov_b32 s34, s67
	s_cbranch_scc0 .LBB0_467
	s_branch .Lpeel_x1

; #define PG8_BAR __builtin_amdgcn_s_barrier()
; template <class Epi, class Sched, bool ALIGN_EPI = false, bool SP2 = false>
; __device__ __forceinline__ void gemm_phase(PG8_LAS unsigned char* lds, const Gemm g, const Sched& S, const Epi& E) {
;     ...
;         }
;         if constexpr (ALIGN_EPI) { if (wr == 0) PG8_BAR; }
.Lpeel_x1:
.LBB0_469:
	s_and_b64 vcc, exec, s[26:27]
	s_cbranch_vccz .LBB0_471
	s_barrier

; #define PG8_STAGE(bufoff, gbase, voff) do { _Pragma("unroll") for (int _i = 0; _i < 2; ++_i) \
;         __builtin_amdgcn_global_load_lds((const unsigned*)((const char*)(gbase) + (voff)[_i]), (PG8_LAS unsigned*)(lds + (bufoff) + ldsw + _i * 8192), 16, 0, 0); } while (0)
; #define PG8_LDA(dst, b, h) do { _Pragma("unroll") for (int m = 0; m < 4; ++m) _Pragma("unroll") for (int k = 0; k < 2; ++k) dst[m][k] = *(const PG8_LAS bf16x8*)(lds + PG8_SA(b, h) + aoff + m * 2048 + k * 1024); } while (0)
; #define PG8_LDB(dst, b, h) do { _Pragma("unroll") for (int n = 0; n < 2; ++n) _Pragma("unroll") for (int k = 0; k < 2; ++k) dst[n][k] = *(const PG8_LAS bf16x8*)(lds + PG8_SB(b, h) + boff + n * 2048 + k * 1024); } while (0)
; #define PG8_MMA(ai, bj, At, Bt) do { __builtin_amdgcn_s_setprio(1); _Pragma("unroll") for (int m = 0; m < 4; ++m) _Pragma("unroll") for (int n = 0; n < 2; ++n) _Pragma("unroll") for (int k = 0; k < 2; ++k) \
;         acc[ai][bj][m][n] = __builtin_amdgcn_mfma_f32_16x16x32_bf16(Bt[n][k], At[m][k], acc[ai][bj][m][n], 0, 0, 0); __builtin_amdgcn_s_setprio(0); } while (0)
; #define PG8_WAIT_V(n) asm volatile("s_waitcnt vmcnt(" #n ")" ::: "memory")
; #define PG8_BAR __builtin_amdgcn_s_barrier()
; template <class Epi, class Sched, bool ALIGN_EPI = false, bool SP2 = false>
; __device__ __forceinline__ void gemm_phase(PG8_LAS unsigned char* lds, const Gemm g, const Sched& S, const Epi& E) {
;     ...
;         for (int t = 0; t < nt; t += 2) {
;             const bool last = (t == nt - 2);
;             const char* a1 = cA + (size_t)(t + 1) * kstep;
;             const char* a2 = last ? nA : cA + (size_t)(t + 2) * kstep; const char* b2 = last ? nB : cB + (size_t)(t + 2) * kstep;
;             const char* a3 = a2 + kstep; const char* b3 = b2 + kstep;
;             if (last && has_next) S.a_ready(nxt);
;             if constexpr (SP2) {
;             PG8_LDB(B0, 0, 0); PG8_LDB(B1, 0, 1); PG8_SCHED; PG8_LDA(At, 0, 0); PG8_STAGE(PG8_SA(1, 1), a1 + hstep, voffA);
;             PG8_WAIT_V(8); PG8_WAIT_L(0); PG8_BAR; PG8_MMA(0, 0, At, B0); PG8_MMA(0, 1, At, B1); PG8_BAR; PG8_SCHED;
;             PG8_LDA(At, 0, 1); PG8_STAGE(PG8_SB(0, 0), b2, voffB); PG8_STAGE(PG8_SB(0, 1), b2 + hstep, voffB); PG8_STAGE(PG8_SA(0, 0), a2, voffA);
;             PG8_WAIT_V(8); PG8_WAIT_L(0); PG8_BAR; PG8_MMA(1, 0, At, B0); PG8_MMA(1, 1, At, B1); PG8_BAR; PG8_SCHED;
.LBB0_595:
	s_andn2_b64 vcc, exec, s[78:79]
	s_cbranch_vccnz .LBB0_598
	s_add_u32 s4, s4, 0x80
	s_addc_u32 s5, s5, 0
	s_add_u32 s9, s6, 0x100
	s_addc_u32 s27, s7, 0
	s_mov_b32 s6, 0
	ds_read_b128 v[128:131], v177
	ds_read_b128 v[154:157], v177 offset:1024
	ds_read_b128 v[158:161], v177 offset:2048
	ds_read_b128 v[162:165], v177 offset:3072
	ds_read_b128 v[166:169], v179
	ds_read_b128 v[170:173], v179 offset:1024
	ds_read_b128 v[184:187], v179 offset:2048
	ds_read_b128 v[188:191], v179 offset:3072
	s_add_i32 s28, s6, 2
	s_add_u32 s29, s4, 0x80
	s_addc_u32 s7, s5, 0
	s_cmp_eq_u32 s86, s6
	s_cselect_b32 s6, s0, s29
	s_cselect_b32 s7, s1, s7
	s_cselect_b32 s39, s37, s27
	s_cselect_b32 s38, s36, s9
	v_lshl_add_u64 v[224:225], s[4:5], 0, v[146:147]
	s_add_i32 m0, s67, 0xc000
	ds_read_b128 v[192:195], v180
	ds_read_b128 v[196:199], v180 offset:1024
	ds_read_b128 v[200:203], v180 offset:2048
	ds_read_b128 v[204:207], v180 offset:3072
	ds_read_b128 v[208:211], v180 offset:4096
	ds_read_b128 v[212:215], v180 offset:5120
	ds_read_b128 v[216:219], v180 offset:6144
	ds_read_b128 v[220:223], v180 offset:7168
	global_load_lds_dwordx4 v[224:225], off
	v_lshl_add_u64 v[224:225], s[4:5], 0, v[148:149]
	s_add_i32 m0, s67, 0xe000
	s_nop 0
	global_load_lds_dwordx4 v[224:225], off
	s_waitcnt vmcnt(8)
	s_waitcnt lgkmcnt(0)
	s_barrier
	s_setprio 1
	s_waitcnt lgkmcnt(0)
	v_mfma_f32_16x16x32_bf16 v[120:123], v[128:131], v[192:195], 0
	v_mfma_f32_16x16x32_bf16 v[124:127], v[158:161], v[192:195], 0
	v_mfma_f32_16x16x32_bf16 v[108:111], v[128:131], v[200:203], 0
	v_mfma_f32_16x16x32_bf16 v[104:107], v[158:161], v[200:203], 0
	v_mfma_f32_16x16x32_bf16 v[92:95], v[128:131], v[208:211], 0
	v_mfma_f32_16x16x32_bf16 v[88:91], v[158:161], v[208:211], 0
	v_mfma_f32_16x16x32_bf16 v[76:79], v[128:131], v[216:219], 0
	v_mfma_f32_16x16x32_bf16 v[72:75], v[158:161], v[216:219], 0
	v_mfma_f32_16x16x32_bf16 v[120:123], v[154:157], v[196:199], v[120:123]
	v_mfma_f32_16x16x32_bf16 v[124:127], v[162:165], v[196:199], v[124:127]
	v_mfma_f32_16x16x32_bf16 v[108:111], v[154:157], v[204:207], v[108:111]
	v_mfma_f32_16x16x32_bf16 v[104:107], v[162:165], v[204:207], v[104:107]
	v_mfma_f32_16x16x32_bf16 v[92:95], v[154:157], v[212:215], v[92:95]
	v_mfma_f32_16x16x32_bf16 v[88:91], v[162:165], v[212:215], v[88:91]
	v_mfma_f32_16x16x32_bf16 v[76:79], v[154:157], v[220:223], v[76:79]
	v_mfma_f32_16x16x32_bf16 v[72:75], v[162:165], v[220:223], v[72:75]
	s_setprio 0
	s_setprio 1
	v_mfma_f32_16x16x32_bf16 v[116:119], v[166:169], v[192:195], 0
	v_mfma_f32_16x16x32_bf16 v[112:115], v[184:187], v[192:195], 0
	v_mfma_f32_16x16x32_bf16 v[100:103], v[166:169], v[200:203], 0
	v_mfma_f32_16x16x32_bf16 v[96:99], v[184:187], v[200:203], 0
	v_mfma_f32_16x16x32_bf16 v[84:87], v[166:169], v[208:211], 0
	v_mfma_f32_16x16x32_bf16 v[80:83], v[184:187], v[208:211], 0
	v_mfma_f32_16x16x32_bf16 v[68:71], v[166:169], v[216:219], 0
	v_mfma_f32_16x16x32_bf16 v[64:67], v[184:187], v[216:219], 0
	v_mfma_f32_16x16x32_bf16 v[116:119], v[170:173], v[196:199], v[116:119]
	v_mfma_f32_16x16x32_bf16 v[112:115], v[188:191], v[196:199], v[112:115]
	v_mfma_f32_16x16x32_bf16 v[100:103], v[170:173], v[204:207], v[100:103]
	v_mfma_f32_16x16x32_bf16 v[96:99], v[188:191], v[204:207], v[96:99]
	v_mfma_f32_16x16x32_bf16 v[84:87], v[170:173], v[212:215], v[84:87]
	v_mfma_f32_16x16x32_bf16 v[80:83], v[188:191], v[212:215], v[80:83]
	v_mfma_f32_16x16x32_bf16 v[68:71], v[170:173], v[220:223], v[68:71]
	v_mfma_f32_16x16x32_bf16 v[64:67], v[188:191], v[220:223], v[64:67]
	s_setprio 0
	s_barrier
	s_add_i32 s29, s11, s66
	v_lshl_add_u64 v[224:225], s[38:39], 0, v[134:135]
	s_mov_b32 m0, s29
	ds_read_b128 v[192:195], v180 offset:16384
	ds_read_b128 v[196:199], v180 offset:17408
	ds_read_b128 v[200:203], v180 offset:18432
	ds_read_b128 v[204:207], v180 offset:19456
	ds_read_b128 v[208:211], v180 offset:20480
	ds_read_b128 v[212:215], v180 offset:21504
	ds_read_b128 v[216:219], v180 offset:22528
	ds_read_b128 v[220:223], v180 offset:23552
	global_load_lds_dwordx4 v[224:225], off
	s_add_i32 m0, s29, 0x2000
	v_lshl_add_u64 v[226:227], s[38:39], 0, v[138:139]
	s_add_u32 s38, s38, s14
	s_addc_u32 s39, s39, s15
	s_add_i32 s29, s19, s66
	global_load_lds_dwordx4 v[226:227], off
	v_lshl_add_u64 v[228:229], s[38:39], 0, v[134:135]
	s_mov_b32 m0, s29
	v_lshl_add_u64 v[230:231], s[38:39], 0, v[138:139]
	global_load_lds_dwordx4 v[228:229], off
	s_add_i32 m0, s29, 0x2000
	v_lshl_add_u64 v[232:233], s[6:7], 0, v[132:133]
	global_load_lds_dwordx4 v[230:231], off
	s_mov_b32 m0, s67
	v_lshl_add_u64 v[234:235], s[6:7], 0, v[136:137]
	global_load_lds_dwordx4 v[232:233], off
	s_mov_b32 m0, s68
	s_nop 0
	global_load_lds_dwordx4 v[234:235], off
	s_waitcnt vmcnt(8)
	s_waitcnt lgkmcnt(0)
	s_barrier
; #define PG8_STAGE(bufoff, gbase, voff) do { _Pragma("unroll") for (int _i = 0; _i < 2; ++_i) \
;         __builtin_amdgcn_global_load_lds((const unsigned*)((const char*)(gbase) + (voff)[_i]), (PG8_LAS unsigned*)(lds + (bufoff) + ldsw + _i * 8192), 16, 0, 0); } while (0)
; #define PG8_LDA(dst, b, h) do { _Pragma("unroll") for (int m = 0; m < 4; ++m) _Pragma("unroll") for (int k = 0; k < 2; ++k) dst[m][k] = *(const PG8_LAS bf16x8*)(lds + PG8_SA(b, h) + aoff + m * 2048 + k * 1024); } while (0)
; #define PG8_LDB(dst, b, h) do { _Pragma("unroll") for (int n = 0; n < 2; ++n) _Pragma("unroll") for (int k = 0; k < 2; ++k) dst[n][k] = *(const PG8_LAS bf16x8*)(lds + PG8_SB(b, h) + boff + n * 2048 + k * 1024); } while (0)
; #define PG8_MMA(ai, bj, At, Bt) do { __builtin_amdgcn_s_setprio(1); _Pragma("unroll") for (int m = 0; m < 4; ++m) _Pragma("unroll") for (int n = 0; n < 2; ++n) _Pragma("unroll") for (int k = 0; k < 2; ++k) \
;         acc[ai][bj][m][n] = __builtin_amdgcn_mfma_f32_16x16x32_bf16(Bt[n][k], At[m][k], acc[ai][bj][m][n], 0, 0, 0); __builtin_amdgcn_s_setprio(0); } while (0)
; #define PG8_WAIT_V(n) asm volatile("s_waitcnt vmcnt(" #n ")" ::: "memory")
; #define PG8_WAIT_L(n) asm volatile("s_waitcnt lgkmcnt(" #n ")" ::: "memory")
; #define PG8_BAR __builtin_amdgcn_s_barrier()
; #define PG8_SCHED __builtin_amdgcn_sched_barrier(0)
; template <class Epi, class Sched, bool ALIGN_EPI = false, bool SP2 = false>
; __device__ __forceinline__ void gemm_phase(PG8_LAS unsigned char* lds, const Gemm g, const Sched& S, const Epi& E) {
;     ...
;             PG8_WAIT_V(8); PG8_WAIT_L(0); PG8_BAR; PG8_MMA(1, 0, At, B0); PG8_MMA(1, 1, At, B1); PG8_BAR; PG8_SCHED;
;             PG8_LDB(B0, 1, 0); PG8_LDB(B1, 1, 1); PG8_SCHED; PG8_LDA(At, 1, 0); PG8_STAGE(PG8_SA(0, 1), a2 + hstep, voffA);
;             PG8_WAIT_V(8); PG8_WAIT_L(0); PG8_BAR; PG8_MMA(0, 0, At, B0); PG8_MMA(0, 1, At, B1); PG8_BAR; PG8_SCHED;
	s_setprio 1
	s_waitcnt lgkmcnt(0)
	v_mfma_f32_16x16x32_bf16 v[60:63], v[128:131], v[192:195], 0
	v_mfma_f32_16x16x32_bf16 v[56:59], v[158:161], v[192:195], 0
	v_mfma_f32_16x16x32_bf16 v[44:47], v[128:131], v[200:203], 0
	v_mfma_f32_16x16x32_bf16 v[40:43], v[158:161], v[200:203], 0
	v_mfma_f32_16x16x32_bf16 v[28:31], v[128:131], v[208:211], 0
	v_mfma_f32_16x16x32_bf16 v[24:27], v[158:161], v[208:211], 0
	v_mfma_f32_16x16x32_bf16 v[12:15], v[128:131], v[216:219], 0
	v_mfma_f32_16x16x32_bf16 v[8:11], v[158:161], v[216:219], 0
	v_mfma_f32_16x16x32_bf16 v[60:63], v[154:157], v[196:199], v[60:63]
	v_mfma_f32_16x16x32_bf16 v[56:59], v[162:165], v[196:199], v[56:59]
	v_mfma_f32_16x16x32_bf16 v[44:47], v[154:157], v[204:207], v[44:47]
	v_mfma_f32_16x16x32_bf16 v[40:43], v[162:165], v[204:207], v[40:43]
	v_mfma_f32_16x16x32_bf16 v[28:31], v[154:157], v[212:215], v[28:31]
	v_mfma_f32_16x16x32_bf16 v[24:27], v[162:165], v[212:215], v[24:27]
	v_mfma_f32_16x16x32_bf16 v[12:15], v[154:157], v[220:223], v[12:15]
	v_mfma_f32_16x16x32_bf16 v[8:11], v[162:165], v[220:223], v[8:11]
	s_setprio 0
	s_setprio 1
	v_mfma_f32_16x16x32_bf16 v[52:55], v[166:169], v[192:195], 0
	v_mfma_f32_16x16x32_bf16 v[48:51], v[184:187], v[192:195], 0
	v_mfma_f32_16x16x32_bf16 v[36:39], v[166:169], v[200:203], 0
	v_mfma_f32_16x16x32_bf16 v[32:35], v[184:187], v[200:203], 0
	v_mfma_f32_16x16x32_bf16 v[20:23], v[166:169], v[208:211], 0
	v_mfma_f32_16x16x32_bf16 v[16:19], v[184:187], v[208:211], 0
	v_mfma_f32_16x16x32_bf16 v[4:7], v[166:169], v[216:219], 0
	v_mfma_f32_16x16x32_bf16 v[0:3], v[184:187], v[216:219], 0
	v_mfma_f32_16x16x32_bf16 v[52:55], v[170:173], v[196:199], v[52:55]
	v_mfma_f32_16x16x32_bf16 v[48:51], v[188:191], v[196:199], v[48:51]
	v_mfma_f32_16x16x32_bf16 v[36:39], v[170:173], v[204:207], v[36:39]
	v_mfma_f32_16x16x32_bf16 v[32:35], v[188:191], v[204:207], v[32:35]
	v_mfma_f32_16x16x32_bf16 v[20:23], v[170:173], v[212:215], v[20:23]
	v_mfma_f32_16x16x32_bf16 v[16:19], v[188:191], v[212:215], v[16:19]
	v_mfma_f32_16x16x32_bf16 v[4:7], v[170:173], v[220:223], v[4:7]
	v_mfma_f32_16x16x32_bf16 v[0:3], v[188:191], v[220:223], v[0:3]
	s_setprio 0
	s_barrier
	s_add_i32 s29, 0, 0x18000
	v_add_u32_e32 v140, s29, v175
	s_add_i32 s38, 0, 0x1c000
	ds_read_b128 v[128:131], v140
	ds_read_b128 v[154:157], v140 offset:1024
	ds_read_b128 v[158:161], v140 offset:2048
	ds_read_b128 v[162:165], v140 offset:3072
	v_add_u32_e32 v140, s38, v175
	ds_read_b128 v[166:169], v140
	ds_read_b128 v[170:173], v140 offset:1024
	ds_read_b128 v[184:187], v140 offset:2048
	ds_read_b128 v[188:191], v140 offset:3072
	s_add_u32 s6, s6, s14
	s_addc_u32 s7, s7, s15
	s_mov_b32 m0, s69
	v_lshl_add_u64 v[236:237], s[6:7], 0, v[132:133]
	ds_read_b128 v[192:195], v180 offset:32768
	ds_read_b128 v[196:199], v180 offset:33792
	ds_read_b128 v[200:203], v180 offset:34816
	ds_read_b128 v[204:207], v180 offset:35840
	ds_read_b128 v[208:211], v180 offset:36864
	ds_read_b128 v[212:215], v180 offset:37888
	ds_read_b128 v[216:219], v180 offset:38912
	ds_read_b128 v[220:223], v180 offset:39936
	global_load_lds_dwordx4 v[236:237], off
	v_lshl_add_u64 v[236:237], s[6:7], 0, v[136:137]
	s_mov_b32 m0, s70
	s_nop 0
	global_load_lds_dwordx4 v[236:237], off
	s_waitcnt vmcnt(8)
	s_waitcnt lgkmcnt(0)
	s_barrier
	s_setprio 1
	s_waitcnt lgkmcnt(0)
	v_mfma_f32_16x16x32_bf16 v[120:123], v[128:131], v[192:195], v[120:123]
	v_mfma_f32_16x16x32_bf16 v[124:127], v[158:161], v[192:195], v[124:127]
	v_mfma_f32_16x16x32_bf16 v[108:111], v[128:131], v[200:203], v[108:111]
	v_mfma_f32_16x16x32_bf16 v[104:107], v[158:161], v[200:203], v[104:107]
	v_mfma_f32_16x16x32_bf16 v[92:95], v[128:131], v[208:211], v[92:95]
	v_mfma_f32_16x16x32_bf16 v[88:91], v[158:161], v[208:211], v[88:91]
	v_mfma_f32_16x16x32_bf16 v[76:79], v[128:131], v[216:219], v[76:79]
	v_mfma_f32_16x16x32_bf16 v[72:75], v[158:161], v[216:219], v[72:75]
	v_mfma_f32_16x16x32_bf16 v[120:123], v[154:157], v[196:199], v[120:123]
	v_mfma_f32_16x16x32_bf16 v[124:127], v[162:165], v[196:199], v[124:127]
	v_mfma_f32_16x16x32_bf16 v[108:111], v[154:157], v[204:207], v[108:111]
	v_mfma_f32_16x16x32_bf16 v[104:107], v[162:165], v[204:207], v[104:107]
	v_mfma_f32_16x16x32_bf16 v[92:95], v[154:157], v[212:215], v[92:95]
	v_mfma_f32_16x16x32_bf16 v[88:91], v[162:165], v[212:215], v[88:91]
	v_mfma_f32_16x16x32_bf16 v[76:79], v[154:157], v[220:223], v[76:79]
	v_mfma_f32_16x16x32_bf16 v[72:75], v[162:165], v[220:223], v[72:75]
	s_setprio 0
	s_setprio 1
	v_mfma_f32_16x16x32_bf16 v[116:119], v[166:169], v[192:195], v[116:119]
	v_mfma_f32_16x16x32_bf16 v[112:115], v[184:187], v[192:195], v[112:115]
	v_mfma_f32_16x16x32_bf16 v[100:103], v[166:169], v[200:203], v[100:103]
	v_mfma_f32_16x16x32_bf16 v[96:99], v[184:187], v[200:203], v[96:99]
	v_mfma_f32_16x16x32_bf16 v[84:87], v[166:169], v[208:211], v[84:87]
	v_mfma_f32_16x16x32_bf16 v[80:83], v[184:187], v[208:211], v[80:83]
	v_mfma_f32_16x16x32_bf16 v[68:71], v[166:169], v[216:219], v[68:71]
	v_mfma_f32_16x16x32_bf16 v[64:67], v[184:187], v[216:219], v[64:67]
	v_mfma_f32_16x16x32_bf16 v[116:119], v[170:173], v[196:199], v[116:119]
	v_mfma_f32_16x16x32_bf16 v[112:115], v[188:191], v[196:199], v[112:115]
	v_mfma_f32_16x16x32_bf16 v[100:103], v[170:173], v[204:207], v[100:103]
	v_mfma_f32_16x16x32_bf16 v[96:99], v[188:191], v[204:207], v[96:99]
	v_mfma_f32_16x16x32_bf16 v[84:87], v[170:173], v[212:215], v[84:87]
	v_mfma_f32_16x16x32_bf16 v[80:83], v[188:191], v[212:215], v[80:83]
	v_mfma_f32_16x16x32_bf16 v[68:71], v[170:173], v[220:223], v[68:71]
	v_mfma_f32_16x16x32_bf16 v[64:67], v[188:191], v[220:223], v[64:67]
	s_setprio 0
	s_barrier
; #define PG8_STAGE(bufoff, gbase, voff) do { _Pragma("unroll") for (int _i = 0; _i < 2; ++_i) \
;         __builtin_amdgcn_global_load_lds((const unsigned*)((const char*)(gbase) + (voff)[_i]), (PG8_LAS unsigned*)(lds + (bufoff) + ldsw + _i * 8192), 16, 0, 0); } while (0)
; #define PG8_LDA(dst, b, h) do { _Pragma("unroll") for (int m = 0; m < 4; ++m) _Pragma("unroll") for (int k = 0; k < 2; ++k) dst[m][k] = *(const PG8_LAS bf16x8*)(lds + PG8_SA(b, h) + aoff + m * 2048 + k * 1024); } while (0)
; #define PG8_MMA(ai, bj, At, Bt) do { __builtin_amdgcn_s_setprio(1); _Pragma("unroll") for (int m = 0; m < 4; ++m) _Pragma("unroll") for (int n = 0; n < 2; ++n) _Pragma("unroll") for (int k = 0; k < 2; ++k) \
;         acc[ai][bj][m][n] = __builtin_amdgcn_mfma_f32_16x16x32_bf16(Bt[n][k], At[m][k], acc[ai][bj][m][n], 0, 0, 0); __builtin_amdgcn_s_setprio(0); } while (0)
; #define PG8_WAIT_V(n) asm volatile("s_waitcnt vmcnt(" #n ")" ::: "memory")
; #define PG8_WAIT_L(n) asm volatile("s_waitcnt lgkmcnt(" #n ")" ::: "memory")
; #define PG8_BAR __builtin_amdgcn_s_barrier()
; #define PG8_SCHED __builtin_amdgcn_sched_barrier(0)
; template <class Epi, class Sched, bool ALIGN_EPI = false, bool SP2 = false>
; __device__ __forceinline__ void gemm_phase(PG8_LAS unsigned char* lds, const Gemm g, const Sched& S, const Epi& E) {
;     ...
;             PG8_LDA(At, 1, 1); PG8_STAGE(PG8_SB(1, 0), b3, voffB); PG8_STAGE(PG8_SB(1, 1), b3 + hstep, voffB); PG8_STAGE(PG8_SA(1, 0), a3, voffA);
;             PG8_WAIT_V(8); PG8_WAIT_L(0); PG8_BAR; PG8_MMA(1, 0, At, B0); PG8_MMA(1, 1, At, B1); PG8_BAR; PG8_SCHED;
	s_add_i32 s6, s29, s66
	v_lshl_add_u64 v[224:225], v[224:225], 0, s[24:25]
	s_mov_b32 m0, s6
	ds_read_b128 v[192:195], v180 offset:49152
	ds_read_b128 v[196:199], v180 offset:50176
	ds_read_b128 v[200:203], v180 offset:51200
	ds_read_b128 v[204:207], v180 offset:52224
	ds_read_b128 v[208:211], v180 offset:53248
	ds_read_b128 v[212:215], v180 offset:54272
	ds_read_b128 v[216:219], v180 offset:55296
	ds_read_b128 v[220:223], v180 offset:56320
	global_load_lds_dwordx4 v[224:225], off
	v_lshl_add_u64 v[224:225], v[226:227], 0, s[24:25]
	s_add_i32 m0, s6, 0x2000
	s_add_i32 s6, s38, s66
	global_load_lds_dwordx4 v[224:225], off
	v_lshl_add_u64 v[224:225], v[228:229], 0, s[24:25]
	s_mov_b32 m0, s6
	s_nop 0
	global_load_lds_dwordx4 v[224:225], off
	v_lshl_add_u64 v[224:225], v[230:231], 0, s[24:25]
	s_add_i32 m0, s6, 0x2000
	s_nop 0
	global_load_lds_dwordx4 v[224:225], off
	v_lshl_add_u64 v[224:225], v[232:233], 0, s[24:25]
	s_mov_b32 m0, s72
	s_nop 0
	global_load_lds_dwordx4 v[224:225], off
	v_lshl_add_u64 v[224:225], v[234:235], 0, s[24:25]
	s_mov_b32 m0, s73
	s_nop 0
	global_load_lds_dwordx4 v[224:225], off
	s_waitcnt vmcnt(8)
	s_waitcnt lgkmcnt(0)
	s_barrier
	s_setprio 1
	s_waitcnt lgkmcnt(0)
	v_mfma_f32_16x16x32_bf16 v[60:63], v[128:131], v[192:195], v[60:63]
	v_mfma_f32_16x16x32_bf16 v[56:59], v[158:161], v[192:195], v[56:59]
	v_mfma_f32_16x16x32_bf16 v[44:47], v[128:131], v[200:203], v[44:47]
	v_mfma_f32_16x16x32_bf16 v[40:43], v[158:161], v[200:203], v[40:43]
	v_mfma_f32_16x16x32_bf16 v[28:31], v[128:131], v[208:211], v[28:31]
	v_mfma_f32_16x16x32_bf16 v[24:27], v[158:161], v[208:211], v[24:27]
	v_mfma_f32_16x16x32_bf16 v[12:15], v[128:131], v[216:219], v[12:15]
	v_mfma_f32_16x16x32_bf16 v[8:11], v[158:161], v[216:219], v[8:11]
	v_mfma_f32_16x16x32_bf16 v[60:63], v[154:157], v[196:199], v[60:63]
	v_mfma_f32_16x16x32_bf16 v[56:59], v[162:165], v[196:199], v[56:59]
	v_mfma_f32_16x16x32_bf16 v[44:47], v[154:157], v[204:207], v[44:47]
	v_mfma_f32_16x16x32_bf16 v[40:43], v[162:165], v[204:207], v[40:43]
	v_mfma_f32_16x16x32_bf16 v[28:31], v[154:157], v[212:215], v[28:31]
	v_mfma_f32_16x16x32_bf16 v[24:27], v[162:165], v[212:215], v[24:27]
	v_mfma_f32_16x16x32_bf16 v[12:15], v[154:157], v[220:223], v[12:15]
	v_mfma_f32_16x16x32_bf16 v[8:11], v[162:165], v[220:223], v[8:11]
	s_setprio 0
	s_setprio 1
	v_mfma_f32_16x16x32_bf16 v[52:55], v[166:169], v[192:195], v[52:55]
	v_mfma_f32_16x16x32_bf16 v[48:51], v[184:187], v[192:195], v[48:51]
	v_mfma_f32_16x16x32_bf16 v[36:39], v[166:169], v[200:203], v[36:39]
	v_mfma_f32_16x16x32_bf16 v[32:35], v[184:187], v[200:203], v[32:35]
	v_mfma_f32_16x16x32_bf16 v[20:23], v[166:169], v[208:211], v[20:23]
	v_mfma_f32_16x16x32_bf16 v[16:19], v[184:187], v[208:211], v[16:19]
	v_mfma_f32_16x16x32_bf16 v[4:7], v[166:169], v[216:219], v[4:7]
	v_mfma_f32_16x16x32_bf16 v[0:3], v[184:187], v[216:219], v[0:3]
	v_mfma_f32_16x16x32_bf16 v[52:55], v[170:173], v[196:199], v[52:55]
	v_mfma_f32_16x16x32_bf16 v[48:51], v[188:191], v[196:199], v[48:51]
	v_mfma_f32_16x16x32_bf16 v[36:39], v[170:173], v[204:207], v[36:39]
	v_mfma_f32_16x16x32_bf16 v[32:35], v[188:191], v[204:207], v[32:35]
	v_mfma_f32_16x16x32_bf16 v[20:23], v[170:173], v[212:215], v[20:23]
	v_mfma_f32_16x16x32_bf16 v[16:19], v[188:191], v[212:215], v[16:19]
	v_mfma_f32_16x16x32_bf16 v[4:7], v[170:173], v[220:223], v[4:7]
	v_mfma_f32_16x16x32_bf16 v[0:3], v[188:191], v[220:223], v[0:3]
	s_setprio 0
	s_barrier
	s_add_u32 s4, s4, 0x100
	s_addc_u32 s5, s5, 0
	s_add_u32 s9, s9, 0x100
	s_addc_u32 s27, s27, 0
	s_cmp_ge_i32 s28, s33
	s_mov_b32 s6, s28
	s_cbranch_scc0 .LBB0_597
	s_branch .Lpeel_x2

; #define PG8_BAR __builtin_amdgcn_s_barrier()
; template <class Epi, class Sched, bool ALIGN_EPI = false, bool SP2 = false>
; __device__ __forceinline__ void gemm_phase(PG8_LAS unsigned char* lds, const Gemm g, const Sched& S, const Epi& E) {
;     ...
;         if constexpr (ALIGN_EPI) { if (wr == 0) PG8_BAR; }
.Lpeel_x2:
.LBB0_598:
	s_and_b64 vcc, exec, s[80:81]
	s_cbranch_vccz .LBB0_600
	s_barrier

; #define PG8_STAGE(bufoff, gbase, voff) do { _Pragma("unroll") for (int _i = 0; _i < 2; ++_i) \
;         __builtin_amdgcn_global_load_lds((const unsigned*)((const char*)(gbase) + (voff)[_i]), (PG8_LAS unsigned*)(lds + (bufoff) + ldsw + _i * 8192), 16, 0, 0); } while (0)
; #define PG8_LDA(dst, b, h) do { _Pragma("unroll") for (int m = 0; m < 4; ++m) _Pragma("unroll") for (int k = 0; k < 2; ++k) dst[m][k] = *(const PG8_LAS bf16x8*)(lds + PG8_SA(b, h) + aoff + m * 2048 + k * 1024); } while (0)
; #define PG8_LDB(dst, b, h) do { _Pragma("unroll") for (int n = 0; n < 2; ++n) _Pragma("unroll") for (int k = 0; k < 2; ++k) dst[n][k] = *(const PG8_LAS bf16x8*)(lds + PG8_SB(b, h) + boff + n * 2048 + k * 1024); } while (0)
; #define PG8_MMA(ai, bj, At, Bt) do { __builtin_amdgcn_s_setprio(1); _Pragma("unroll") for (int m = 0; m < 4; ++m) _Pragma("unroll") for (int n = 0; n < 2; ++n) _Pragma("unroll") for (int k = 0; k < 2; ++k) \
;         acc[ai][bj][m][n] = __builtin_amdgcn_mfma_f32_16x16x32_bf16(Bt[n][k], At[m][k], acc[ai][bj][m][n], 0, 0, 0); __builtin_amdgcn_s_setprio(0); } while (0)
; #define PG8_WAIT_V(n) asm volatile("s_waitcnt vmcnt(" #n ")" ::: "memory")
; #define PG8_WAIT_L(n) asm volatile("s_waitcnt lgkmcnt(" #n ")" ::: "memory")
; #define PG8_BAR __builtin_amdgcn_s_barrier()
; #define PG8_SCHED __builtin_amdgcn_sched_barrier(0)
; template <class Epi, class Sched, bool ALIGN_EPI = false, bool SP2 = false>
; __device__ __forceinline__ void gemm_phase(PG8_LAS unsigned char* lds, const Gemm g, const Sched& S, const Epi& E) {
;     ...
;             const char* a1 = cA + (size_t)(t + 1) * kstep;
;             const char* a2 = last ? nA : cA + (size_t)(t + 2) * kstep; const char* b2 = last ? nB : cB + (size_t)(t + 2) * kstep;
;             const char* a3 = a2 + kstep; const char* b3 = b2 + kstep;
;             if (last && has_next) S.a_ready(nxt);
;             if constexpr (SP2) {
;             PG8_LDB(B0, 0, 0); PG8_LDB(B1, 0, 1); PG8_SCHED; PG8_LDA(At, 0, 0); PG8_STAGE(PG8_SA(1, 1), a1 + hstep, voffA);
;             PG8_WAIT_V(8); PG8_WAIT_L(0); PG8_BAR; PG8_MMA(0, 0, At, B0); PG8_MMA(0, 1, At, B1); PG8_BAR; PG8_SCHED;
;             PG8_LDA(At, 0, 1); PG8_STAGE(PG8_SB(0, 0), b2, voffB); PG8_STAGE(PG8_SB(0, 1), b2 + hstep, voffB); PG8_STAGE(PG8_SA(0, 0), a2, voffA);
.LBB0_1220:
	s_andn2_b64 vcc, exec, s[24:25]
	s_waitcnt vmcnt(0)
	s_waitcnt lgkmcnt(0)
	s_cbranch_vccnz .LBB0_1223
	s_add_u32 s30, s30, 0x80
	s_addc_u32 s31, s31, 0
	s_add_u32 s63, s34, 0x100
	s_addc_u32 s64, s35, 0
	s_mov_b32 s34, 0
	ds_read_b128 v[144:147], v151
	ds_read_b128 v[156:159], v151 offset:1024
	ds_read_b128 v[160:163], v151 offset:2048
	ds_read_b128 v[164:167], v151 offset:3072
	ds_read_b128 v[168:171], v152
	ds_read_b128 v[172:175], v152 offset:1024
	ds_read_b128 v[180:183], v152 offset:2048
	ds_read_b128 v[184:187], v152 offset:3072
	s_add_i32 s65, s34, 2
	s_add_u32 s66, s30, 0x80
	s_addc_u32 s35, s31, 0
	s_cmp_eq_u32 s41, s34
	s_cselect_b32 s34, s0, s66
	s_cselect_b32 s35, s1, s35
	s_cselect_b32 s67, s29, s64
	s_cselect_b32 s66, s28, s63
	v_lshl_add_u64 v[176:177], s[30:31], 0, v[136:137]
	s_add_i32 m0, s17, 0xc000
	ds_read_b128 v[188:191], v153
	ds_read_b128 v[192:195], v153 offset:1024
	ds_read_b128 v[196:199], v153 offset:2048
	ds_read_b128 v[200:203], v153 offset:3072
	ds_read_b128 v[204:207], v153 offset:4096
	ds_read_b128 v[208:211], v153 offset:5120
	ds_read_b128 v[212:215], v153 offset:6144
	ds_read_b128 v[216:219], v153 offset:7168
	global_load_lds_dwordx4 v[176:177], off
	v_lshl_add_u64 v[176:177], s[30:31], 0, v[138:139]
	s_add_i32 m0, s17, 0xe000
	s_nop 0
	global_load_lds_dwordx4 v[176:177], off
	s_waitcnt vmcnt(8)
	s_waitcnt lgkmcnt(0)
	s_barrier
	s_setprio 1
	s_waitcnt lgkmcnt(0)
	v_mfma_f32_16x16x32_bf16 v[124:127], v[144:147], v[188:191], 0
	v_mfma_f32_16x16x32_bf16 v[120:123], v[160:163], v[188:191], 0
	v_mfma_f32_16x16x32_bf16 v[108:111], v[144:147], v[196:199], 0
	v_mfma_f32_16x16x32_bf16 v[104:107], v[160:163], v[196:199], 0
	v_mfma_f32_16x16x32_bf16 v[92:95], v[144:147], v[204:207], 0
	v_mfma_f32_16x16x32_bf16 v[88:91], v[160:163], v[204:207], 0
	v_mfma_f32_16x16x32_bf16 v[76:79], v[144:147], v[212:215], 0
	v_mfma_f32_16x16x32_bf16 v[72:75], v[160:163], v[212:215], 0
	v_mfma_f32_16x16x32_bf16 v[124:127], v[156:159], v[192:195], v[124:127]
	v_mfma_f32_16x16x32_bf16 v[120:123], v[164:167], v[192:195], v[120:123]
	v_mfma_f32_16x16x32_bf16 v[108:111], v[156:159], v[200:203], v[108:111]
	v_mfma_f32_16x16x32_bf16 v[104:107], v[164:167], v[200:203], v[104:107]
	v_mfma_f32_16x16x32_bf16 v[92:95], v[156:159], v[208:211], v[92:95]
	v_mfma_f32_16x16x32_bf16 v[88:91], v[164:167], v[208:211], v[88:91]
	v_mfma_f32_16x16x32_bf16 v[76:79], v[156:159], v[216:219], v[76:79]
	v_mfma_f32_16x16x32_bf16 v[72:75], v[164:167], v[216:219], v[72:75]
	s_setprio 0
	s_setprio 1
	v_mfma_f32_16x16x32_bf16 v[116:119], v[168:171], v[188:191], 0
	v_mfma_f32_16x16x32_bf16 v[112:115], v[180:183], v[188:191], 0
	v_mfma_f32_16x16x32_bf16 v[100:103], v[168:171], v[196:199], 0
	v_mfma_f32_16x16x32_bf16 v[96:99], v[180:183], v[196:199], 0
	v_mfma_f32_16x16x32_bf16 v[84:87], v[168:171], v[204:207], 0
	v_mfma_f32_16x16x32_bf16 v[80:83], v[180:183], v[204:207], 0
	v_mfma_f32_16x16x32_bf16 v[68:71], v[168:171], v[212:215], 0
	v_mfma_f32_16x16x32_bf16 v[64:67], v[180:183], v[212:215], 0
	v_mfma_f32_16x16x32_bf16 v[116:119], v[172:175], v[192:195], v[116:119]
	v_mfma_f32_16x16x32_bf16 v[112:115], v[184:187], v[192:195], v[112:115]
	v_mfma_f32_16x16x32_bf16 v[100:103], v[172:175], v[200:203], v[100:103]
	v_mfma_f32_16x16x32_bf16 v[96:99], v[184:187], v[200:203], v[96:99]
	v_mfma_f32_16x16x32_bf16 v[84:87], v[172:175], v[208:211], v[84:87]
	v_mfma_f32_16x16x32_bf16 v[80:83], v[184:187], v[208:211], v[80:83]
	v_mfma_f32_16x16x32_bf16 v[68:71], v[172:175], v[216:219], v[68:71]
	v_mfma_f32_16x16x32_bf16 v[64:67], v[184:187], v[216:219], v[64:67]
	s_setprio 0
	s_barrier
	s_add_i32 s68, s57, s16
	v_lshl_add_u64 v[176:177], s[66:67], 0, v[130:131]
	s_mov_b32 m0, s68
	ds_read_b128 v[188:191], v153 offset:16384
	ds_read_b128 v[192:195], v153 offset:17408
	ds_read_b128 v[196:199], v153 offset:18432
	ds_read_b128 v[200:203], v153 offset:19456
	ds_read_b128 v[204:207], v153 offset:20480
	ds_read_b128 v[208:211], v153 offset:21504
	ds_read_b128 v[212:215], v153 offset:22528
	ds_read_b128 v[216:219], v153 offset:23552
	global_load_lds_dwordx4 v[176:177], off
	s_add_i32 m0, s68, 0x2000
	v_lshl_add_u64 v[178:179], s[66:67], 0, v[134:135]
	s_add_u32 s66, s66, s6
	s_addc_u32 s67, s67, s7
	s_add_i32 s68, s58, s16
	global_load_lds_dwordx4 v[178:179], off
	v_lshl_add_u64 v[220:221], s[66:67], 0, v[130:131]
	s_mov_b32 m0, s68
	v_lshl_add_u64 v[222:223], s[66:67], 0, v[134:135]
	global_load_lds_dwordx4 v[220:221], off
	s_add_i32 m0, s68, 0x2000
	v_lshl_add_u64 v[224:225], s[34:35], 0, v[128:129]
	global_load_lds_dwordx4 v[222:223], off
	s_mov_b32 m0, s17
	v_lshl_add_u64 v[226:227], s[34:35], 0, v[132:133]
	global_load_lds_dwordx4 v[224:225], off
	s_mov_b32 m0, s19
	s_nop 0
	global_load_lds_dwordx4 v[226:227], off
	s_waitcnt vmcnt(8)
	s_waitcnt lgkmcnt(0)
	s_barrier
; #define PG8_STAGE(bufoff, gbase, voff) do { _Pragma("unroll") for (int _i = 0; _i < 2; ++_i) \
;         __builtin_amdgcn_global_load_lds((const unsigned*)((const char*)(gbase) + (voff)[_i]), (PG8_LAS unsigned*)(lds + (bufoff) + ldsw + _i * 8192), 16, 0, 0); } while (0)
; #define PG8_LDA(dst, b, h) do { _Pragma("unroll") for (int m = 0; m < 4; ++m) _Pragma("unroll") for (int k = 0; k < 2; ++k) dst[m][k] = *(const PG8_LAS bf16x8*)(lds + PG8_SA(b, h) + aoff + m * 2048 + k * 1024); } while (0)
; #define PG8_LDB(dst, b, h) do { _Pragma("unroll") for (int n = 0; n < 2; ++n) _Pragma("unroll") for (int k = 0; k < 2; ++k) dst[n][k] = *(const PG8_LAS bf16x8*)(lds + PG8_SB(b, h) + boff + n * 2048 + k * 1024); } while (0)
; #define PG8_MMA(ai, bj, At, Bt) do { __builtin_amdgcn_s_setprio(1); _Pragma("unroll") for (int m = 0; m < 4; ++m) _Pragma("unroll") for (int n = 0; n < 2; ++n) _Pragma("unroll") for (int k = 0; k < 2; ++k) \
;         acc[ai][bj][m][n] = __builtin_amdgcn_mfma_f32_16x16x32_bf16(Bt[n][k], At[m][k], acc[ai][bj][m][n], 0, 0, 0); __builtin_amdgcn_s_setprio(0); } while (0)
; #define PG8_WAIT_V(n) asm volatile("s_waitcnt vmcnt(" #n ")" ::: "memory")
; #define PG8_WAIT_L(n) asm volatile("s_waitcnt lgkmcnt(" #n ")" ::: "memory")
; #define PG8_BAR __builtin_amdgcn_s_barrier()
; #define PG8_SCHED __builtin_amdgcn_sched_barrier(0)
; template <class Epi, class Sched, bool ALIGN_EPI = false, bool SP2 = false>
; __device__ __forceinline__ void gemm_phase(PG8_LAS unsigned char* lds, const Gemm g, const Sched& S, const Epi& E) {
;     ...
;             PG8_WAIT_V(8); PG8_WAIT_L(0); PG8_BAR; PG8_MMA(1, 0, At, B0); PG8_MMA(1, 1, At, B1); PG8_BAR; PG8_SCHED;
;             PG8_LDB(B0, 1, 0); PG8_LDB(B1, 1, 1); PG8_SCHED; PG8_LDA(At, 1, 0); PG8_STAGE(PG8_SA(0, 1), a2 + hstep, voffA);
;             PG8_WAIT_V(8); PG8_WAIT_L(0); PG8_BAR; PG8_MMA(0, 0, At, B0); PG8_MMA(0, 1, At, B1); PG8_BAR; PG8_SCHED;
	s_setprio 1
	s_waitcnt lgkmcnt(0)
	v_mfma_f32_16x16x32_bf16 v[60:63], v[144:147], v[188:191], 0
	v_mfma_f32_16x16x32_bf16 v[56:59], v[160:163], v[188:191], 0
	v_mfma_f32_16x16x32_bf16 v[44:47], v[144:147], v[196:199], 0
	v_mfma_f32_16x16x32_bf16 v[40:43], v[160:163], v[196:199], 0
	v_mfma_f32_16x16x32_bf16 v[28:31], v[144:147], v[204:207], 0
	v_mfma_f32_16x16x32_bf16 v[24:27], v[160:163], v[204:207], 0
	v_mfma_f32_16x16x32_bf16 v[12:15], v[144:147], v[212:215], 0
	v_mfma_f32_16x16x32_bf16 v[8:11], v[160:163], v[212:215], 0
	v_mfma_f32_16x16x32_bf16 v[60:63], v[156:159], v[192:195], v[60:63]
	v_mfma_f32_16x16x32_bf16 v[56:59], v[164:167], v[192:195], v[56:59]
	v_mfma_f32_16x16x32_bf16 v[44:47], v[156:159], v[200:203], v[44:47]
	v_mfma_f32_16x16x32_bf16 v[40:43], v[164:167], v[200:203], v[40:43]
	v_mfma_f32_16x16x32_bf16 v[28:31], v[156:159], v[208:211], v[28:31]
	v_mfma_f32_16x16x32_bf16 v[24:27], v[164:167], v[208:211], v[24:27]
	v_mfma_f32_16x16x32_bf16 v[12:15], v[156:159], v[216:219], v[12:15]
	v_mfma_f32_16x16x32_bf16 v[8:11], v[164:167], v[216:219], v[8:11]
	s_setprio 0
	s_setprio 1
	v_mfma_f32_16x16x32_bf16 v[52:55], v[168:171], v[188:191], 0
	v_mfma_f32_16x16x32_bf16 v[48:51], v[180:183], v[188:191], 0
	v_mfma_f32_16x16x32_bf16 v[36:39], v[168:171], v[196:199], 0
	v_mfma_f32_16x16x32_bf16 v[32:35], v[180:183], v[196:199], 0
	v_mfma_f32_16x16x32_bf16 v[20:23], v[168:171], v[204:207], 0
	v_mfma_f32_16x16x32_bf16 v[16:19], v[180:183], v[204:207], 0
	v_mfma_f32_16x16x32_bf16 v[4:7], v[168:171], v[212:215], 0
	v_mfma_f32_16x16x32_bf16 v[0:3], v[180:183], v[212:215], 0
	v_mfma_f32_16x16x32_bf16 v[52:55], v[172:175], v[192:195], v[52:55]
	v_mfma_f32_16x16x32_bf16 v[48:51], v[184:187], v[192:195], v[48:51]
	v_mfma_f32_16x16x32_bf16 v[36:39], v[172:175], v[200:203], v[36:39]
	v_mfma_f32_16x16x32_bf16 v[32:35], v[184:187], v[200:203], v[32:35]
	v_mfma_f32_16x16x32_bf16 v[20:23], v[172:175], v[208:211], v[20:23]
	v_mfma_f32_16x16x32_bf16 v[16:19], v[184:187], v[208:211], v[16:19]
	v_mfma_f32_16x16x32_bf16 v[4:7], v[172:175], v[216:219], v[4:7]
	v_mfma_f32_16x16x32_bf16 v[0:3], v[184:187], v[216:219], v[0:3]
	s_setprio 0
	s_barrier
	s_add_i32 s66, 0, 0x18000
	v_add_u32_e32 v155, s66, v149
	s_add_i32 s67, 0, 0x1c000
	ds_read_b128 v[144:147], v155
	ds_read_b128 v[156:159], v155 offset:1024
	ds_read_b128 v[160:163], v155 offset:2048
	ds_read_b128 v[164:167], v155 offset:3072
	v_add_u32_e32 v155, s67, v149
	ds_read_b128 v[168:171], v155
	ds_read_b128 v[172:175], v155 offset:1024
	ds_read_b128 v[180:183], v155 offset:2048
	ds_read_b128 v[184:187], v155 offset:3072
	s_add_u32 s34, s34, s6
	s_addc_u32 s35, s35, s7
	s_mov_b32 m0, s33
	v_lshl_add_u64 v[228:229], s[34:35], 0, v[128:129]
	ds_read_b128 v[188:191], v153 offset:32768
	ds_read_b128 v[192:195], v153 offset:33792
	ds_read_b128 v[196:199], v153 offset:34816
	ds_read_b128 v[200:203], v153 offset:35840
	ds_read_b128 v[204:207], v153 offset:36864
	ds_read_b128 v[208:211], v153 offset:37888
	ds_read_b128 v[212:215], v153 offset:38912
	ds_read_b128 v[216:219], v153 offset:39936
	global_load_lds_dwordx4 v[228:229], off
	v_lshl_add_u64 v[228:229], s[34:35], 0, v[132:133]
	s_mov_b32 m0, s36
	s_nop 0
	global_load_lds_dwordx4 v[228:229], off
	s_waitcnt vmcnt(8)
	s_waitcnt lgkmcnt(0)
	s_barrier
	s_setprio 1
	s_waitcnt lgkmcnt(0)
	v_mfma_f32_16x16x32_bf16 v[124:127], v[144:147], v[188:191], v[124:127]
	v_mfma_f32_16x16x32_bf16 v[120:123], v[160:163], v[188:191], v[120:123]
	v_mfma_f32_16x16x32_bf16 v[108:111], v[144:147], v[196:199], v[108:111]
	v_mfma_f32_16x16x32_bf16 v[104:107], v[160:163], v[196:199], v[104:107]
	v_mfma_f32_16x16x32_bf16 v[92:95], v[144:147], v[204:207], v[92:95]
	v_mfma_f32_16x16x32_bf16 v[88:91], v[160:163], v[204:207], v[88:91]
	v_mfma_f32_16x16x32_bf16 v[76:79], v[144:147], v[212:215], v[76:79]
	v_mfma_f32_16x16x32_bf16 v[72:75], v[160:163], v[212:215], v[72:75]
	v_mfma_f32_16x16x32_bf16 v[124:127], v[156:159], v[192:195], v[124:127]
	v_mfma_f32_16x16x32_bf16 v[120:123], v[164:167], v[192:195], v[120:123]
	v_mfma_f32_16x16x32_bf16 v[108:111], v[156:159], v[200:203], v[108:111]
	v_mfma_f32_16x16x32_bf16 v[104:107], v[164:167], v[200:203], v[104:107]
	v_mfma_f32_16x16x32_bf16 v[92:95], v[156:159], v[208:211], v[92:95]
	v_mfma_f32_16x16x32_bf16 v[88:91], v[164:167], v[208:211], v[88:91]
	v_mfma_f32_16x16x32_bf16 v[76:79], v[156:159], v[216:219], v[76:79]
	v_mfma_f32_16x16x32_bf16 v[72:75], v[164:167], v[216:219], v[72:75]
	s_setprio 0
	s_setprio 1
	v_mfma_f32_16x16x32_bf16 v[116:119], v[168:171], v[188:191], v[116:119]
	v_mfma_f32_16x16x32_bf16 v[112:115], v[180:183], v[188:191], v[112:115]
	v_mfma_f32_16x16x32_bf16 v[100:103], v[168:171], v[196:199], v[100:103]
	v_mfma_f32_16x16x32_bf16 v[96:99], v[180:183], v[196:199], v[96:99]
	v_mfma_f32_16x16x32_bf16 v[84:87], v[168:171], v[204:207], v[84:87]
	v_mfma_f32_16x16x32_bf16 v[80:83], v[180:183], v[204:207], v[80:83]
	v_mfma_f32_16x16x32_bf16 v[68:71], v[168:171], v[212:215], v[68:71]
	v_mfma_f32_16x16x32_bf16 v[64:67], v[180:183], v[212:215], v[64:67]
	v_mfma_f32_16x16x32_bf16 v[116:119], v[172:175], v[192:195], v[116:119]
	v_mfma_f32_16x16x32_bf16 v[112:115], v[184:187], v[192:195], v[112:115]
	v_mfma_f32_16x16x32_bf16 v[100:103], v[172:175], v[200:203], v[100:103]
	v_mfma_f32_16x16x32_bf16 v[96:99], v[184:187], v[200:203], v[96:99]
	v_mfma_f32_16x16x32_bf16 v[84:87], v[172:175], v[208:211], v[84:87]
	v_mfma_f32_16x16x32_bf16 v[80:83], v[184:187], v[208:211], v[80:83]
	v_mfma_f32_16x16x32_bf16 v[68:71], v[172:175], v[216:219], v[68:71]
	v_mfma_f32_16x16x32_bf16 v[64:67], v[184:187], v[216:219], v[64:67]
	s_setprio 0
	s_barrier
; #define PG8_STAGE(bufoff, gbase, voff) do { _Pragma("unroll") for (int _i = 0; _i < 2; ++_i) \
;         __builtin_amdgcn_global_load_lds((const unsigned*)((const char*)(gbase) + (voff)[_i]), (PG8_LAS unsigned*)(lds + (bufoff) + ldsw + _i * 8192), 16, 0, 0); } while (0)
; #define PG8_LDA(dst, b, h) do { _Pragma("unroll") for (int m = 0; m < 4; ++m) _Pragma("unroll") for (int k = 0; k < 2; ++k) dst[m][k] = *(const PG8_LAS bf16x8*)(lds + PG8_SA(b, h) + aoff + m * 2048 + k * 1024); } while (0)
; #define PG8_MMA(ai, bj, At, Bt) do { __builtin_amdgcn_s_setprio(1); _Pragma("unroll") for (int m = 0; m < 4; ++m) _Pragma("unroll") for (int n = 0; n < 2; ++n) _Pragma("unroll") for (int k = 0; k < 2; ++k) \
;         acc[ai][bj][m][n] = __builtin_amdgcn_mfma_f32_16x16x32_bf16(Bt[n][k], At[m][k], acc[ai][bj][m][n], 0, 0, 0); __builtin_amdgcn_s_setprio(0); } while (0)
; #define PG8_WAIT_V(n) asm volatile("s_waitcnt vmcnt(" #n ")" ::: "memory")
; #define PG8_WAIT_L(n) asm volatile("s_waitcnt lgkmcnt(" #n ")" ::: "memory")
; #define PG8_BAR __builtin_amdgcn_s_barrier()
; #define PG8_SCHED __builtin_amdgcn_sched_barrier(0)
; template <class Epi, class Sched, bool ALIGN_EPI = false, bool SP2 = false>
; __device__ __forceinline__ void gemm_phase(PG8_LAS unsigned char* lds, const Gemm g, const Sched& S, const Epi& E) {
;     ...
;             PG8_LDA(At, 1, 1); PG8_STAGE(PG8_SB(1, 0), b3, voffB); PG8_STAGE(PG8_SB(1, 1), b3 + hstep, voffB); PG8_STAGE(PG8_SA(1, 0), a3, voffA);
;             PG8_WAIT_V(8); PG8_WAIT_L(0); PG8_BAR; PG8_MMA(1, 0, At, B0); PG8_MMA(1, 1, At, B1); PG8_BAR; PG8_SCHED;
	s_add_i32 s34, s66, s16
	v_lshl_add_u64 v[176:177], v[176:177], 0, s[22:23]
	s_mov_b32 m0, s34
	ds_read_b128 v[188:191], v153 offset:49152
	ds_read_b128 v[192:195], v153 offset:50176
	ds_read_b128 v[196:199], v153 offset:51200
	ds_read_b128 v[200:203], v153 offset:52224
	ds_read_b128 v[204:207], v153 offset:53248
	ds_read_b128 v[208:211], v153 offset:54272
	ds_read_b128 v[212:215], v153 offset:55296
	ds_read_b128 v[216:219], v153 offset:56320
	global_load_lds_dwordx4 v[176:177], off
	v_lshl_add_u64 v[176:177], v[178:179], 0, s[22:23]
	s_add_i32 m0, s34, 0x2000
	s_add_i32 s34, s67, s16
	global_load_lds_dwordx4 v[176:177], off
	v_lshl_add_u64 v[176:177], v[220:221], 0, s[22:23]
	s_mov_b32 m0, s34
	s_nop 0
	global_load_lds_dwordx4 v[176:177], off
	v_lshl_add_u64 v[176:177], v[222:223], 0, s[22:23]
	s_add_i32 m0, s34, 0x2000
	s_nop 0
	global_load_lds_dwordx4 v[176:177], off
	v_lshl_add_u64 v[176:177], v[224:225], 0, s[22:23]
	s_mov_b32 m0, s37
	s_nop 0
	global_load_lds_dwordx4 v[176:177], off
	v_lshl_add_u64 v[176:177], v[226:227], 0, s[22:23]
	s_mov_b32 m0, s38
	s_nop 0
	global_load_lds_dwordx4 v[176:177], off
	s_waitcnt vmcnt(8)
	s_waitcnt lgkmcnt(0)
	s_barrier
	s_setprio 1
	s_waitcnt lgkmcnt(0)
	v_mfma_f32_16x16x32_bf16 v[60:63], v[144:147], v[188:191], v[60:63]
	v_mfma_f32_16x16x32_bf16 v[56:59], v[160:163], v[188:191], v[56:59]
	v_mfma_f32_16x16x32_bf16 v[44:47], v[144:147], v[196:199], v[44:47]
	v_mfma_f32_16x16x32_bf16 v[40:43], v[160:163], v[196:199], v[40:43]
	v_mfma_f32_16x16x32_bf16 v[28:31], v[144:147], v[204:207], v[28:31]
	v_mfma_f32_16x16x32_bf16 v[24:27], v[160:163], v[204:207], v[24:27]
	v_mfma_f32_16x16x32_bf16 v[12:15], v[144:147], v[212:215], v[12:15]
	v_mfma_f32_16x16x32_bf16 v[8:11], v[160:163], v[212:215], v[8:11]
	v_mfma_f32_16x16x32_bf16 v[60:63], v[156:159], v[192:195], v[60:63]
	v_mfma_f32_16x16x32_bf16 v[56:59], v[164:167], v[192:195], v[56:59]
	v_mfma_f32_16x16x32_bf16 v[44:47], v[156:159], v[200:203], v[44:47]
	v_mfma_f32_16x16x32_bf16 v[40:43], v[164:167], v[200:203], v[40:43]
	v_mfma_f32_16x16x32_bf16 v[28:31], v[156:159], v[208:211], v[28:31]
	v_mfma_f32_16x16x32_bf16 v[24:27], v[164:167], v[208:211], v[24:27]
	v_mfma_f32_16x16x32_bf16 v[12:15], v[156:159], v[216:219], v[12:15]
	v_mfma_f32_16x16x32_bf16 v[8:11], v[164:167], v[216:219], v[8:11]
	s_setprio 0
	s_setprio 1
	v_mfma_f32_16x16x32_bf16 v[52:55], v[168:171], v[188:191], v[52:55]
	v_mfma_f32_16x16x32_bf16 v[48:51], v[180:183], v[188:191], v[48:51]
	v_mfma_f32_16x16x32_bf16 v[36:39], v[168:171], v[196:199], v[36:39]
	v_mfma_f32_16x16x32_bf16 v[32:35], v[180:183], v[196:199], v[32:35]
	v_mfma_f32_16x16x32_bf16 v[20:23], v[168:171], v[204:207], v[20:23]
	v_mfma_f32_16x16x32_bf16 v[16:19], v[180:183], v[204:207], v[16:19]
	v_mfma_f32_16x16x32_bf16 v[4:7], v[168:171], v[212:215], v[4:7]
	v_mfma_f32_16x16x32_bf16 v[0:3], v[180:183], v[212:215], v[0:3]
	v_mfma_f32_16x16x32_bf16 v[52:55], v[172:175], v[192:195], v[52:55]
	v_mfma_f32_16x16x32_bf16 v[48:51], v[184:187], v[192:195], v[48:51]
	v_mfma_f32_16x16x32_bf16 v[36:39], v[172:175], v[200:203], v[36:39]
	v_mfma_f32_16x16x32_bf16 v[32:35], v[184:187], v[200:203], v[32:35]
	v_mfma_f32_16x16x32_bf16 v[20:23], v[172:175], v[208:211], v[20:23]
	v_mfma_f32_16x16x32_bf16 v[16:19], v[184:187], v[208:211], v[16:19]
	v_mfma_f32_16x16x32_bf16 v[4:7], v[172:175], v[216:219], v[4:7]
	v_mfma_f32_16x16x32_bf16 v[0:3], v[184:187], v[216:219], v[0:3]
	s_setprio 0
	s_barrier
	s_add_u32 s30, s30, 0x100
	s_addc_u32 s31, s31, 0
	s_add_u32 s63, s63, 0x100
	s_addc_u32 s64, s64, 0
	s_cmp_ge_i32 s65, s40
	s_mov_b32 s34, s65
	s_cbranch_scc0 .LBB0_1222
	s_branch .Lpeel_x3

; #define PG8_STAGE(bufoff, gbase, voff) do { _Pragma("unroll") for (int _i = 0; _i < 2; ++_i) \
;         __builtin_amdgcn_global_load_lds((const unsigned*)((const char*)(gbase) + (voff)[_i]), (PG8_LAS unsigned*)(lds + (bufoff) + ldsw + _i * 8192), 16, 0, 0); } while (0)
; #define PG8_LDA(dst, b, h) do { _Pragma("unroll") for (int m = 0; m < 4; ++m) _Pragma("unroll") for (int k = 0; k < 2; ++k) dst[m][k] = *(const PG8_LAS bf16x8*)(lds + PG8_SA(b, h) + aoff + m * 2048 + k * 1024); } while (0)
; #define PG8_LDB(dst, b, h) do { _Pragma("unroll") for (int n = 0; n < 2; ++n) _Pragma("unroll") for (int k = 0; k < 2; ++k) dst[n][k] = *(const PG8_LAS bf16x8*)(lds + PG8_SB(b, h) + boff + n * 2048 + k * 1024); } while (0)
; #define PG8_MMA(ai, bj, At, Bt) do { __builtin_amdgcn_s_setprio(1); _Pragma("unroll") for (int m = 0; m < 4; ++m) _Pragma("unroll") for (int n = 0; n < 2; ++n) _Pragma("unroll") for (int k = 0; k < 2; ++k) \
;         acc[ai][bj][m][n] = __builtin_amdgcn_mfma_f32_16x16x32_bf16(Bt[n][k], At[m][k], acc[ai][bj][m][n], 0, 0, 0); __builtin_amdgcn_s_setprio(0); } while (0)
; #define PG8_WAIT_V(n) asm volatile("s_waitcnt vmcnt(" #n ")" ::: "memory")
; #define PG8_WAIT_L(n) asm volatile("s_waitcnt lgkmcnt(" #n ")" ::: "memory")
; #define PG8_BAR __builtin_amdgcn_s_barrier()
; #define PG8_SCHED __builtin_amdgcn_sched_barrier(0)
; template <class Epi, class Sched, bool ALIGN_EPI = false, bool SP2 = false>
; __device__ __forceinline__ void gemm_phase(PG8_LAS unsigned char* lds, const Gemm g, const Sched& S, const Epi& E) {
;     ...
;             const char* a1 = cA + (size_t)(t + 1) * kstep;
;             const char* a2 = last ? nA : cA + (size_t)(t + 2) * kstep; const char* b2 = last ? nB : cB + (size_t)(t + 2) * kstep;
;             const char* a3 = a2 + kstep; const char* b3 = b2 + kstep;
;             if (last && has_next) S.a_ready(nxt);
;             if constexpr (SP2) {
;             PG8_LDB(B0, 0, 0); PG8_LDB(B1, 0, 1); PG8_SCHED; PG8_LDA(At, 0, 0); PG8_STAGE(PG8_SA(1, 1), a1 + hstep, voffA);
;             PG8_WAIT_V(8); PG8_WAIT_L(0); PG8_BAR; PG8_MMA(0, 0, At, B0); PG8_MMA(0, 1, At, B1); PG8_BAR; PG8_SCHED;
;             PG8_LDA(At, 0, 1); PG8_STAGE(PG8_SB(0, 0), b2, voffB); PG8_STAGE(PG8_SB(0, 1), b2 + hstep, voffB); PG8_STAGE(PG8_SA(0, 0), a2, voffA);
.LBB0_1315:
	s_andn2_b64 vcc, exec, s[20:21]
	s_waitcnt vmcnt(0)
	s_cbranch_vccnz .LBB0_1318
	s_add_u32 s26, s26, 0x80
	s_addc_u32 s27, s27, 0
	s_add_u32 s62, s28, 0x100
	s_addc_u32 s63, s29, 0
	s_mov_b32 s28, 0
	ds_read_b128 v[154:157], v149
	ds_read_b128 v[158:161], v149 offset:1024
	ds_read_b128 v[162:165], v149 offset:2048
	ds_read_b128 v[166:169], v149 offset:3072
	ds_read_b128 v[170:173], v150
	ds_read_b128 v[174:177], v150 offset:1024
	ds_read_b128 v[180:183], v150 offset:2048
	ds_read_b128 v[184:187], v150 offset:3072
	s_add_i32 s64, s28, 2
	s_add_u32 s65, s26, 0x80
	s_addc_u32 s29, s27, 0
	s_cmp_eq_u32 s39, s28
	s_cselect_b32 s28, s0, s65
	s_cselect_b32 s29, s1, s29
	s_cselect_b32 s67, s25, s63
	s_cselect_b32 s66, s24, s62
	v_lshl_add_u64 v[144:145], s[26:27], 0, v[136:137]
	s_add_i32 m0, s30, 0xc000
	ds_read_b128 v[188:191], v151
	ds_read_b128 v[192:195], v151 offset:1024
	ds_read_b128 v[196:199], v151 offset:2048
	ds_read_b128 v[200:203], v151 offset:3072
	ds_read_b128 v[204:207], v151 offset:4096
	ds_read_b128 v[208:211], v151 offset:5120
	ds_read_b128 v[212:215], v151 offset:6144
	ds_read_b128 v[216:219], v151 offset:7168
	global_load_lds_dwordx4 v[144:145], off
	v_lshl_add_u64 v[144:145], s[26:27], 0, v[138:139]
	s_add_i32 m0, s30, 0xe000
	s_nop 0
	global_load_lds_dwordx4 v[144:145], off
	s_waitcnt vmcnt(8)
	s_waitcnt lgkmcnt(0)
	s_barrier
	s_setprio 1
	s_waitcnt lgkmcnt(0)
	v_mfma_f32_16x16x32_bf16 v[116:119], v[154:157], v[188:191], 0
	v_mfma_f32_16x16x32_bf16 v[112:115], v[162:165], v[188:191], 0
	v_mfma_f32_16x16x32_bf16 v[100:103], v[154:157], v[196:199], 0
	v_mfma_f32_16x16x32_bf16 v[96:99], v[162:165], v[196:199], 0
	v_mfma_f32_16x16x32_bf16 v[84:87], v[154:157], v[204:207], 0
	v_mfma_f32_16x16x32_bf16 v[80:83], v[162:165], v[204:207], 0
	v_mfma_f32_16x16x32_bf16 v[68:71], v[154:157], v[212:215], 0
	v_mfma_f32_16x16x32_bf16 v[64:67], v[162:165], v[212:215], 0
	v_mfma_f32_16x16x32_bf16 v[116:119], v[158:161], v[192:195], v[116:119]
	v_mfma_f32_16x16x32_bf16 v[112:115], v[166:169], v[192:195], v[112:115]
	v_mfma_f32_16x16x32_bf16 v[100:103], v[158:161], v[200:203], v[100:103]
	v_mfma_f32_16x16x32_bf16 v[96:99], v[166:169], v[200:203], v[96:99]
	v_mfma_f32_16x16x32_bf16 v[84:87], v[158:161], v[208:211], v[84:87]
	v_mfma_f32_16x16x32_bf16 v[80:83], v[166:169], v[208:211], v[80:83]
	v_mfma_f32_16x16x32_bf16 v[68:71], v[158:161], v[216:219], v[68:71]
	v_mfma_f32_16x16x32_bf16 v[64:67], v[166:169], v[216:219], v[64:67]
	s_setprio 0
	s_setprio 1
	v_mfma_f32_16x16x32_bf16 v[124:127], v[170:173], v[188:191], 0
	v_mfma_f32_16x16x32_bf16 v[120:123], v[180:183], v[188:191], 0
	v_mfma_f32_16x16x32_bf16 v[108:111], v[170:173], v[196:199], 0
	v_mfma_f32_16x16x32_bf16 v[104:107], v[180:183], v[196:199], 0
	v_mfma_f32_16x16x32_bf16 v[92:95], v[170:173], v[204:207], 0
	v_mfma_f32_16x16x32_bf16 v[88:91], v[180:183], v[204:207], 0
	v_mfma_f32_16x16x32_bf16 v[76:79], v[170:173], v[212:215], 0
	v_mfma_f32_16x16x32_bf16 v[72:75], v[180:183], v[212:215], 0
	v_mfma_f32_16x16x32_bf16 v[124:127], v[174:177], v[192:195], v[124:127]
	v_mfma_f32_16x16x32_bf16 v[120:123], v[184:187], v[192:195], v[120:123]
	v_mfma_f32_16x16x32_bf16 v[108:111], v[174:177], v[200:203], v[108:111]
	v_mfma_f32_16x16x32_bf16 v[104:107], v[184:187], v[200:203], v[104:107]
	v_mfma_f32_16x16x32_bf16 v[92:95], v[174:177], v[208:211], v[92:95]
	v_mfma_f32_16x16x32_bf16 v[88:91], v[184:187], v[208:211], v[88:91]
	v_mfma_f32_16x16x32_bf16 v[76:79], v[174:177], v[216:219], v[76:79]
	v_mfma_f32_16x16x32_bf16 v[72:75], v[184:187], v[216:219], v[72:75]
	s_setprio 0
	s_barrier
	s_add_i32 s65, s50, s16
	v_lshl_add_u64 v[144:145], s[66:67], 0, v[132:133]
	s_mov_b32 m0, s65
	ds_read_b128 v[188:191], v151 offset:16384
	ds_read_b128 v[192:195], v151 offset:17408
	ds_read_b128 v[196:199], v151 offset:18432
	ds_read_b128 v[200:203], v151 offset:19456
	ds_read_b128 v[204:207], v151 offset:20480
	ds_read_b128 v[208:211], v151 offset:21504
	ds_read_b128 v[212:215], v151 offset:22528
	ds_read_b128 v[216:219], v151 offset:23552
	global_load_lds_dwordx4 v[144:145], off
	s_add_i32 m0, s65, 0x2000
	v_lshl_add_u64 v[178:179], s[66:67], 0, v[128:129]
	s_add_u32 s66, s66, s8
	s_addc_u32 s67, s67, s9
	s_add_i32 s65, s51, s16
	global_load_lds_dwordx4 v[178:179], off
	v_lshl_add_u64 v[220:221], s[66:67], 0, v[132:133]
	s_mov_b32 m0, s65
	v_lshl_add_u64 v[222:223], s[66:67], 0, v[128:129]
	global_load_lds_dwordx4 v[220:221], off
	s_add_i32 m0, s65, 0x2000
	v_lshl_add_u64 v[224:225], s[28:29], 0, v[134:135]
	global_load_lds_dwordx4 v[222:223], off
	s_mov_b32 m0, s30
	v_lshl_add_u64 v[226:227], s[28:29], 0, v[130:131]
	global_load_lds_dwordx4 v[224:225], off
	s_mov_b32 m0, s31
	s_nop 0
	global_load_lds_dwordx4 v[226:227], off
	s_waitcnt vmcnt(8)
	s_waitcnt lgkmcnt(0)
	s_barrier
; #define PG8_STAGE(bufoff, gbase, voff) do { _Pragma("unroll") for (int _i = 0; _i < 2; ++_i) \
;         __builtin_amdgcn_global_load_lds((const unsigned*)((const char*)(gbase) + (voff)[_i]), (PG8_LAS unsigned*)(lds + (bufoff) + ldsw + _i * 8192), 16, 0, 0); } while (0)
; #define PG8_LDA(dst, b, h) do { _Pragma("unroll") for (int m = 0; m < 4; ++m) _Pragma("unroll") for (int k = 0; k < 2; ++k) dst[m][k] = *(const PG8_LAS bf16x8*)(lds + PG8_SA(b, h) + aoff + m * 2048 + k * 1024); } while (0)
; #define PG8_LDB(dst, b, h) do { _Pragma("unroll") for (int n = 0; n < 2; ++n) _Pragma("unroll") for (int k = 0; k < 2; ++k) dst[n][k] = *(const PG8_LAS bf16x8*)(lds + PG8_SB(b, h) + boff + n * 2048 + k * 1024); } while (0)
; #define PG8_MMA(ai, bj, At, Bt) do { __builtin_amdgcn_s_setprio(1); _Pragma("unroll") for (int m = 0; m < 4; ++m) _Pragma("unroll") for (int n = 0; n < 2; ++n) _Pragma("unroll") for (int k = 0; k < 2; ++k) \
;         acc[ai][bj][m][n] = __builtin_amdgcn_mfma_f32_16x16x32_bf16(Bt[n][k], At[m][k], acc[ai][bj][m][n], 0, 0, 0); __builtin_amdgcn_s_setprio(0); } while (0)
; #define PG8_WAIT_V(n) asm volatile("s_waitcnt vmcnt(" #n ")" ::: "memory")
; #define PG8_WAIT_L(n) asm volatile("s_waitcnt lgkmcnt(" #n ")" ::: "memory")
; #define PG8_BAR __builtin_amdgcn_s_barrier()
; #define PG8_SCHED __builtin_amdgcn_sched_barrier(0)
; template <class Epi, class Sched, bool ALIGN_EPI = false, bool SP2 = false>
; __device__ __forceinline__ void gemm_phase(PG8_LAS unsigned char* lds, const Gemm g, const Sched& S, const Epi& E) {
;     ...
;             PG8_WAIT_V(8); PG8_WAIT_L(0); PG8_BAR; PG8_MMA(1, 0, At, B0); PG8_MMA(1, 1, At, B1); PG8_BAR; PG8_SCHED;
;             PG8_LDB(B0, 1, 0); PG8_LDB(B1, 1, 1); PG8_SCHED; PG8_LDA(At, 1, 0); PG8_STAGE(PG8_SA(0, 1), a2 + hstep, voffA);
;             PG8_WAIT_V(8); PG8_WAIT_L(0); PG8_BAR; PG8_MMA(0, 0, At, B0); PG8_MMA(0, 1, At, B1); PG8_BAR; PG8_SCHED;
	s_setprio 1
	s_waitcnt lgkmcnt(0)
	v_mfma_f32_16x16x32_bf16 v[52:55], v[154:157], v[188:191], 0
	v_mfma_f32_16x16x32_bf16 v[48:51], v[162:165], v[188:191], 0
	v_mfma_f32_16x16x32_bf16 v[36:39], v[154:157], v[196:199], 0
	v_mfma_f32_16x16x32_bf16 v[32:35], v[162:165], v[196:199], 0
	v_mfma_f32_16x16x32_bf16 v[20:23], v[154:157], v[204:207], 0
	v_mfma_f32_16x16x32_bf16 v[16:19], v[162:165], v[204:207], 0
	v_mfma_f32_16x16x32_bf16 v[4:7], v[154:157], v[212:215], 0
	v_mfma_f32_16x16x32_bf16 v[0:3], v[162:165], v[212:215], 0
	v_mfma_f32_16x16x32_bf16 v[52:55], v[158:161], v[192:195], v[52:55]
	v_mfma_f32_16x16x32_bf16 v[48:51], v[166:169], v[192:195], v[48:51]
	v_mfma_f32_16x16x32_bf16 v[36:39], v[158:161], v[200:203], v[36:39]
	v_mfma_f32_16x16x32_bf16 v[32:35], v[166:169], v[200:203], v[32:35]
	v_mfma_f32_16x16x32_bf16 v[20:23], v[158:161], v[208:211], v[20:23]
	v_mfma_f32_16x16x32_bf16 v[16:19], v[166:169], v[208:211], v[16:19]
	v_mfma_f32_16x16x32_bf16 v[4:7], v[158:161], v[216:219], v[4:7]
	v_mfma_f32_16x16x32_bf16 v[0:3], v[166:169], v[216:219], v[0:3]
	s_setprio 0
	s_setprio 1
	v_mfma_f32_16x16x32_bf16 v[60:63], v[170:173], v[188:191], 0
	v_mfma_f32_16x16x32_bf16 v[56:59], v[180:183], v[188:191], 0
	v_mfma_f32_16x16x32_bf16 v[44:47], v[170:173], v[196:199], 0
	v_mfma_f32_16x16x32_bf16 v[40:43], v[180:183], v[196:199], 0
	v_mfma_f32_16x16x32_bf16 v[28:31], v[170:173], v[204:207], 0
	v_mfma_f32_16x16x32_bf16 v[24:27], v[180:183], v[204:207], 0
	v_mfma_f32_16x16x32_bf16 v[12:15], v[170:173], v[212:215], 0
	v_mfma_f32_16x16x32_bf16 v[8:11], v[180:183], v[212:215], 0
	v_mfma_f32_16x16x32_bf16 v[60:63], v[174:177], v[192:195], v[60:63]
	v_mfma_f32_16x16x32_bf16 v[56:59], v[184:187], v[192:195], v[56:59]
	v_mfma_f32_16x16x32_bf16 v[44:47], v[174:177], v[200:203], v[44:47]
	v_mfma_f32_16x16x32_bf16 v[40:43], v[184:187], v[200:203], v[40:43]
	v_mfma_f32_16x16x32_bf16 v[28:31], v[174:177], v[208:211], v[28:31]
	v_mfma_f32_16x16x32_bf16 v[24:27], v[184:187], v[208:211], v[24:27]
	v_mfma_f32_16x16x32_bf16 v[12:15], v[174:177], v[216:219], v[12:15]
	v_mfma_f32_16x16x32_bf16 v[8:11], v[184:187], v[216:219], v[8:11]
	s_setprio 0
	s_barrier
	s_add_i32 s65, 0, 0x18000
	v_add_u32_e32 v153, s65, v147
	s_add_i32 s66, 0, 0x1c000
	ds_read_b128 v[154:157], v153
	ds_read_b128 v[158:161], v153 offset:1024
	ds_read_b128 v[162:165], v153 offset:2048
	ds_read_b128 v[166:169], v153 offset:3072
	v_add_u32_e32 v153, s66, v147
	ds_read_b128 v[170:173], v153
	ds_read_b128 v[174:177], v153 offset:1024
	ds_read_b128 v[180:183], v153 offset:2048
	ds_read_b128 v[184:187], v153 offset:3072
	s_add_u32 s28, s28, s8
	s_addc_u32 s29, s29, s9
	s_mov_b32 m0, s33
	v_lshl_add_u64 v[228:229], s[28:29], 0, v[134:135]
	ds_read_b128 v[188:191], v151 offset:32768
	ds_read_b128 v[192:195], v151 offset:33792
	ds_read_b128 v[196:199], v151 offset:34816
	ds_read_b128 v[200:203], v151 offset:35840
	ds_read_b128 v[204:207], v151 offset:36864
	ds_read_b128 v[208:211], v151 offset:37888
	ds_read_b128 v[212:215], v151 offset:38912
	ds_read_b128 v[216:219], v151 offset:39936
	global_load_lds_dwordx4 v[228:229], off
	v_lshl_add_u64 v[228:229], s[28:29], 0, v[130:131]
	s_mov_b32 m0, s34
	s_nop 0
	global_load_lds_dwordx4 v[228:229], off
	s_waitcnt vmcnt(8)
	s_waitcnt lgkmcnt(0)
	s_barrier
	s_setprio 1
	s_waitcnt lgkmcnt(0)
	v_mfma_f32_16x16x32_bf16 v[116:119], v[154:157], v[188:191], v[116:119]
	v_mfma_f32_16x16x32_bf16 v[112:115], v[162:165], v[188:191], v[112:115]
	v_mfma_f32_16x16x32_bf16 v[100:103], v[154:157], v[196:199], v[100:103]
	v_mfma_f32_16x16x32_bf16 v[96:99], v[162:165], v[196:199], v[96:99]
	v_mfma_f32_16x16x32_bf16 v[84:87], v[154:157], v[204:207], v[84:87]
	v_mfma_f32_16x16x32_bf16 v[80:83], v[162:165], v[204:207], v[80:83]
	v_mfma_f32_16x16x32_bf16 v[68:71], v[154:157], v[212:215], v[68:71]
	v_mfma_f32_16x16x32_bf16 v[64:67], v[162:165], v[212:215], v[64:67]
	v_mfma_f32_16x16x32_bf16 v[116:119], v[158:161], v[192:195], v[116:119]
	v_mfma_f32_16x16x32_bf16 v[112:115], v[166:169], v[192:195], v[112:115]
	v_mfma_f32_16x16x32_bf16 v[100:103], v[158:161], v[200:203], v[100:103]
	v_mfma_f32_16x16x32_bf16 v[96:99], v[166:169], v[200:203], v[96:99]
	v_mfma_f32_16x16x32_bf16 v[84:87], v[158:161], v[208:211], v[84:87]
	v_mfma_f32_16x16x32_bf16 v[80:83], v[166:169], v[208:211], v[80:83]
	v_mfma_f32_16x16x32_bf16 v[68:71], v[158:161], v[216:219], v[68:71]
	v_mfma_f32_16x16x32_bf16 v[64:67], v[166:169], v[216:219], v[64:67]
	s_setprio 0
	s_setprio 1
	v_mfma_f32_16x16x32_bf16 v[124:127], v[170:173], v[188:191], v[124:127]
	v_mfma_f32_16x16x32_bf16 v[120:123], v[180:183], v[188:191], v[120:123]
	v_mfma_f32_16x16x32_bf16 v[108:111], v[170:173], v[196:199], v[108:111]
	v_mfma_f32_16x16x32_bf16 v[104:107], v[180:183], v[196:199], v[104:107]
	v_mfma_f32_16x16x32_bf16 v[92:95], v[170:173], v[204:207], v[92:95]
	v_mfma_f32_16x16x32_bf16 v[88:91], v[180:183], v[204:207], v[88:91]
	v_mfma_f32_16x16x32_bf16 v[76:79], v[170:173], v[212:215], v[76:79]
	v_mfma_f32_16x16x32_bf16 v[72:75], v[180:183], v[212:215], v[72:75]
	v_mfma_f32_16x16x32_bf16 v[124:127], v[174:177], v[192:195], v[124:127]
	v_mfma_f32_16x16x32_bf16 v[120:123], v[184:187], v[192:195], v[120:123]
	v_mfma_f32_16x16x32_bf16 v[108:111], v[174:177], v[200:203], v[108:111]
	v_mfma_f32_16x16x32_bf16 v[104:107], v[184:187], v[200:203], v[104:107]
	v_mfma_f32_16x16x32_bf16 v[92:95], v[174:177], v[208:211], v[92:95]
	v_mfma_f32_16x16x32_bf16 v[88:91], v[184:187], v[208:211], v[88:91]
	v_mfma_f32_16x16x32_bf16 v[76:79], v[174:177], v[216:219], v[76:79]
	v_mfma_f32_16x16x32_bf16 v[72:75], v[184:187], v[216:219], v[72:75]
	s_setprio 0
	s_barrier
; #define PG8_STAGE(bufoff, gbase, voff) do { _Pragma("unroll") for (int _i = 0; _i < 2; ++_i) \
;         __builtin_amdgcn_global_load_lds((const unsigned*)((const char*)(gbase) + (voff)[_i]), (PG8_LAS unsigned*)(lds + (bufoff) + ldsw + _i * 8192), 16, 0, 0); } while (0)
; #define PG8_LDA(dst, b, h) do { _Pragma("unroll") for (int m = 0; m < 4; ++m) _Pragma("unroll") for (int k = 0; k < 2; ++k) dst[m][k] = *(const PG8_LAS bf16x8*)(lds + PG8_SA(b, h) + aoff + m * 2048 + k * 1024); } while (0)
; #define PG8_MMA(ai, bj, At, Bt) do { __builtin_amdgcn_s_setprio(1); _Pragma("unroll") for (int m = 0; m < 4; ++m) _Pragma("unroll") for (int n = 0; n < 2; ++n) _Pragma("unroll") for (int k = 0; k < 2; ++k) \
;         acc[ai][bj][m][n] = __builtin_amdgcn_mfma_f32_16x16x32_bf16(Bt[n][k], At[m][k], acc[ai][bj][m][n], 0, 0, 0); __builtin_amdgcn_s_setprio(0); } while (0)
; #define PG8_WAIT_V(n) asm volatile("s_waitcnt vmcnt(" #n ")" ::: "memory")
; #define PG8_WAIT_L(n) asm volatile("s_waitcnt lgkmcnt(" #n ")" ::: "memory")
; #define PG8_BAR __builtin_amdgcn_s_barrier()
; #define PG8_SCHED __builtin_amdgcn_sched_barrier(0)
; template <class Epi, class Sched, bool ALIGN_EPI = false, bool SP2 = false>
; __device__ __forceinline__ void gemm_phase(PG8_LAS unsigned char* lds, const Gemm g, const Sched& S, const Epi& E) {
;     ...
;             PG8_LDA(At, 1, 1); PG8_STAGE(PG8_SB(1, 0), b3, voffB); PG8_STAGE(PG8_SB(1, 1), b3 + hstep, voffB); PG8_STAGE(PG8_SA(1, 0), a3, voffA);
;             PG8_WAIT_V(8); PG8_WAIT_L(0); PG8_BAR; PG8_MMA(1, 0, At, B0); PG8_MMA(1, 1, At, B1); PG8_BAR; PG8_SCHED;
	s_add_i32 s28, s65, s16
	v_lshl_add_u64 v[144:145], v[144:145], 0, s[14:15]
	s_mov_b32 m0, s28
	ds_read_b128 v[188:191], v151 offset:49152
	ds_read_b128 v[192:195], v151 offset:50176
	ds_read_b128 v[196:199], v151 offset:51200
	ds_read_b128 v[200:203], v151 offset:52224
	ds_read_b128 v[204:207], v151 offset:53248
	ds_read_b128 v[208:211], v151 offset:54272
	ds_read_b128 v[212:215], v151 offset:55296
	ds_read_b128 v[216:219], v151 offset:56320
	global_load_lds_dwordx4 v[144:145], off
	v_lshl_add_u64 v[144:145], v[178:179], 0, s[14:15]
	s_add_i32 m0, s28, 0x2000
	s_add_i32 s28, s66, s16
	global_load_lds_dwordx4 v[144:145], off
	v_lshl_add_u64 v[144:145], v[220:221], 0, s[14:15]
	s_mov_b32 m0, s28
	s_nop 0
	global_load_lds_dwordx4 v[144:145], off
	v_lshl_add_u64 v[144:145], v[222:223], 0, s[14:15]
	s_add_i32 m0, s28, 0x2000
	s_nop 0
	global_load_lds_dwordx4 v[144:145], off
	v_lshl_add_u64 v[144:145], v[224:225], 0, s[14:15]
	s_mov_b32 m0, s36
	s_nop 0
	global_load_lds_dwordx4 v[144:145], off
	v_lshl_add_u64 v[144:145], v[226:227], 0, s[14:15]
	s_mov_b32 m0, s37
	s_nop 0
	global_load_lds_dwordx4 v[144:145], off
	s_waitcnt vmcnt(8)
	s_waitcnt lgkmcnt(0)
	s_barrier
	s_setprio 1
	s_waitcnt lgkmcnt(0)
	v_mfma_f32_16x16x32_bf16 v[52:55], v[154:157], v[188:191], v[52:55]
	v_mfma_f32_16x16x32_bf16 v[48:51], v[162:165], v[188:191], v[48:51]
	v_mfma_f32_16x16x32_bf16 v[36:39], v[154:157], v[196:199], v[36:39]
	v_mfma_f32_16x16x32_bf16 v[32:35], v[162:165], v[196:199], v[32:35]
	v_mfma_f32_16x16x32_bf16 v[20:23], v[154:157], v[204:207], v[20:23]
	v_mfma_f32_16x16x32_bf16 v[16:19], v[162:165], v[204:207], v[16:19]
	v_mfma_f32_16x16x32_bf16 v[4:7], v[154:157], v[212:215], v[4:7]
	v_mfma_f32_16x16x32_bf16 v[0:3], v[162:165], v[212:215], v[0:3]
	v_mfma_f32_16x16x32_bf16 v[52:55], v[158:161], v[192:195], v[52:55]
	v_mfma_f32_16x16x32_bf16 v[48:51], v[166:169], v[192:195], v[48:51]
	v_mfma_f32_16x16x32_bf16 v[36:39], v[158:161], v[200:203], v[36:39]
	v_mfma_f32_16x16x32_bf16 v[32:35], v[166:169], v[200:203], v[32:35]
	v_mfma_f32_16x16x32_bf16 v[20:23], v[158:161], v[208:211], v[20:23]
	v_mfma_f32_16x16x32_bf16 v[16:19], v[166:169], v[208:211], v[16:19]
	v_mfma_f32_16x16x32_bf16 v[4:7], v[158:161], v[216:219], v[4:7]
	v_mfma_f32_16x16x32_bf16 v[0:3], v[166:169], v[216:219], v[0:3]
	s_setprio 0
	s_setprio 1
	v_mfma_f32_16x16x32_bf16 v[60:63], v[170:173], v[188:191], v[60:63]
	v_mfma_f32_16x16x32_bf16 v[56:59], v[180:183], v[188:191], v[56:59]
	v_mfma_f32_16x16x32_bf16 v[44:47], v[170:173], v[196:199], v[44:47]
	v_mfma_f32_16x16x32_bf16 v[40:43], v[180:183], v[196:199], v[40:43]
	v_mfma_f32_16x16x32_bf16 v[28:31], v[170:173], v[204:207], v[28:31]
	v_mfma_f32_16x16x32_bf16 v[24:27], v[180:183], v[204:207], v[24:27]
	v_mfma_f32_16x16x32_bf16 v[12:15], v[170:173], v[212:215], v[12:15]
	v_mfma_f32_16x16x32_bf16 v[8:11], v[180:183], v[212:215], v[8:11]
	v_mfma_f32_16x16x32_bf16 v[60:63], v[174:177], v[192:195], v[60:63]
	v_mfma_f32_16x16x32_bf16 v[56:59], v[184:187], v[192:195], v[56:59]
	v_mfma_f32_16x16x32_bf16 v[44:47], v[174:177], v[200:203], v[44:47]
	v_mfma_f32_16x16x32_bf16 v[40:43], v[184:187], v[200:203], v[40:43]
	v_mfma_f32_16x16x32_bf16 v[28:31], v[174:177], v[208:211], v[28:31]
	v_mfma_f32_16x16x32_bf16 v[24:27], v[184:187], v[208:211], v[24:27]
	v_mfma_f32_16x16x32_bf16 v[12:15], v[174:177], v[216:219], v[12:15]
	v_mfma_f32_16x16x32_bf16 v[8:11], v[184:187], v[216:219], v[8:11]
	s_setprio 0
	s_barrier
	s_add_u32 s26, s26, 0x100
	s_addc_u32 s27, s27, 0
	s_add_u32 s62, s62, 0x100
	s_addc_u32 s63, s63, 0
	s_cmp_ge_i32 s64, s38
	s_mov_b32 s28, s64
	s_cbranch_scc0 .LBB0_1317
	s_branch .Lpeel_x4

; #define PG8_BAR __builtin_amdgcn_s_barrier()
; template <class Epi, class Sched, bool ALIGN_EPI = false, bool SP2 = false>
; __device__ __forceinline__ void gemm_phase(PG8_LAS unsigned char* lds, const Gemm g, const Sched& S, const Epi& E) {
;     ...
;         if constexpr (ALIGN_EPI) { if (wr == 0) PG8_BAR; }
.Lpeel_x4:
.LBB0_1318:
	s_and_b64 vcc, exec, s[22:23]
	s_cbranch_vccz .LBB0_1320
	s_barrier

; #define PG8_STAGE(bufoff, gbase, voff) do { _Pragma("unroll") for (int _i = 0; _i < 2; ++_i) \
;         __builtin_amdgcn_global_load_lds((const unsigned*)((const char*)(gbase) + (voff)[_i]), (PG8_LAS unsigned*)(lds + (bufoff) + ldsw + _i * 8192), 16, 0, 0); } while (0)
; #define PG8_LDA(dst, b, h) do { _Pragma("unroll") for (int m = 0; m < 4; ++m) _Pragma("unroll") for (int k = 0; k < 2; ++k) dst[m][k] = *(const PG8_LAS bf16x8*)(lds + PG8_SA(b, h) + aoff + m * 2048 + k * 1024); } while (0)
; #define PG8_LDB(dst, b, h) do { _Pragma("unroll") for (int n = 0; n < 2; ++n) _Pragma("unroll") for (int k = 0; k < 2; ++k) dst[n][k] = *(const PG8_LAS bf16x8*)(lds + PG8_SB(b, h) + boff + n * 2048 + k * 1024); } while (0)
; #define PG8_MMA(ai, bj, At, Bt) do { __builtin_amdgcn_s_setprio(1); _Pragma("unroll") for (int m = 0; m < 4; ++m) _Pragma("unroll") for (int n = 0; n < 2; ++n) _Pragma("unroll") for (int k = 0; k < 2; ++k) \
;         acc[ai][bj][m][n] = __builtin_amdgcn_mfma_f32_16x16x32_bf16(Bt[n][k], At[m][k], acc[ai][bj][m][n], 0, 0, 0); __builtin_amdgcn_s_setprio(0); } while (0)
; #define PG8_WAIT_V(n) asm volatile("s_waitcnt vmcnt(" #n ")" ::: "memory")
; #define PG8_WAIT_L(n) asm volatile("s_waitcnt lgkmcnt(" #n ")" ::: "memory")
; #define PG8_BAR __builtin_amdgcn_s_barrier()
; #define PG8_SCHED __builtin_amdgcn_sched_barrier(0)
; template <class Epi, class Sched, bool ALIGN_EPI = false, bool SP2 = false>
; __device__ __forceinline__ void gemm_phase(PG8_LAS unsigned char* lds, const Gemm g, const Sched& S, const Epi& E) {
;     ...
;             const char* a1 = cA + (size_t)(t + 1) * kstep;
;             const char* a2 = last ? nA : cA + (size_t)(t + 2) * kstep; const char* b2 = last ? nB : cB + (size_t)(t + 2) * kstep;
;             const char* a3 = a2 + kstep; const char* b3 = b2 + kstep;
;             if (last && has_next) S.a_ready(nxt);
;             if constexpr (SP2) {
;             PG8_LDB(B0, 0, 0); PG8_LDB(B1, 0, 1); PG8_SCHED; PG8_LDA(At, 0, 0); PG8_STAGE(PG8_SA(1, 1), a1 + hstep, voffA);
;             PG8_WAIT_V(8); PG8_WAIT_L(0); PG8_BAR; PG8_MMA(0, 0, At, B0); PG8_MMA(0, 1, At, B1); PG8_BAR; PG8_SCHED;
;             PG8_LDA(At, 0, 1); PG8_STAGE(PG8_SB(0, 0), b2, voffB); PG8_STAGE(PG8_SB(0, 1), b2 + hstep, voffB); PG8_STAGE(PG8_SA(0, 0), a2, voffA);
.LBB0_1409:
	v_mov_b32_e32 v151, 0
	s_andn2_b64 vcc, exec, s[24:25]
	v_mov_b32_e32 v150, 0
	v_mov_b32_e32 v155, 0
	v_mov_b32_e32 v154, 0
	v_mov_b32_e32 v153, 0
	v_mov_b32_e32 v152, 0
	v_mov_b32_e32 v149, 0
	v_mov_b32_e32 v148, 0
	s_waitcnt vmcnt(0)
	v_mov_b32_e32 v145, 0
	v_mov_b32_e32 v144, 0
	v_mov_b32_e32 v147, 0
	v_mov_b32_e32 v146, 0
	s_waitcnt lgkmcnt(0)
	s_cbranch_vccnz .LBB0_1413
	s_add_u32 s30, s30, 0x80
	s_addc_u32 s31, s31, 0
	s_add_u32 s63, s34, 0x100
	s_addc_u32 s64, s35, 0
	s_mov_b32 s34, 0
	ds_read_b128 v[144:147], v159
	ds_read_b128 v[148:151], v159 offset:1024
	ds_read_b128 v[152:155], v159 offset:2048
	ds_read_b128 v[164:167], v159 offset:3072
	ds_read_b128 v[168:171], v160
	ds_read_b128 v[172:175], v160 offset:1024
	ds_read_b128 v[180:183], v160 offset:2048
	ds_read_b128 v[184:187], v160 offset:3072
	s_add_i32 s65, s34, 2
	s_add_u32 s66, s30, 0x80
	s_addc_u32 s35, s31, 0
	s_cmp_eq_u32 s41, s34
	s_cselect_b32 s34, s0, s66
	s_cselect_b32 s35, s1, s35
	s_cselect_b32 s67, s29, s64
	s_cselect_b32 s66, s28, s63
	v_lshl_add_u64 v[176:177], s[30:31], 0, v[136:137]
	s_add_i32 m0, s17, 0xc000
	ds_read_b128 v[188:191], v161
	ds_read_b128 v[192:195], v161 offset:1024
	ds_read_b128 v[196:199], v161 offset:2048
	ds_read_b128 v[200:203], v161 offset:3072
	ds_read_b128 v[204:207], v161 offset:4096
	ds_read_b128 v[208:211], v161 offset:5120
	ds_read_b128 v[212:215], v161 offset:6144
	ds_read_b128 v[216:219], v161 offset:7168
	global_load_lds_dwordx4 v[176:177], off
	v_lshl_add_u64 v[176:177], s[30:31], 0, v[138:139]
	s_add_i32 m0, s17, 0xe000
	s_nop 0
	global_load_lds_dwordx4 v[176:177], off
	s_waitcnt vmcnt(8)
	s_waitcnt lgkmcnt(0)
	s_barrier
	s_setprio 1
	s_waitcnt lgkmcnt(0)
	v_mfma_f32_16x16x32_bf16 v[124:127], v[144:147], v[188:191], 0
	v_mfma_f32_16x16x32_bf16 v[120:123], v[152:155], v[188:191], 0
	v_mfma_f32_16x16x32_bf16 v[116:119], v[144:147], v[196:199], 0
	v_mfma_f32_16x16x32_bf16 v[112:115], v[152:155], v[196:199], 0
	v_mfma_f32_16x16x32_bf16 v[104:107], v[144:147], v[204:207], 0
	v_mfma_f32_16x16x32_bf16 v[96:99], v[152:155], v[204:207], 0
	v_mfma_f32_16x16x32_bf16 v[88:91], v[144:147], v[212:215], 0
	v_mfma_f32_16x16x32_bf16 v[80:83], v[152:155], v[212:215], 0
	v_mfma_f32_16x16x32_bf16 v[124:127], v[148:151], v[192:195], v[124:127]
	v_mfma_f32_16x16x32_bf16 v[120:123], v[164:167], v[192:195], v[120:123]
	v_mfma_f32_16x16x32_bf16 v[116:119], v[148:151], v[200:203], v[116:119]
	v_mfma_f32_16x16x32_bf16 v[112:115], v[164:167], v[200:203], v[112:115]
	v_mfma_f32_16x16x32_bf16 v[104:107], v[148:151], v[208:211], v[104:107]
	v_mfma_f32_16x16x32_bf16 v[96:99], v[164:167], v[208:211], v[96:99]
	v_mfma_f32_16x16x32_bf16 v[88:91], v[148:151], v[216:219], v[88:91]
	v_mfma_f32_16x16x32_bf16 v[80:83], v[164:167], v[216:219], v[80:83]
	s_setprio 0
	s_setprio 1
	v_mfma_f32_16x16x32_bf16 v[108:111], v[168:171], v[188:191], 0
	v_mfma_f32_16x16x32_bf16 v[100:103], v[180:183], v[188:191], 0
	v_mfma_f32_16x16x32_bf16 v[92:95], v[168:171], v[196:199], 0
	v_mfma_f32_16x16x32_bf16 v[84:87], v[180:183], v[196:199], 0
	v_mfma_f32_16x16x32_bf16 v[76:79], v[168:171], v[204:207], 0
	v_mfma_f32_16x16x32_bf16 v[72:75], v[180:183], v[204:207], 0
	v_mfma_f32_16x16x32_bf16 v[68:71], v[168:171], v[212:215], 0
	v_mfma_f32_16x16x32_bf16 v[64:67], v[180:183], v[212:215], 0
	v_mfma_f32_16x16x32_bf16 v[108:111], v[172:175], v[192:195], v[108:111]
	v_mfma_f32_16x16x32_bf16 v[100:103], v[184:187], v[192:195], v[100:103]
	v_mfma_f32_16x16x32_bf16 v[92:95], v[172:175], v[200:203], v[92:95]
	v_mfma_f32_16x16x32_bf16 v[84:87], v[184:187], v[200:203], v[84:87]
	v_mfma_f32_16x16x32_bf16 v[76:79], v[172:175], v[208:211], v[76:79]
	v_mfma_f32_16x16x32_bf16 v[72:75], v[184:187], v[208:211], v[72:75]
	v_mfma_f32_16x16x32_bf16 v[68:71], v[172:175], v[216:219], v[68:71]
	v_mfma_f32_16x16x32_bf16 v[64:67], v[184:187], v[216:219], v[64:67]
	s_setprio 0
	s_barrier
	s_add_i32 s68, s57, s16
	v_lshl_add_u64 v[176:177], s[66:67], 0, v[130:131]
	s_mov_b32 m0, s68
	ds_read_b128 v[188:191], v161 offset:16384
	ds_read_b128 v[192:195], v161 offset:17408
	ds_read_b128 v[196:199], v161 offset:18432
	ds_read_b128 v[200:203], v161 offset:19456
	ds_read_b128 v[204:207], v161 offset:20480
	ds_read_b128 v[208:211], v161 offset:21504
	ds_read_b128 v[212:215], v161 offset:22528
	ds_read_b128 v[216:219], v161 offset:23552
	global_load_lds_dwordx4 v[176:177], off
	s_add_i32 m0, s68, 0x2000
	v_lshl_add_u64 v[178:179], s[66:67], 0, v[134:135]
	s_add_u32 s66, s66, s6
	s_addc_u32 s67, s67, s7
	s_add_i32 s68, s58, s16
	global_load_lds_dwordx4 v[178:179], off
	v_lshl_add_u64 v[220:221], s[66:67], 0, v[130:131]
	s_mov_b32 m0, s68
	v_lshl_add_u64 v[222:223], s[66:67], 0, v[134:135]
	global_load_lds_dwordx4 v[220:221], off
	s_add_i32 m0, s68, 0x2000
	v_lshl_add_u64 v[224:225], s[34:35], 0, v[128:129]
	global_load_lds_dwordx4 v[222:223], off
	s_mov_b32 m0, s17
	v_lshl_add_u64 v[226:227], s[34:35], 0, v[132:133]
	global_load_lds_dwordx4 v[224:225], off
	s_mov_b32 m0, s19
	s_nop 0
	global_load_lds_dwordx4 v[226:227], off
	s_waitcnt vmcnt(8)
	s_waitcnt lgkmcnt(0)
	s_barrier
; #define PG8_STAGE(bufoff, gbase, voff) do { _Pragma("unroll") for (int _i = 0; _i < 2; ++_i) \
;         __builtin_amdgcn_global_load_lds((const unsigned*)((const char*)(gbase) + (voff)[_i]), (PG8_LAS unsigned*)(lds + (bufoff) + ldsw + _i * 8192), 16, 0, 0); } while (0)
; #define PG8_LDA(dst, b, h) do { _Pragma("unroll") for (int m = 0; m < 4; ++m) _Pragma("unroll") for (int k = 0; k < 2; ++k) dst[m][k] = *(const PG8_LAS bf16x8*)(lds + PG8_SA(b, h) + aoff + m * 2048 + k * 1024); } while (0)
; #define PG8_LDB(dst, b, h) do { _Pragma("unroll") for (int n = 0; n < 2; ++n) _Pragma("unroll") for (int k = 0; k < 2; ++k) dst[n][k] = *(const PG8_LAS bf16x8*)(lds + PG8_SB(b, h) + boff + n * 2048 + k * 1024); } while (0)
; #define PG8_MMA(ai, bj, At, Bt) do { __builtin_amdgcn_s_setprio(1); _Pragma("unroll") for (int m = 0; m < 4; ++m) _Pragma("unroll") for (int n = 0; n < 2; ++n) _Pragma("unroll") for (int k = 0; k < 2; ++k) \
;         acc[ai][bj][m][n] = __builtin_amdgcn_mfma_f32_16x16x32_bf16(Bt[n][k], At[m][k], acc[ai][bj][m][n], 0, 0, 0); __builtin_amdgcn_s_setprio(0); } while (0)
; #define PG8_WAIT_V(n) asm volatile("s_waitcnt vmcnt(" #n ")" ::: "memory")
; #define PG8_WAIT_L(n) asm volatile("s_waitcnt lgkmcnt(" #n ")" ::: "memory")
; #define PG8_BAR __builtin_amdgcn_s_barrier()
; #define PG8_SCHED __builtin_amdgcn_sched_barrier(0)
; template <class Epi, class Sched, bool ALIGN_EPI = false, bool SP2 = false>
; __device__ __forceinline__ void gemm_phase(PG8_LAS unsigned char* lds, const Gemm g, const Sched& S, const Epi& E) {
;     ...
;             PG8_WAIT_V(8); PG8_WAIT_L(0); PG8_BAR; PG8_MMA(1, 0, At, B0); PG8_MMA(1, 1, At, B1); PG8_BAR; PG8_SCHED;
;             PG8_LDB(B0, 1, 0); PG8_LDB(B1, 1, 1); PG8_SCHED; PG8_LDA(At, 1, 0); PG8_STAGE(PG8_SA(0, 1), a2 + hstep, voffA);
;             PG8_WAIT_V(8); PG8_WAIT_L(0); PG8_BAR; PG8_MMA(0, 0, At, B0); PG8_MMA(0, 1, At, B1); PG8_BAR; PG8_SCHED;
	s_setprio 1
	s_waitcnt lgkmcnt(0)
	v_mfma_f32_16x16x32_bf16 v[60:63], v[144:147], v[188:191], 0
	v_mfma_f32_16x16x32_bf16 v[56:59], v[152:155], v[188:191], 0
	v_mfma_f32_16x16x32_bf16 v[52:55], v[144:147], v[196:199], 0
	v_mfma_f32_16x16x32_bf16 v[48:51], v[152:155], v[196:199], 0
	v_mfma_f32_16x16x32_bf16 v[40:43], v[144:147], v[204:207], 0
	v_mfma_f32_16x16x32_bf16 v[32:35], v[152:155], v[204:207], 0
	v_mfma_f32_16x16x32_bf16 v[24:27], v[144:147], v[212:215], 0
	v_mfma_f32_16x16x32_bf16 v[16:19], v[152:155], v[212:215], 0
	v_mfma_f32_16x16x32_bf16 v[60:63], v[148:151], v[192:195], v[60:63]
	v_mfma_f32_16x16x32_bf16 v[56:59], v[164:167], v[192:195], v[56:59]
	v_mfma_f32_16x16x32_bf16 v[52:55], v[148:151], v[200:203], v[52:55]
	v_mfma_f32_16x16x32_bf16 v[48:51], v[164:167], v[200:203], v[48:51]
	v_mfma_f32_16x16x32_bf16 v[40:43], v[148:151], v[208:211], v[40:43]
	v_mfma_f32_16x16x32_bf16 v[32:35], v[164:167], v[208:211], v[32:35]
	v_mfma_f32_16x16x32_bf16 v[24:27], v[148:151], v[216:219], v[24:27]
	v_mfma_f32_16x16x32_bf16 v[16:19], v[164:167], v[216:219], v[16:19]
	s_setprio 0
	s_setprio 1
	v_mfma_f32_16x16x32_bf16 v[44:47], v[168:171], v[188:191], 0
	v_mfma_f32_16x16x32_bf16 v[36:39], v[180:183], v[188:191], 0
	v_mfma_f32_16x16x32_bf16 v[28:31], v[168:171], v[196:199], 0
	v_mfma_f32_16x16x32_bf16 v[20:23], v[180:183], v[196:199], 0
	v_mfma_f32_16x16x32_bf16 v[12:15], v[168:171], v[204:207], 0
	v_mfma_f32_16x16x32_bf16 v[8:11], v[180:183], v[204:207], 0
	v_mfma_f32_16x16x32_bf16 v[4:7], v[168:171], v[212:215], 0
	v_mfma_f32_16x16x32_bf16 v[0:3], v[180:183], v[212:215], 0
	v_mfma_f32_16x16x32_bf16 v[44:47], v[172:175], v[192:195], v[44:47]
	v_mfma_f32_16x16x32_bf16 v[36:39], v[184:187], v[192:195], v[36:39]
	v_mfma_f32_16x16x32_bf16 v[28:31], v[172:175], v[200:203], v[28:31]
	v_mfma_f32_16x16x32_bf16 v[20:23], v[184:187], v[200:203], v[20:23]
	v_mfma_f32_16x16x32_bf16 v[12:15], v[172:175], v[208:211], v[12:15]
	v_mfma_f32_16x16x32_bf16 v[8:11], v[184:187], v[208:211], v[8:11]
	v_mfma_f32_16x16x32_bf16 v[4:7], v[172:175], v[216:219], v[4:7]
	v_mfma_f32_16x16x32_bf16 v[0:3], v[184:187], v[216:219], v[0:3]
	s_setprio 0
	s_barrier
	s_add_i32 s66, 0, 0x18000
	v_add_u32_e32 v163, s66, v157
	s_add_i32 s67, 0, 0x1c000
	ds_read_b128 v[144:147], v163
	ds_read_b128 v[148:151], v163 offset:1024
	ds_read_b128 v[152:155], v163 offset:2048
	ds_read_b128 v[164:167], v163 offset:3072
	v_add_u32_e32 v163, s67, v157
	ds_read_b128 v[168:171], v163
	ds_read_b128 v[172:175], v163 offset:1024
	ds_read_b128 v[180:183], v163 offset:2048
	ds_read_b128 v[184:187], v163 offset:3072
	s_add_u32 s34, s34, s6
	s_addc_u32 s35, s35, s7
	s_mov_b32 m0, s33
	v_lshl_add_u64 v[228:229], s[34:35], 0, v[128:129]
	ds_read_b128 v[188:191], v161 offset:32768
	ds_read_b128 v[192:195], v161 offset:33792
	ds_read_b128 v[196:199], v161 offset:34816
	ds_read_b128 v[200:203], v161 offset:35840
	ds_read_b128 v[204:207], v161 offset:36864
	ds_read_b128 v[208:211], v161 offset:37888
	ds_read_b128 v[212:215], v161 offset:38912
	ds_read_b128 v[216:219], v161 offset:39936
	global_load_lds_dwordx4 v[228:229], off
	v_lshl_add_u64 v[228:229], s[34:35], 0, v[132:133]
	s_mov_b32 m0, s36
	s_nop 0
	global_load_lds_dwordx4 v[228:229], off
	s_waitcnt vmcnt(8)
	s_waitcnt lgkmcnt(0)
	s_barrier
	s_setprio 1
	s_waitcnt lgkmcnt(0)
	v_mfma_f32_16x16x32_bf16 v[124:127], v[144:147], v[188:191], v[124:127]
	v_mfma_f32_16x16x32_bf16 v[120:123], v[152:155], v[188:191], v[120:123]
	v_mfma_f32_16x16x32_bf16 v[116:119], v[144:147], v[196:199], v[116:119]
	v_mfma_f32_16x16x32_bf16 v[112:115], v[152:155], v[196:199], v[112:115]
	v_mfma_f32_16x16x32_bf16 v[104:107], v[144:147], v[204:207], v[104:107]
	v_mfma_f32_16x16x32_bf16 v[96:99], v[152:155], v[204:207], v[96:99]
	v_mfma_f32_16x16x32_bf16 v[88:91], v[144:147], v[212:215], v[88:91]
	v_mfma_f32_16x16x32_bf16 v[80:83], v[152:155], v[212:215], v[80:83]
	v_mfma_f32_16x16x32_bf16 v[124:127], v[148:151], v[192:195], v[124:127]
	v_mfma_f32_16x16x32_bf16 v[120:123], v[164:167], v[192:195], v[120:123]
	v_mfma_f32_16x16x32_bf16 v[116:119], v[148:151], v[200:203], v[116:119]
	v_mfma_f32_16x16x32_bf16 v[112:115], v[164:167], v[200:203], v[112:115]
	v_mfma_f32_16x16x32_bf16 v[104:107], v[148:151], v[208:211], v[104:107]
	v_mfma_f32_16x16x32_bf16 v[96:99], v[164:167], v[208:211], v[96:99]
	v_mfma_f32_16x16x32_bf16 v[88:91], v[148:151], v[216:219], v[88:91]
	v_mfma_f32_16x16x32_bf16 v[80:83], v[164:167], v[216:219], v[80:83]
	s_setprio 0
	s_setprio 1
	v_mfma_f32_16x16x32_bf16 v[108:111], v[168:171], v[188:191], v[108:111]
	v_mfma_f32_16x16x32_bf16 v[100:103], v[180:183], v[188:191], v[100:103]
	v_mfma_f32_16x16x32_bf16 v[92:95], v[168:171], v[196:199], v[92:95]
	v_mfma_f32_16x16x32_bf16 v[84:87], v[180:183], v[196:199], v[84:87]
	v_mfma_f32_16x16x32_bf16 v[76:79], v[168:171], v[204:207], v[76:79]
	v_mfma_f32_16x16x32_bf16 v[72:75], v[180:183], v[204:207], v[72:75]
	v_mfma_f32_16x16x32_bf16 v[68:71], v[168:171], v[212:215], v[68:71]
	v_mfma_f32_16x16x32_bf16 v[64:67], v[180:183], v[212:215], v[64:67]
	v_mfma_f32_16x16x32_bf16 v[108:111], v[172:175], v[192:195], v[108:111]
	v_mfma_f32_16x16x32_bf16 v[100:103], v[184:187], v[192:195], v[100:103]
	v_mfma_f32_16x16x32_bf16 v[92:95], v[172:175], v[200:203], v[92:95]
	v_mfma_f32_16x16x32_bf16 v[84:87], v[184:187], v[200:203], v[84:87]
	v_mfma_f32_16x16x32_bf16 v[76:79], v[172:175], v[208:211], v[76:79]
	v_mfma_f32_16x16x32_bf16 v[72:75], v[184:187], v[208:211], v[72:75]
	v_mfma_f32_16x16x32_bf16 v[68:71], v[172:175], v[216:219], v[68:71]
	v_mfma_f32_16x16x32_bf16 v[64:67], v[184:187], v[216:219], v[64:67]
	s_setprio 0
	s_barrier
; #define PG8_STAGE(bufoff, gbase, voff) do { _Pragma("unroll") for (int _i = 0; _i < 2; ++_i) \
;         __builtin_amdgcn_global_load_lds((const unsigned*)((const char*)(gbase) + (voff)[_i]), (PG8_LAS unsigned*)(lds + (bufoff) + ldsw + _i * 8192), 16, 0, 0); } while (0)
; #define PG8_LDA(dst, b, h) do { _Pragma("unroll") for (int m = 0; m < 4; ++m) _Pragma("unroll") for (int k = 0; k < 2; ++k) dst[m][k] = *(const PG8_LAS bf16x8*)(lds + PG8_SA(b, h) + aoff + m * 2048 + k * 1024); } while (0)
; #define PG8_MMA(ai, bj, At, Bt) do { __builtin_amdgcn_s_setprio(1); _Pragma("unroll") for (int m = 0; m < 4; ++m) _Pragma("unroll") for (int n = 0; n < 2; ++n) _Pragma("unroll") for (int k = 0; k < 2; ++k) \
;         acc[ai][bj][m][n] = __builtin_amdgcn_mfma_f32_16x16x32_bf16(Bt[n][k], At[m][k], acc[ai][bj][m][n], 0, 0, 0); __builtin_amdgcn_s_setprio(0); } while (0)
; #define PG8_WAIT_V(n) asm volatile("s_waitcnt vmcnt(" #n ")" ::: "memory")
; #define PG8_WAIT_L(n) asm volatile("s_waitcnt lgkmcnt(" #n ")" ::: "memory")
; #define PG8_BAR __builtin_amdgcn_s_barrier()
; #define PG8_SCHED __builtin_amdgcn_sched_barrier(0)
; template <class Epi, class Sched, bool ALIGN_EPI = false, bool SP2 = false>
; __device__ __forceinline__ void gemm_phase(PG8_LAS unsigned char* lds, const Gemm g, const Sched& S, const Epi& E) {
;     ...
;             PG8_LDA(At, 1, 1); PG8_STAGE(PG8_SB(1, 0), b3, voffB); PG8_STAGE(PG8_SB(1, 1), b3 + hstep, voffB); PG8_STAGE(PG8_SA(1, 0), a3, voffA);
;             PG8_WAIT_V(8); PG8_WAIT_L(0); PG8_BAR; PG8_MMA(1, 0, At, B0); PG8_MMA(1, 1, At, B1); PG8_BAR; PG8_SCHED;
	s_add_i32 s34, s66, s16
	v_lshl_add_u64 v[176:177], v[176:177], 0, s[22:23]
	s_mov_b32 m0, s34
	ds_read_b128 v[188:191], v161 offset:49152
	ds_read_b128 v[192:195], v161 offset:50176
	ds_read_b128 v[196:199], v161 offset:51200
	ds_read_b128 v[200:203], v161 offset:52224
	ds_read_b128 v[204:207], v161 offset:53248
	ds_read_b128 v[208:211], v161 offset:54272
	ds_read_b128 v[212:215], v161 offset:55296
	ds_read_b128 v[216:219], v161 offset:56320
	global_load_lds_dwordx4 v[176:177], off
	v_lshl_add_u64 v[176:177], v[178:179], 0, s[22:23]
	s_add_i32 m0, s34, 0x2000
	s_add_i32 s34, s67, s16
	global_load_lds_dwordx4 v[176:177], off
	v_lshl_add_u64 v[176:177], v[220:221], 0, s[22:23]
	s_mov_b32 m0, s34
	s_nop 0
	global_load_lds_dwordx4 v[176:177], off
	v_lshl_add_u64 v[176:177], v[222:223], 0, s[22:23]
	s_add_i32 m0, s34, 0x2000
	s_nop 0
	global_load_lds_dwordx4 v[176:177], off
	v_lshl_add_u64 v[176:177], v[224:225], 0, s[22:23]
	s_mov_b32 m0, s37
	s_nop 0
	global_load_lds_dwordx4 v[176:177], off
	v_lshl_add_u64 v[176:177], v[226:227], 0, s[22:23]
	s_mov_b32 m0, s38
	s_nop 0
	global_load_lds_dwordx4 v[176:177], off
	s_waitcnt vmcnt(8)
	s_waitcnt lgkmcnt(0)
	s_barrier
	s_setprio 1
	s_waitcnt lgkmcnt(0)
	v_mfma_f32_16x16x32_bf16 v[60:63], v[144:147], v[188:191], v[60:63]
	v_mfma_f32_16x16x32_bf16 v[56:59], v[152:155], v[188:191], v[56:59]
	v_mfma_f32_16x16x32_bf16 v[52:55], v[144:147], v[196:199], v[52:55]
	v_mfma_f32_16x16x32_bf16 v[48:51], v[152:155], v[196:199], v[48:51]
	v_mfma_f32_16x16x32_bf16 v[40:43], v[144:147], v[204:207], v[40:43]
	v_mfma_f32_16x16x32_bf16 v[32:35], v[152:155], v[204:207], v[32:35]
	v_mfma_f32_16x16x32_bf16 v[24:27], v[144:147], v[212:215], v[24:27]
	v_mfma_f32_16x16x32_bf16 v[16:19], v[152:155], v[212:215], v[16:19]
	v_mfma_f32_16x16x32_bf16 v[60:63], v[148:151], v[192:195], v[60:63]
	v_mfma_f32_16x16x32_bf16 v[56:59], v[164:167], v[192:195], v[56:59]
	v_mfma_f32_16x16x32_bf16 v[52:55], v[148:151], v[200:203], v[52:55]
	v_mfma_f32_16x16x32_bf16 v[48:51], v[164:167], v[200:203], v[48:51]
	v_mfma_f32_16x16x32_bf16 v[40:43], v[148:151], v[208:211], v[40:43]
	v_mfma_f32_16x16x32_bf16 v[32:35], v[164:167], v[208:211], v[32:35]
	v_mfma_f32_16x16x32_bf16 v[24:27], v[148:151], v[216:219], v[24:27]
	v_mfma_f32_16x16x32_bf16 v[16:19], v[164:167], v[216:219], v[16:19]
	s_setprio 0
	s_setprio 1
	v_mfma_f32_16x16x32_bf16 v[44:47], v[168:171], v[188:191], v[44:47]
	v_mfma_f32_16x16x32_bf16 v[36:39], v[180:183], v[188:191], v[36:39]
	v_mfma_f32_16x16x32_bf16 v[28:31], v[168:171], v[196:199], v[28:31]
	v_mfma_f32_16x16x32_bf16 v[20:23], v[180:183], v[196:199], v[20:23]
	v_mfma_f32_16x16x32_bf16 v[12:15], v[168:171], v[204:207], v[12:15]
	v_mfma_f32_16x16x32_bf16 v[8:11], v[180:183], v[204:207], v[8:11]
	v_mfma_f32_16x16x32_bf16 v[4:7], v[168:171], v[212:215], v[4:7]
	v_mfma_f32_16x16x32_bf16 v[0:3], v[180:183], v[212:215], v[0:3]
	v_mfma_f32_16x16x32_bf16 v[44:47], v[172:175], v[192:195], v[44:47]
	v_mfma_f32_16x16x32_bf16 v[36:39], v[184:187], v[192:195], v[36:39]
	v_mfma_f32_16x16x32_bf16 v[28:31], v[172:175], v[200:203], v[28:31]
	v_mfma_f32_16x16x32_bf16 v[20:23], v[184:187], v[200:203], v[20:23]
	v_mfma_f32_16x16x32_bf16 v[12:15], v[172:175], v[208:211], v[12:15]
	v_mfma_f32_16x16x32_bf16 v[8:11], v[184:187], v[208:211], v[8:11]
	v_mfma_f32_16x16x32_bf16 v[4:7], v[172:175], v[216:219], v[4:7]
	v_mfma_f32_16x16x32_bf16 v[0:3], v[184:187], v[216:219], v[0:3]
	s_setprio 0
	s_barrier
	s_add_u32 s30, s30, 0x100
	s_addc_u32 s31, s31, 0
	s_add_u32 s63, s63, 0x100
	s_addc_u32 s64, s64, 0
	s_cmp_ge_i32 s65, s40
	s_mov_b32 s34, s65
	s_cbranch_scc0 .LBB0_1411
	s_branch .Lpeel_x5

; #define PG8_STAGE(bufoff, gbase, voff) do { _Pragma("unroll") for (int _i = 0; _i < 2; ++_i) \
;         __builtin_amdgcn_global_load_lds((const unsigned*)((const char*)(gbase) + (voff)[_i]), (PG8_LAS unsigned*)(lds + (bufoff) + ldsw + _i * 8192), 16, 0, 0); } while (0)
; #define PG8_LDA(dst, b, h) do { _Pragma("unroll") for (int m = 0; m < 4; ++m) _Pragma("unroll") for (int k = 0; k < 2; ++k) dst[m][k] = *(const PG8_LAS bf16x8*)(lds + PG8_SA(b, h) + aoff + m * 2048 + k * 1024); } while (0)
; #define PG8_LDB(dst, b, h) do { _Pragma("unroll") for (int n = 0; n < 2; ++n) _Pragma("unroll") for (int k = 0; k < 2; ++k) dst[n][k] = *(const PG8_LAS bf16x8*)(lds + PG8_SB(b, h) + boff + n * 2048 + k * 1024); } while (0)
; #define PG8_MMA(ai, bj, At, Bt) do { __builtin_amdgcn_s_setprio(1); _Pragma("unroll") for (int m = 0; m < 4; ++m) _Pragma("unroll") for (int n = 0; n < 2; ++n) _Pragma("unroll") for (int k = 0; k < 2; ++k) \
;         acc[ai][bj][m][n] = __builtin_amdgcn_mfma_f32_16x16x32_bf16(Bt[n][k], At[m][k], acc[ai][bj][m][n], 0, 0, 0); __builtin_amdgcn_s_setprio(0); } while (0)
; #define PG8_WAIT_V(n) asm volatile("s_waitcnt vmcnt(" #n ")" ::: "memory")
; #define PG8_WAIT_L(n) asm volatile("s_waitcnt lgkmcnt(" #n ")" ::: "memory")
; #define PG8_BAR __builtin_amdgcn_s_barrier()
; #define PG8_SCHED __builtin_amdgcn_sched_barrier(0)
; template <class Epi, class Sched, bool ALIGN_EPI = false, bool SP2 = false>
; __device__ __forceinline__ void gemm_phase(PG8_LAS unsigned char* lds, const Gemm g, const Sched& S, const Epi& E) {
;     ...
;             const char* a1 = cA + (size_t)(t + 1) * kstep;
;             const char* a2 = last ? nA : cA + (size_t)(t + 2) * kstep; const char* b2 = last ? nB : cB + (size_t)(t + 2) * kstep;
;             const char* a3 = a2 + kstep; const char* b3 = b2 + kstep;
;             if (last && has_next) S.a_ready(nxt);
;             if constexpr (SP2) {
;             PG8_LDB(B0, 0, 0); PG8_LDB(B1, 0, 1); PG8_SCHED; PG8_LDA(At, 0, 0); PG8_STAGE(PG8_SA(1, 1), a1 + hstep, voffA);
;             PG8_WAIT_V(8); PG8_WAIT_L(0); PG8_BAR; PG8_MMA(0, 0, At, B0); PG8_MMA(0, 1, At, B1); PG8_BAR; PG8_SCHED;
;             PG8_LDA(At, 0, 1); PG8_STAGE(PG8_SB(0, 0), b2, voffB); PG8_STAGE(PG8_SB(0, 1), b2 + hstep, voffB); PG8_STAGE(PG8_SA(0, 0), a2, voffA);
.LBB0_1729:
	s_andn2_b64 vcc, exec, s[36:37]
	s_waitcnt vmcnt(0)
	s_waitcnt lgkmcnt(0)
	s_waitcnt lgkmcnt(0)
	s_cbranch_vccnz .LBB0_1732
	s_add_u32 s0, s8, 0x80
	s_addc_u32 s1, s9, 0
	s_add_u32 s8, s6, 0x100
	s_addc_u32 s9, s7, 0
	s_mov_b32 s6, 0
	ds_read_b128 v[146:149], v167
	ds_read_b128 v[150:153], v167 offset:1024
	ds_read_b128 v[154:157], v167 offset:2048
	ds_read_b128 v[158:161], v167 offset:3072
	ds_read_b128 v[172:175], v168
	ds_read_b128 v[176:179], v168 offset:1024
	ds_read_b128 v[180:183], v168 offset:2048
	ds_read_b128 v[184:187], v168 offset:3072
	s_add_i32 s10, s6, 2
	s_add_u32 s11, s0, 0x80
	s_addc_u32 s7, s1, 0
	s_cmp_eq_u32 s71, s6
	s_cselect_b32 s6, s56, s11
	s_cselect_b32 s7, s57, s7
	s_cselect_b32 s15, s59, s9
	s_cselect_b32 s14, s58, s8
	v_lshl_add_u64 v[162:163], s[0:1], 0, v[138:139]
	s_add_i32 m0, s19, 0xc000
	ds_read_b128 v[188:191], v169
	ds_read_b128 v[192:195], v169 offset:1024
	ds_read_b128 v[196:199], v169 offset:2048
	ds_read_b128 v[200:203], v169 offset:3072
	ds_read_b128 v[204:207], v169 offset:4096
	ds_read_b128 v[208:211], v169 offset:5120
	ds_read_b128 v[212:215], v169 offset:6144
	ds_read_b128 v[216:219], v169 offset:7168
	global_load_lds_dwordx4 v[162:163], off
	v_lshl_add_u64 v[162:163], s[0:1], 0, v[140:141]
	s_add_i32 m0, s19, 0xe000
	s_nop 0
	global_load_lds_dwordx4 v[162:163], off
	s_waitcnt vmcnt(8)
	s_waitcnt lgkmcnt(0)
	s_barrier
	s_setprio 1
	s_waitcnt lgkmcnt(0)
	v_mfma_f32_16x16x32_bf16 v[124:127], v[146:149], v[188:191], 0
	v_mfma_f32_16x16x32_bf16 v[120:123], v[154:157], v[188:191], 0
	v_mfma_f32_16x16x32_bf16 v[108:111], v[146:149], v[196:199], 0
	v_mfma_f32_16x16x32_bf16 v[104:107], v[154:157], v[196:199], 0
	v_mfma_f32_16x16x32_bf16 v[92:95], v[146:149], v[204:207], 0
	v_mfma_f32_16x16x32_bf16 v[88:91], v[154:157], v[204:207], 0
	v_mfma_f32_16x16x32_bf16 v[76:79], v[146:149], v[212:215], 0
	v_mfma_f32_16x16x32_bf16 v[72:75], v[154:157], v[212:215], 0
	v_mfma_f32_16x16x32_bf16 v[124:127], v[150:153], v[192:195], v[124:127]
	v_mfma_f32_16x16x32_bf16 v[120:123], v[158:161], v[192:195], v[120:123]
	v_mfma_f32_16x16x32_bf16 v[108:111], v[150:153], v[200:203], v[108:111]
	v_mfma_f32_16x16x32_bf16 v[104:107], v[158:161], v[200:203], v[104:107]
	v_mfma_f32_16x16x32_bf16 v[92:95], v[150:153], v[208:211], v[92:95]
	v_mfma_f32_16x16x32_bf16 v[88:91], v[158:161], v[208:211], v[88:91]
	v_mfma_f32_16x16x32_bf16 v[76:79], v[150:153], v[216:219], v[76:79]
	v_mfma_f32_16x16x32_bf16 v[72:75], v[158:161], v[216:219], v[72:75]
	s_setprio 0
	s_setprio 1
	v_mfma_f32_16x16x32_bf16 v[116:119], v[172:175], v[188:191], 0
	v_mfma_f32_16x16x32_bf16 v[112:115], v[180:183], v[188:191], 0
	v_mfma_f32_16x16x32_bf16 v[100:103], v[172:175], v[196:199], 0
	v_mfma_f32_16x16x32_bf16 v[96:99], v[180:183], v[196:199], 0
	v_mfma_f32_16x16x32_bf16 v[84:87], v[172:175], v[204:207], 0
	v_mfma_f32_16x16x32_bf16 v[80:83], v[180:183], v[204:207], 0
	v_mfma_f32_16x16x32_bf16 v[68:71], v[172:175], v[212:215], 0
	v_mfma_f32_16x16x32_bf16 v[64:67], v[180:183], v[212:215], 0
	v_mfma_f32_16x16x32_bf16 v[116:119], v[176:179], v[192:195], v[116:119]
	v_mfma_f32_16x16x32_bf16 v[112:115], v[184:187], v[192:195], v[112:115]
	v_mfma_f32_16x16x32_bf16 v[100:103], v[176:179], v[200:203], v[100:103]
	v_mfma_f32_16x16x32_bf16 v[96:99], v[184:187], v[200:203], v[96:99]
	v_mfma_f32_16x16x32_bf16 v[84:87], v[176:179], v[208:211], v[84:87]
	v_mfma_f32_16x16x32_bf16 v[80:83], v[184:187], v[208:211], v[80:83]
	v_mfma_f32_16x16x32_bf16 v[68:71], v[176:179], v[216:219], v[68:71]
	v_mfma_f32_16x16x32_bf16 v[64:67], v[184:187], v[216:219], v[64:67]
	s_setprio 0
	s_barrier
	s_add_i32 s11, s75, s17
	v_lshl_add_u64 v[162:163], s[14:15], 0, v[130:131]
	s_mov_b32 m0, s11
	ds_read_b128 v[188:191], v169 offset:16384
	ds_read_b128 v[192:195], v169 offset:17408
	ds_read_b128 v[196:199], v169 offset:18432
	ds_read_b128 v[200:203], v169 offset:19456
	ds_read_b128 v[204:207], v169 offset:20480
	ds_read_b128 v[208:211], v169 offset:21504
	ds_read_b128 v[212:215], v169 offset:22528
	ds_read_b128 v[216:219], v169 offset:23552
	global_load_lds_dwordx4 v[162:163], off
	s_add_i32 m0, s11, 0x2000
	v_lshl_add_u64 v[220:221], s[14:15], 0, v[134:135]
	s_add_u32 s14, s14, s24
	s_addc_u32 s15, s15, s25
	s_add_i32 s11, s76, s17
	global_load_lds_dwordx4 v[220:221], off
	v_lshl_add_u64 v[222:223], s[14:15], 0, v[130:131]
	s_mov_b32 m0, s11
	v_lshl_add_u64 v[224:225], s[14:15], 0, v[134:135]
	global_load_lds_dwordx4 v[222:223], off
	s_add_i32 m0, s11, 0x2000
	v_lshl_add_u64 v[226:227], s[6:7], 0, v[128:129]
	global_load_lds_dwordx4 v[224:225], off
	s_mov_b32 m0, s19
	v_lshl_add_u64 v[228:229], s[6:7], 0, v[132:133]
	global_load_lds_dwordx4 v[226:227], off
	s_mov_b32 m0, s33
	s_nop 0
	global_load_lds_dwordx4 v[228:229], off
	s_waitcnt vmcnt(8)
	s_waitcnt lgkmcnt(0)
	s_barrier
; #define PG8_STAGE(bufoff, gbase, voff) do { _Pragma("unroll") for (int _i = 0; _i < 2; ++_i) \
;         __builtin_amdgcn_global_load_lds((const unsigned*)((const char*)(gbase) + (voff)[_i]), (PG8_LAS unsigned*)(lds + (bufoff) + ldsw + _i * 8192), 16, 0, 0); } while (0)
; #define PG8_LDA(dst, b, h) do { _Pragma("unroll") for (int m = 0; m < 4; ++m) _Pragma("unroll") for (int k = 0; k < 2; ++k) dst[m][k] = *(const PG8_LAS bf16x8*)(lds + PG8_SA(b, h) + aoff + m * 2048 + k * 1024); } while (0)
; #define PG8_LDB(dst, b, h) do { _Pragma("unroll") for (int n = 0; n < 2; ++n) _Pragma("unroll") for (int k = 0; k < 2; ++k) dst[n][k] = *(const PG8_LAS bf16x8*)(lds + PG8_SB(b, h) + boff + n * 2048 + k * 1024); } while (0)
; #define PG8_MMA(ai, bj, At, Bt) do { __builtin_amdgcn_s_setprio(1); _Pragma("unroll") for (int m = 0; m < 4; ++m) _Pragma("unroll") for (int n = 0; n < 2; ++n) _Pragma("unroll") for (int k = 0; k < 2; ++k) \
;         acc[ai][bj][m][n] = __builtin_amdgcn_mfma_f32_16x16x32_bf16(Bt[n][k], At[m][k], acc[ai][bj][m][n], 0, 0, 0); __builtin_amdgcn_s_setprio(0); } while (0)
; #define PG8_WAIT_V(n) asm volatile("s_waitcnt vmcnt(" #n ")" ::: "memory")
; #define PG8_WAIT_L(n) asm volatile("s_waitcnt lgkmcnt(" #n ")" ::: "memory")
; #define PG8_BAR __builtin_amdgcn_s_barrier()
; #define PG8_SCHED __builtin_amdgcn_sched_barrier(0)
; template <class Epi, class Sched, bool ALIGN_EPI = false, bool SP2 = false>
; __device__ __forceinline__ void gemm_phase(PG8_LAS unsigned char* lds, const Gemm g, const Sched& S, const Epi& E) {
;     ...
;             PG8_WAIT_V(8); PG8_WAIT_L(0); PG8_BAR; PG8_MMA(1, 0, At, B0); PG8_MMA(1, 1, At, B1); PG8_BAR; PG8_SCHED;
;             PG8_LDB(B0, 1, 0); PG8_LDB(B1, 1, 1); PG8_SCHED; PG8_LDA(At, 1, 0); PG8_STAGE(PG8_SA(0, 1), a2 + hstep, voffA);
;             PG8_WAIT_V(8); PG8_WAIT_L(0); PG8_BAR; PG8_MMA(0, 0, At, B0); PG8_MMA(0, 1, At, B1); PG8_BAR; PG8_SCHED;
	s_setprio 1
	s_waitcnt lgkmcnt(0)
	v_mfma_f32_16x16x32_bf16 v[60:63], v[146:149], v[188:191], 0
	v_mfma_f32_16x16x32_bf16 v[56:59], v[154:157], v[188:191], 0
	v_mfma_f32_16x16x32_bf16 v[44:47], v[146:149], v[196:199], 0
	v_mfma_f32_16x16x32_bf16 v[40:43], v[154:157], v[196:199], 0
	v_mfma_f32_16x16x32_bf16 v[28:31], v[146:149], v[204:207], 0
	v_mfma_f32_16x16x32_bf16 v[24:27], v[154:157], v[204:207], 0
	v_mfma_f32_16x16x32_bf16 v[12:15], v[146:149], v[212:215], 0
	v_mfma_f32_16x16x32_bf16 v[8:11], v[154:157], v[212:215], 0
	v_mfma_f32_16x16x32_bf16 v[60:63], v[150:153], v[192:195], v[60:63]
	v_mfma_f32_16x16x32_bf16 v[56:59], v[158:161], v[192:195], v[56:59]
	v_mfma_f32_16x16x32_bf16 v[44:47], v[150:153], v[200:203], v[44:47]
	v_mfma_f32_16x16x32_bf16 v[40:43], v[158:161], v[200:203], v[40:43]
	v_mfma_f32_16x16x32_bf16 v[28:31], v[150:153], v[208:211], v[28:31]
	v_mfma_f32_16x16x32_bf16 v[24:27], v[158:161], v[208:211], v[24:27]
	v_mfma_f32_16x16x32_bf16 v[12:15], v[150:153], v[216:219], v[12:15]
	v_mfma_f32_16x16x32_bf16 v[8:11], v[158:161], v[216:219], v[8:11]
	s_setprio 0
	s_setprio 1
	v_mfma_f32_16x16x32_bf16 v[52:55], v[172:175], v[188:191], 0
	v_mfma_f32_16x16x32_bf16 v[48:51], v[180:183], v[188:191], 0
	v_mfma_f32_16x16x32_bf16 v[36:39], v[172:175], v[196:199], 0
	v_mfma_f32_16x16x32_bf16 v[32:35], v[180:183], v[196:199], 0
	v_mfma_f32_16x16x32_bf16 v[20:23], v[172:175], v[204:207], 0
	v_mfma_f32_16x16x32_bf16 v[16:19], v[180:183], v[204:207], 0
	v_mfma_f32_16x16x32_bf16 v[4:7], v[172:175], v[212:215], 0
	v_mfma_f32_16x16x32_bf16 v[0:3], v[180:183], v[212:215], 0
	v_mfma_f32_16x16x32_bf16 v[52:55], v[176:179], v[192:195], v[52:55]
	v_mfma_f32_16x16x32_bf16 v[48:51], v[184:187], v[192:195], v[48:51]
	v_mfma_f32_16x16x32_bf16 v[36:39], v[176:179], v[200:203], v[36:39]
	v_mfma_f32_16x16x32_bf16 v[32:35], v[184:187], v[200:203], v[32:35]
	v_mfma_f32_16x16x32_bf16 v[20:23], v[176:179], v[208:211], v[20:23]
	v_mfma_f32_16x16x32_bf16 v[16:19], v[184:187], v[208:211], v[16:19]
	v_mfma_f32_16x16x32_bf16 v[4:7], v[176:179], v[216:219], v[4:7]
	v_mfma_f32_16x16x32_bf16 v[0:3], v[184:187], v[216:219], v[0:3]
	s_setprio 0
	s_barrier
	s_add_i32 s11, 0, 0x18000
	v_add_u32_e32 v136, s11, v165
	s_add_i32 s13, 0, 0x1c000
	ds_read_b128 v[146:149], v136
	ds_read_b128 v[150:153], v136 offset:1024
	ds_read_b128 v[154:157], v136 offset:2048
	ds_read_b128 v[158:161], v136 offset:3072
	v_add_u32_e32 v136, s13, v165
	ds_read_b128 v[172:175], v136
	ds_read_b128 v[176:179], v136 offset:1024
	ds_read_b128 v[180:183], v136 offset:2048
	ds_read_b128 v[184:187], v136 offset:3072
	s_add_u32 s6, s6, s24
	s_addc_u32 s7, s7, s25
	s_mov_b32 m0, s66
	v_lshl_add_u64 v[230:231], s[6:7], 0, v[128:129]
	ds_read_b128 v[188:191], v169 offset:32768
	ds_read_b128 v[192:195], v169 offset:33792
	ds_read_b128 v[196:199], v169 offset:34816
	ds_read_b128 v[200:203], v169 offset:35840
	ds_read_b128 v[204:207], v169 offset:36864
	ds_read_b128 v[208:211], v169 offset:37888
	ds_read_b128 v[212:215], v169 offset:38912
	ds_read_b128 v[216:219], v169 offset:39936
	global_load_lds_dwordx4 v[230:231], off
	v_lshl_add_u64 v[230:231], s[6:7], 0, v[132:133]
	s_mov_b32 m0, s67
	s_nop 0
	global_load_lds_dwordx4 v[230:231], off
	s_waitcnt vmcnt(8)
	s_waitcnt lgkmcnt(0)
	s_barrier
	s_setprio 1
	s_waitcnt lgkmcnt(0)
	v_mfma_f32_16x16x32_bf16 v[124:127], v[146:149], v[188:191], v[124:127]
	v_mfma_f32_16x16x32_bf16 v[120:123], v[154:157], v[188:191], v[120:123]
	v_mfma_f32_16x16x32_bf16 v[108:111], v[146:149], v[196:199], v[108:111]
	v_mfma_f32_16x16x32_bf16 v[104:107], v[154:157], v[196:199], v[104:107]
	v_mfma_f32_16x16x32_bf16 v[92:95], v[146:149], v[204:207], v[92:95]
	v_mfma_f32_16x16x32_bf16 v[88:91], v[154:157], v[204:207], v[88:91]
	v_mfma_f32_16x16x32_bf16 v[76:79], v[146:149], v[212:215], v[76:79]
	v_mfma_f32_16x16x32_bf16 v[72:75], v[154:157], v[212:215], v[72:75]
	v_mfma_f32_16x16x32_bf16 v[124:127], v[150:153], v[192:195], v[124:127]
	v_mfma_f32_16x16x32_bf16 v[120:123], v[158:161], v[192:195], v[120:123]
	v_mfma_f32_16x16x32_bf16 v[108:111], v[150:153], v[200:203], v[108:111]
	v_mfma_f32_16x16x32_bf16 v[104:107], v[158:161], v[200:203], v[104:107]
	v_mfma_f32_16x16x32_bf16 v[92:95], v[150:153], v[208:211], v[92:95]
	v_mfma_f32_16x16x32_bf16 v[88:91], v[158:161], v[208:211], v[88:91]
	v_mfma_f32_16x16x32_bf16 v[76:79], v[150:153], v[216:219], v[76:79]
	v_mfma_f32_16x16x32_bf16 v[72:75], v[158:161], v[216:219], v[72:75]
	s_setprio 0
	s_setprio 1
	v_mfma_f32_16x16x32_bf16 v[116:119], v[172:175], v[188:191], v[116:119]
	v_mfma_f32_16x16x32_bf16 v[112:115], v[180:183], v[188:191], v[112:115]
	v_mfma_f32_16x16x32_bf16 v[100:103], v[172:175], v[196:199], v[100:103]
	v_mfma_f32_16x16x32_bf16 v[96:99], v[180:183], v[196:199], v[96:99]
	v_mfma_f32_16x16x32_bf16 v[84:87], v[172:175], v[204:207], v[84:87]
	v_mfma_f32_16x16x32_bf16 v[80:83], v[180:183], v[204:207], v[80:83]
	v_mfma_f32_16x16x32_bf16 v[68:71], v[172:175], v[212:215], v[68:71]
	v_mfma_f32_16x16x32_bf16 v[64:67], v[180:183], v[212:215], v[64:67]
	v_mfma_f32_16x16x32_bf16 v[116:119], v[176:179], v[192:195], v[116:119]
	v_mfma_f32_16x16x32_bf16 v[112:115], v[184:187], v[192:195], v[112:115]
	v_mfma_f32_16x16x32_bf16 v[100:103], v[176:179], v[200:203], v[100:103]
	v_mfma_f32_16x16x32_bf16 v[96:99], v[184:187], v[200:203], v[96:99]
	v_mfma_f32_16x16x32_bf16 v[84:87], v[176:179], v[208:211], v[84:87]
	v_mfma_f32_16x16x32_bf16 v[80:83], v[184:187], v[208:211], v[80:83]
	v_mfma_f32_16x16x32_bf16 v[68:71], v[176:179], v[216:219], v[68:71]
	v_mfma_f32_16x16x32_bf16 v[64:67], v[184:187], v[216:219], v[64:67]
	s_setprio 0
	s_barrier
; #define PG8_STAGE(bufoff, gbase, voff) do { _Pragma("unroll") for (int _i = 0; _i < 2; ++_i) \
;         __builtin_amdgcn_global_load_lds((const unsigned*)((const char*)(gbase) + (voff)[_i]), (PG8_LAS unsigned*)(lds + (bufoff) + ldsw + _i * 8192), 16, 0, 0); } while (0)
; #define PG8_LDA(dst, b, h) do { _Pragma("unroll") for (int m = 0; m < 4; ++m) _Pragma("unroll") for (int k = 0; k < 2; ++k) dst[m][k] = *(const PG8_LAS bf16x8*)(lds + PG8_SA(b, h) + aoff + m * 2048 + k * 1024); } while (0)
; #define PG8_MMA(ai, bj, At, Bt) do { __builtin_amdgcn_s_setprio(1); _Pragma("unroll") for (int m = 0; m < 4; ++m) _Pragma("unroll") for (int n = 0; n < 2; ++n) _Pragma("unroll") for (int k = 0; k < 2; ++k) \
;         acc[ai][bj][m][n] = __builtin_amdgcn_mfma_f32_16x16x32_bf16(Bt[n][k], At[m][k], acc[ai][bj][m][n], 0, 0, 0); __builtin_amdgcn_s_setprio(0); } while (0)
; #define PG8_WAIT_V(n) asm volatile("s_waitcnt vmcnt(" #n ")" ::: "memory")
; #define PG8_WAIT_L(n) asm volatile("s_waitcnt lgkmcnt(" #n ")" ::: "memory")
; #define PG8_BAR __builtin_amdgcn_s_barrier()
; #define PG8_SCHED __builtin_amdgcn_sched_barrier(0)
; template <class Epi, class Sched, bool ALIGN_EPI = false, bool SP2 = false>
; __device__ __forceinline__ void gemm_phase(PG8_LAS unsigned char* lds, const Gemm g, const Sched& S, const Epi& E) {
;     ...
;             PG8_LDA(At, 1, 1); PG8_STAGE(PG8_SB(1, 0), b3, voffB); PG8_STAGE(PG8_SB(1, 1), b3 + hstep, voffB); PG8_STAGE(PG8_SA(1, 0), a3, voffA);
;             PG8_WAIT_V(8); PG8_WAIT_L(0); PG8_BAR; PG8_MMA(1, 0, At, B0); PG8_MMA(1, 1, At, B1); PG8_BAR; PG8_SCHED;
	s_add_i32 s6, s11, s17
	v_lshl_add_u64 v[162:163], v[162:163], 0, s[34:35]
	s_mov_b32 m0, s6
	ds_read_b128 v[188:191], v169 offset:49152
	ds_read_b128 v[192:195], v169 offset:50176
	ds_read_b128 v[196:199], v169 offset:51200
	ds_read_b128 v[200:203], v169 offset:52224
	ds_read_b128 v[204:207], v169 offset:53248
	ds_read_b128 v[208:211], v169 offset:54272
	ds_read_b128 v[212:215], v169 offset:55296
	ds_read_b128 v[216:219], v169 offset:56320
	global_load_lds_dwordx4 v[162:163], off
	v_lshl_add_u64 v[162:163], v[220:221], 0, s[34:35]
	s_add_i32 m0, s6, 0x2000
	s_add_i32 s6, s13, s17
	global_load_lds_dwordx4 v[162:163], off
	v_lshl_add_u64 v[162:163], v[222:223], 0, s[34:35]
	s_mov_b32 m0, s6
	s_nop 0
	global_load_lds_dwordx4 v[162:163], off
	v_lshl_add_u64 v[162:163], v[224:225], 0, s[34:35]
	s_add_i32 m0, s6, 0x2000
	s_nop 0
	global_load_lds_dwordx4 v[162:163], off
	v_lshl_add_u64 v[162:163], v[226:227], 0, s[34:35]
	s_mov_b32 m0, s68
	s_nop 0
	global_load_lds_dwordx4 v[162:163], off
	v_lshl_add_u64 v[162:163], v[228:229], 0, s[34:35]
	s_mov_b32 m0, s69
	s_nop 0
	global_load_lds_dwordx4 v[162:163], off
	s_waitcnt vmcnt(8)
	s_waitcnt lgkmcnt(0)
	s_barrier
	s_setprio 1
	s_waitcnt lgkmcnt(0)
	v_mfma_f32_16x16x32_bf16 v[60:63], v[146:149], v[188:191], v[60:63]
	v_mfma_f32_16x16x32_bf16 v[56:59], v[154:157], v[188:191], v[56:59]
	v_mfma_f32_16x16x32_bf16 v[44:47], v[146:149], v[196:199], v[44:47]
	v_mfma_f32_16x16x32_bf16 v[40:43], v[154:157], v[196:199], v[40:43]
	v_mfma_f32_16x16x32_bf16 v[28:31], v[146:149], v[204:207], v[28:31]
	v_mfma_f32_16x16x32_bf16 v[24:27], v[154:157], v[204:207], v[24:27]
	v_mfma_f32_16x16x32_bf16 v[12:15], v[146:149], v[212:215], v[12:15]
	v_mfma_f32_16x16x32_bf16 v[8:11], v[154:157], v[212:215], v[8:11]
	v_mfma_f32_16x16x32_bf16 v[60:63], v[150:153], v[192:195], v[60:63]
	v_mfma_f32_16x16x32_bf16 v[56:59], v[158:161], v[192:195], v[56:59]
	v_mfma_f32_16x16x32_bf16 v[44:47], v[150:153], v[200:203], v[44:47]
	v_mfma_f32_16x16x32_bf16 v[40:43], v[158:161], v[200:203], v[40:43]
	v_mfma_f32_16x16x32_bf16 v[28:31], v[150:153], v[208:211], v[28:31]
	v_mfma_f32_16x16x32_bf16 v[24:27], v[158:161], v[208:211], v[24:27]
	v_mfma_f32_16x16x32_bf16 v[12:15], v[150:153], v[216:219], v[12:15]
	v_mfma_f32_16x16x32_bf16 v[8:11], v[158:161], v[216:219], v[8:11]
	s_setprio 0
	s_setprio 1
	v_mfma_f32_16x16x32_bf16 v[52:55], v[172:175], v[188:191], v[52:55]
	v_mfma_f32_16x16x32_bf16 v[48:51], v[180:183], v[188:191], v[48:51]
	v_mfma_f32_16x16x32_bf16 v[36:39], v[172:175], v[196:199], v[36:39]
	v_mfma_f32_16x16x32_bf16 v[32:35], v[180:183], v[196:199], v[32:35]
	v_mfma_f32_16x16x32_bf16 v[20:23], v[172:175], v[204:207], v[20:23]
	v_mfma_f32_16x16x32_bf16 v[16:19], v[180:183], v[204:207], v[16:19]
	v_mfma_f32_16x16x32_bf16 v[4:7], v[172:175], v[212:215], v[4:7]
	v_mfma_f32_16x16x32_bf16 v[0:3], v[180:183], v[212:215], v[0:3]
	v_mfma_f32_16x16x32_bf16 v[52:55], v[176:179], v[192:195], v[52:55]
	v_mfma_f32_16x16x32_bf16 v[48:51], v[184:187], v[192:195], v[48:51]
	v_mfma_f32_16x16x32_bf16 v[36:39], v[176:179], v[200:203], v[36:39]
	v_mfma_f32_16x16x32_bf16 v[32:35], v[184:187], v[200:203], v[32:35]
	v_mfma_f32_16x16x32_bf16 v[20:23], v[176:179], v[208:211], v[20:23]
	v_mfma_f32_16x16x32_bf16 v[16:19], v[184:187], v[208:211], v[16:19]
	v_mfma_f32_16x16x32_bf16 v[4:7], v[176:179], v[216:219], v[4:7]
	v_mfma_f32_16x16x32_bf16 v[0:3], v[184:187], v[216:219], v[0:3]
	s_setprio 0
	s_barrier
	s_add_u32 s0, s0, 0x100
	s_addc_u32 s1, s1, 0
	s_add_u32 s8, s8, 0x100
	s_addc_u32 s9, s9, 0
	s_cmp_ge_i32 s10, s70
	s_mov_b32 s6, s10
	s_cbranch_scc0 .LBB0_1731
	s_branch .Lpeel_x8

; #define PG8_BAR __builtin_amdgcn_s_barrier()
; template <class Epi, class Sched, bool ALIGN_EPI = false, bool SP2 = false>
; __device__ __forceinline__ void gemm_phase(PG8_LAS unsigned char* lds, const Gemm g, const Sched& S, const Epi& E) {
;     ...
;         if constexpr (ALIGN_EPI) { if (wr == 0) PG8_BAR; }
.Lpeel_x8:
.LBB0_1732:
	s_and_b64 vcc, exec, s[38:39]
	s_cbranch_vccz .LBB0_1734
	s_barrier

; #define PG8_STAGE(bufoff, gbase, voff) do { _Pragma("unroll") for (int _i = 0; _i < 2; ++_i) \
;         __builtin_amdgcn_global_load_lds((const unsigned*)((const char*)(gbase) + (voff)[_i]), (PG8_LAS unsigned*)(lds + (bufoff) + ldsw + _i * 8192), 16, 0, 0); } while (0)
; #define PG8_LDA(dst, b, h) do { _Pragma("unroll") for (int m = 0; m < 4; ++m) _Pragma("unroll") for (int k = 0; k < 2; ++k) dst[m][k] = *(const PG8_LAS bf16x8*)(lds + PG8_SA(b, h) + aoff + m * 2048 + k * 1024); } while (0)
; #define PG8_LDB(dst, b, h) do { _Pragma("unroll") for (int n = 0; n < 2; ++n) _Pragma("unroll") for (int k = 0; k < 2; ++k) dst[n][k] = *(const PG8_LAS bf16x8*)(lds + PG8_SB(b, h) + boff + n * 2048 + k * 1024); } while (0)
; #define PG8_MMA(ai, bj, At, Bt) do { __builtin_amdgcn_s_setprio(1); _Pragma("unroll") for (int m = 0; m < 4; ++m) _Pragma("unroll") for (int n = 0; n < 2; ++n) _Pragma("unroll") for (int k = 0; k < 2; ++k) \
;         acc[ai][bj][m][n] = __builtin_amdgcn_mfma_f32_16x16x32_bf16(Bt[n][k], At[m][k], acc[ai][bj][m][n], 0, 0, 0); __builtin_amdgcn_s_setprio(0); } while (0)
; #define PG8_WAIT_V(n) asm volatile("s_waitcnt vmcnt(" #n ")" ::: "memory")
; #define PG8_WAIT_L(n) asm volatile("s_waitcnt lgkmcnt(" #n ")" ::: "memory")
; #define PG8_BAR __builtin_amdgcn_s_barrier()
; #define PG8_SCHED __builtin_amdgcn_sched_barrier(0)
; template <class Epi, class Sched, bool ALIGN_EPI = false, bool SP2 = false>
; __device__ __forceinline__ void gemm_phase(PG8_LAS unsigned char* lds, const Gemm g, const Sched& S, const Epi& E) {
;     ...
;             const char* a1 = cA + (size_t)(t + 1) * kstep;
;             const char* a2 = last ? nA : cA + (size_t)(t + 2) * kstep; const char* b2 = last ? nB : cB + (size_t)(t + 2) * kstep;
;             const char* a3 = a2 + kstep; const char* b3 = b2 + kstep;
;             if (last && has_next) S.a_ready(nxt);
;             if constexpr (SP2) {
;             PG8_LDB(B0, 0, 0); PG8_LDB(B1, 0, 1); PG8_SCHED; PG8_LDA(At, 0, 0); PG8_STAGE(PG8_SA(1, 1), a1 + hstep, voffA);
;             PG8_WAIT_V(8); PG8_WAIT_L(0); PG8_BAR; PG8_MMA(0, 0, At, B0); PG8_MMA(0, 1, At, B1); PG8_BAR; PG8_SCHED;
;             PG8_LDA(At, 0, 1); PG8_STAGE(PG8_SB(0, 0), b2, voffB); PG8_STAGE(PG8_SB(0, 1), b2 + hstep, voffB); PG8_STAGE(PG8_SA(0, 0), a2, voffA);
.LBB0_2050:
	s_andn2_b64 vcc, exec, s[24:25]
	s_waitcnt vmcnt(0)
	s_cbranch_vccnz .LBB0_2053
	s_add_u32 s0, s6, 0x80
	s_addc_u32 s1, s7, 0
	s_add_u32 s6, s4, 0x100
	s_addc_u32 s7, s5, 0
	s_mov_b32 s4, 0
	ds_read_b128 v[146:149], v156
	ds_read_b128 v[160:163], v156 offset:1024
	ds_read_b128 v[164:167], v156 offset:2048
	ds_read_b128 v[168:171], v156 offset:3072
	ds_read_b128 v[172:175], v157
	ds_read_b128 v[176:179], v157 offset:1024
	ds_read_b128 v[180:183], v157 offset:2048
	ds_read_b128 v[184:187], v157 offset:3072
	s_add_i32 s78, s4, 2
	s_add_u32 s79, s0, 0x80
	s_addc_u32 s5, s1, 0
	s_cmp_eq_u32 s57, s4
	s_cselect_b32 s4, s36, s79
	s_cselect_b32 s5, s37, s5
	s_cselect_b32 s81, s39, s7
	s_cselect_b32 s80, s38, s6
	v_lshl_add_u64 v[150:151], s[0:1], 0, v[138:139]
	s_add_i32 m0, s19, 0xc000
	ds_read_b128 v[188:191], v158
	ds_read_b128 v[192:195], v158 offset:1024
	ds_read_b128 v[196:199], v158 offset:2048
	ds_read_b128 v[200:203], v158 offset:3072
	ds_read_b128 v[204:207], v158 offset:4096
	ds_read_b128 v[208:211], v158 offset:5120
	ds_read_b128 v[212:215], v158 offset:6144
	ds_read_b128 v[216:219], v158 offset:7168
	global_load_lds_dwordx4 v[150:151], off
	v_lshl_add_u64 v[150:151], s[0:1], 0, v[140:141]
	s_add_i32 m0, s19, 0xe000
	s_nop 0
	global_load_lds_dwordx4 v[150:151], off
	s_waitcnt vmcnt(8)
	s_waitcnt lgkmcnt(0)
	s_barrier
	s_setprio 1
	s_waitcnt lgkmcnt(0)
	v_mfma_f32_16x16x32_bf16 v[120:123], v[146:149], v[188:191], 0
	v_mfma_f32_16x16x32_bf16 v[124:127], v[164:167], v[188:191], 0
	v_mfma_f32_16x16x32_bf16 v[108:111], v[146:149], v[196:199], 0
	v_mfma_f32_16x16x32_bf16 v[104:107], v[164:167], v[196:199], 0
	v_mfma_f32_16x16x32_bf16 v[92:95], v[146:149], v[204:207], 0
	v_mfma_f32_16x16x32_bf16 v[88:91], v[164:167], v[204:207], 0
	v_mfma_f32_16x16x32_bf16 v[76:79], v[146:149], v[212:215], 0
	v_mfma_f32_16x16x32_bf16 v[72:75], v[164:167], v[212:215], 0
	v_mfma_f32_16x16x32_bf16 v[120:123], v[160:163], v[192:195], v[120:123]
	v_mfma_f32_16x16x32_bf16 v[124:127], v[168:171], v[192:195], v[124:127]
	v_mfma_f32_16x16x32_bf16 v[108:111], v[160:163], v[200:203], v[108:111]
	v_mfma_f32_16x16x32_bf16 v[104:107], v[168:171], v[200:203], v[104:107]
	v_mfma_f32_16x16x32_bf16 v[92:95], v[160:163], v[208:211], v[92:95]
	v_mfma_f32_16x16x32_bf16 v[88:91], v[168:171], v[208:211], v[88:91]
	v_mfma_f32_16x16x32_bf16 v[76:79], v[160:163], v[216:219], v[76:79]
	v_mfma_f32_16x16x32_bf16 v[72:75], v[168:171], v[216:219], v[72:75]
	s_setprio 0
	s_setprio 1
	v_mfma_f32_16x16x32_bf16 v[116:119], v[172:175], v[188:191], 0
	v_mfma_f32_16x16x32_bf16 v[112:115], v[180:183], v[188:191], 0
	v_mfma_f32_16x16x32_bf16 v[100:103], v[172:175], v[196:199], 0
	v_mfma_f32_16x16x32_bf16 v[96:99], v[180:183], v[196:199], 0
	v_mfma_f32_16x16x32_bf16 v[84:87], v[172:175], v[204:207], 0
	v_mfma_f32_16x16x32_bf16 v[80:83], v[180:183], v[204:207], 0
	v_mfma_f32_16x16x32_bf16 v[68:71], v[172:175], v[212:215], 0
	v_mfma_f32_16x16x32_bf16 v[64:67], v[180:183], v[212:215], 0
	v_mfma_f32_16x16x32_bf16 v[116:119], v[176:179], v[192:195], v[116:119]
	v_mfma_f32_16x16x32_bf16 v[112:115], v[184:187], v[192:195], v[112:115]
	v_mfma_f32_16x16x32_bf16 v[100:103], v[176:179], v[200:203], v[100:103]
	v_mfma_f32_16x16x32_bf16 v[96:99], v[184:187], v[200:203], v[96:99]
	v_mfma_f32_16x16x32_bf16 v[84:87], v[176:179], v[208:211], v[84:87]
	v_mfma_f32_16x16x32_bf16 v[80:83], v[184:187], v[208:211], v[80:83]
	v_mfma_f32_16x16x32_bf16 v[68:71], v[176:179], v[216:219], v[68:71]
	v_mfma_f32_16x16x32_bf16 v[64:67], v[184:187], v[216:219], v[64:67]
	s_setprio 0
	s_barrier
	s_add_i32 s79, s63, s17
	v_lshl_add_u64 v[150:151], s[80:81], 0, v[130:131]
	s_mov_b32 m0, s79
	ds_read_b128 v[188:191], v158 offset:16384
	ds_read_b128 v[192:195], v158 offset:17408
	ds_read_b128 v[196:199], v158 offset:18432
	ds_read_b128 v[200:203], v158 offset:19456
	ds_read_b128 v[204:207], v158 offset:20480
	ds_read_b128 v[208:211], v158 offset:21504
	ds_read_b128 v[212:215], v158 offset:22528
	ds_read_b128 v[216:219], v158 offset:23552
	global_load_lds_dwordx4 v[150:151], off
	s_add_i32 m0, s79, 0x2000
	v_lshl_add_u64 v[220:221], s[80:81], 0, v[134:135]
	s_add_u32 s80, s80, s12
	s_addc_u32 s81, s81, s13
	s_add_i32 s79, s64, s17
	global_load_lds_dwordx4 v[220:221], off
	v_lshl_add_u64 v[222:223], s[80:81], 0, v[130:131]
	s_mov_b32 m0, s79
	v_lshl_add_u64 v[224:225], s[80:81], 0, v[134:135]
	global_load_lds_dwordx4 v[222:223], off
	s_add_i32 m0, s79, 0x2000
	v_lshl_add_u64 v[226:227], s[4:5], 0, v[128:129]
	global_load_lds_dwordx4 v[224:225], off
	s_mov_b32 m0, s19
	v_lshl_add_u64 v[228:229], s[4:5], 0, v[132:133]
	global_load_lds_dwordx4 v[226:227], off
	s_mov_b32 m0, s33
	s_nop 0
	global_load_lds_dwordx4 v[228:229], off
	s_waitcnt vmcnt(8)
	s_waitcnt lgkmcnt(0)
	s_barrier
; #define PG8_STAGE(bufoff, gbase, voff) do { _Pragma("unroll") for (int _i = 0; _i < 2; ++_i) \
;         __builtin_amdgcn_global_load_lds((const unsigned*)((const char*)(gbase) + (voff)[_i]), (PG8_LAS unsigned*)(lds + (bufoff) + ldsw + _i * 8192), 16, 0, 0); } while (0)
; #define PG8_LDA(dst, b, h) do { _Pragma("unroll") for (int m = 0; m < 4; ++m) _Pragma("unroll") for (int k = 0; k < 2; ++k) dst[m][k] = *(const PG8_LAS bf16x8*)(lds + PG8_SA(b, h) + aoff + m * 2048 + k * 1024); } while (0)
; #define PG8_LDB(dst, b, h) do { _Pragma("unroll") for (int n = 0; n < 2; ++n) _Pragma("unroll") for (int k = 0; k < 2; ++k) dst[n][k] = *(const PG8_LAS bf16x8*)(lds + PG8_SB(b, h) + boff + n * 2048 + k * 1024); } while (0)
; #define PG8_MMA(ai, bj, At, Bt) do { __builtin_amdgcn_s_setprio(1); _Pragma("unroll") for (int m = 0; m < 4; ++m) _Pragma("unroll") for (int n = 0; n < 2; ++n) _Pragma("unroll") for (int k = 0; k < 2; ++k) \
;         acc[ai][bj][m][n] = __builtin_amdgcn_mfma_f32_16x16x32_bf16(Bt[n][k], At[m][k], acc[ai][bj][m][n], 0, 0, 0); __builtin_amdgcn_s_setprio(0); } while (0)
; #define PG8_WAIT_V(n) asm volatile("s_waitcnt vmcnt(" #n ")" ::: "memory")
; #define PG8_WAIT_L(n) asm volatile("s_waitcnt lgkmcnt(" #n ")" ::: "memory")
; #define PG8_BAR __builtin_amdgcn_s_barrier()
; #define PG8_SCHED __builtin_amdgcn_sched_barrier(0)
; template <class Epi, class Sched, bool ALIGN_EPI = false, bool SP2 = false>
; __device__ __forceinline__ void gemm_phase(PG8_LAS unsigned char* lds, const Gemm g, const Sched& S, const Epi& E) {
;     ...
;             PG8_WAIT_V(8); PG8_WAIT_L(0); PG8_BAR; PG8_MMA(1, 0, At, B0); PG8_MMA(1, 1, At, B1); PG8_BAR; PG8_SCHED;
;             PG8_LDB(B0, 1, 0); PG8_LDB(B1, 1, 1); PG8_SCHED; PG8_LDA(At, 1, 0); PG8_STAGE(PG8_SA(0, 1), a2 + hstep, voffA);
;             PG8_WAIT_V(8); PG8_WAIT_L(0); PG8_BAR; PG8_MMA(0, 0, At, B0); PG8_MMA(0, 1, At, B1); PG8_BAR; PG8_SCHED;
	s_setprio 1
	s_waitcnt lgkmcnt(0)
	v_mfma_f32_16x16x32_bf16 v[60:63], v[146:149], v[188:191], 0
	v_mfma_f32_16x16x32_bf16 v[56:59], v[164:167], v[188:191], 0
	v_mfma_f32_16x16x32_bf16 v[44:47], v[146:149], v[196:199], 0
	v_mfma_f32_16x16x32_bf16 v[40:43], v[164:167], v[196:199], 0
	v_mfma_f32_16x16x32_bf16 v[28:31], v[146:149], v[204:207], 0
	v_mfma_f32_16x16x32_bf16 v[24:27], v[164:167], v[204:207], 0
	v_mfma_f32_16x16x32_bf16 v[12:15], v[146:149], v[212:215], 0
	v_mfma_f32_16x16x32_bf16 v[8:11], v[164:167], v[212:215], 0
	v_mfma_f32_16x16x32_bf16 v[60:63], v[160:163], v[192:195], v[60:63]
	v_mfma_f32_16x16x32_bf16 v[56:59], v[168:171], v[192:195], v[56:59]
	v_mfma_f32_16x16x32_bf16 v[44:47], v[160:163], v[200:203], v[44:47]
	v_mfma_f32_16x16x32_bf16 v[40:43], v[168:171], v[200:203], v[40:43]
	v_mfma_f32_16x16x32_bf16 v[28:31], v[160:163], v[208:211], v[28:31]
	v_mfma_f32_16x16x32_bf16 v[24:27], v[168:171], v[208:211], v[24:27]
	v_mfma_f32_16x16x32_bf16 v[12:15], v[160:163], v[216:219], v[12:15]
	v_mfma_f32_16x16x32_bf16 v[8:11], v[168:171], v[216:219], v[8:11]
	s_setprio 0
	s_setprio 1
	v_mfma_f32_16x16x32_bf16 v[52:55], v[172:175], v[188:191], 0
	v_mfma_f32_16x16x32_bf16 v[48:51], v[180:183], v[188:191], 0
	v_mfma_f32_16x16x32_bf16 v[36:39], v[172:175], v[196:199], 0
	v_mfma_f32_16x16x32_bf16 v[32:35], v[180:183], v[196:199], 0
	v_mfma_f32_16x16x32_bf16 v[20:23], v[172:175], v[204:207], 0
	v_mfma_f32_16x16x32_bf16 v[16:19], v[180:183], v[204:207], 0
	v_mfma_f32_16x16x32_bf16 v[4:7], v[172:175], v[212:215], 0
	v_mfma_f32_16x16x32_bf16 v[0:3], v[180:183], v[212:215], 0
	v_mfma_f32_16x16x32_bf16 v[52:55], v[176:179], v[192:195], v[52:55]
	v_mfma_f32_16x16x32_bf16 v[48:51], v[184:187], v[192:195], v[48:51]
	v_mfma_f32_16x16x32_bf16 v[36:39], v[176:179], v[200:203], v[36:39]
	v_mfma_f32_16x16x32_bf16 v[32:35], v[184:187], v[200:203], v[32:35]
	v_mfma_f32_16x16x32_bf16 v[20:23], v[176:179], v[208:211], v[20:23]
	v_mfma_f32_16x16x32_bf16 v[16:19], v[184:187], v[208:211], v[16:19]
	v_mfma_f32_16x16x32_bf16 v[4:7], v[176:179], v[216:219], v[4:7]
	v_mfma_f32_16x16x32_bf16 v[0:3], v[184:187], v[216:219], v[0:3]
	s_setprio 0
	s_barrier
	s_add_i32 s79, 0, 0x18000
	v_add_u32_e32 v137, s79, v153
	s_add_i32 s80, 0, 0x1c000
	ds_read_b128 v[146:149], v137
	ds_read_b128 v[160:163], v137 offset:1024
	ds_read_b128 v[164:167], v137 offset:2048
	ds_read_b128 v[168:171], v137 offset:3072
	v_add_u32_e32 v137, s80, v153
	ds_read_b128 v[172:175], v137
	ds_read_b128 v[176:179], v137 offset:1024
	ds_read_b128 v[180:183], v137 offset:2048
	ds_read_b128 v[184:187], v137 offset:3072
	s_add_u32 s4, s4, s12
	s_addc_u32 s5, s5, s13
	s_mov_b32 m0, s40
	v_lshl_add_u64 v[230:231], s[4:5], 0, v[128:129]
	ds_read_b128 v[188:191], v158 offset:32768
	ds_read_b128 v[192:195], v158 offset:33792
	ds_read_b128 v[196:199], v158 offset:34816
	ds_read_b128 v[200:203], v158 offset:35840
	ds_read_b128 v[204:207], v158 offset:36864
	ds_read_b128 v[208:211], v158 offset:37888
	ds_read_b128 v[212:215], v158 offset:38912
	ds_read_b128 v[216:219], v158 offset:39936
	global_load_lds_dwordx4 v[230:231], off
	v_lshl_add_u64 v[230:231], s[4:5], 0, v[132:133]
	s_mov_b32 m0, s41
	s_nop 0
	global_load_lds_dwordx4 v[230:231], off
	s_waitcnt vmcnt(8)
	s_waitcnt lgkmcnt(0)
	s_barrier
	s_setprio 1
	s_waitcnt lgkmcnt(0)
	v_mfma_f32_16x16x32_bf16 v[120:123], v[146:149], v[188:191], v[120:123]
	v_mfma_f32_16x16x32_bf16 v[124:127], v[164:167], v[188:191], v[124:127]
	v_mfma_f32_16x16x32_bf16 v[108:111], v[146:149], v[196:199], v[108:111]
	v_mfma_f32_16x16x32_bf16 v[104:107], v[164:167], v[196:199], v[104:107]
	v_mfma_f32_16x16x32_bf16 v[92:95], v[146:149], v[204:207], v[92:95]
	v_mfma_f32_16x16x32_bf16 v[88:91], v[164:167], v[204:207], v[88:91]
	v_mfma_f32_16x16x32_bf16 v[76:79], v[146:149], v[212:215], v[76:79]
	v_mfma_f32_16x16x32_bf16 v[72:75], v[164:167], v[212:215], v[72:75]
	v_mfma_f32_16x16x32_bf16 v[120:123], v[160:163], v[192:195], v[120:123]
	v_mfma_f32_16x16x32_bf16 v[124:127], v[168:171], v[192:195], v[124:127]
	v_mfma_f32_16x16x32_bf16 v[108:111], v[160:163], v[200:203], v[108:111]
	v_mfma_f32_16x16x32_bf16 v[104:107], v[168:171], v[200:203], v[104:107]
	v_mfma_f32_16x16x32_bf16 v[92:95], v[160:163], v[208:211], v[92:95]
	v_mfma_f32_16x16x32_bf16 v[88:91], v[168:171], v[208:211], v[88:91]
	v_mfma_f32_16x16x32_bf16 v[76:79], v[160:163], v[216:219], v[76:79]
	v_mfma_f32_16x16x32_bf16 v[72:75], v[168:171], v[216:219], v[72:75]
	s_setprio 0
	s_setprio 1
	v_mfma_f32_16x16x32_bf16 v[116:119], v[172:175], v[188:191], v[116:119]
	v_mfma_f32_16x16x32_bf16 v[112:115], v[180:183], v[188:191], v[112:115]
	v_mfma_f32_16x16x32_bf16 v[100:103], v[172:175], v[196:199], v[100:103]
	v_mfma_f32_16x16x32_bf16 v[96:99], v[180:183], v[196:199], v[96:99]
	v_mfma_f32_16x16x32_bf16 v[84:87], v[172:175], v[204:207], v[84:87]
	v_mfma_f32_16x16x32_bf16 v[80:83], v[180:183], v[204:207], v[80:83]
	v_mfma_f32_16x16x32_bf16 v[68:71], v[172:175], v[212:215], v[68:71]
	v_mfma_f32_16x16x32_bf16 v[64:67], v[180:183], v[212:215], v[64:67]
	v_mfma_f32_16x16x32_bf16 v[116:119], v[176:179], v[192:195], v[116:119]
	v_mfma_f32_16x16x32_bf16 v[112:115], v[184:187], v[192:195], v[112:115]
	v_mfma_f32_16x16x32_bf16 v[100:103], v[176:179], v[200:203], v[100:103]
	v_mfma_f32_16x16x32_bf16 v[96:99], v[184:187], v[200:203], v[96:99]
	v_mfma_f32_16x16x32_bf16 v[84:87], v[176:179], v[208:211], v[84:87]
	v_mfma_f32_16x16x32_bf16 v[80:83], v[184:187], v[208:211], v[80:83]
	v_mfma_f32_16x16x32_bf16 v[68:71], v[176:179], v[216:219], v[68:71]
	v_mfma_f32_16x16x32_bf16 v[64:67], v[184:187], v[216:219], v[64:67]
	s_setprio 0
	s_barrier
; #define PG8_STAGE(bufoff, gbase, voff) do { _Pragma("unroll") for (int _i = 0; _i < 2; ++_i) \
;         __builtin_amdgcn_global_load_lds((const unsigned*)((const char*)(gbase) + (voff)[_i]), (PG8_LAS unsigned*)(lds + (bufoff) + ldsw + _i * 8192), 16, 0, 0); } while (0)
; #define PG8_LDA(dst, b, h) do { _Pragma("unroll") for (int m = 0; m < 4; ++m) _Pragma("unroll") for (int k = 0; k < 2; ++k) dst[m][k] = *(const PG8_LAS bf16x8*)(lds + PG8_SA(b, h) + aoff + m * 2048 + k * 1024); } while (0)
; #define PG8_MMA(ai, bj, At, Bt) do { __builtin_amdgcn_s_setprio(1); _Pragma("unroll") for (int m = 0; m < 4; ++m) _Pragma("unroll") for (int n = 0; n < 2; ++n) _Pragma("unroll") for (int k = 0; k < 2; ++k) \
;         acc[ai][bj][m][n] = __builtin_amdgcn_mfma_f32_16x16x32_bf16(Bt[n][k], At[m][k], acc[ai][bj][m][n], 0, 0, 0); __builtin_amdgcn_s_setprio(0); } while (0)
; #define PG8_WAIT_V(n) asm volatile("s_waitcnt vmcnt(" #n ")" ::: "memory")
; #define PG8_WAIT_L(n) asm volatile("s_waitcnt lgkmcnt(" #n ")" ::: "memory")
; #define PG8_BAR __builtin_amdgcn_s_barrier()
; #define PG8_SCHED __builtin_amdgcn_sched_barrier(0)
; template <class Epi, class Sched, bool ALIGN_EPI = false, bool SP2 = false>
; __device__ __forceinline__ void gemm_phase(PG8_LAS unsigned char* lds, const Gemm g, const Sched& S, const Epi& E) {
;     ...
;             PG8_LDA(At, 1, 1); PG8_STAGE(PG8_SB(1, 0), b3, voffB); PG8_STAGE(PG8_SB(1, 1), b3 + hstep, voffB); PG8_STAGE(PG8_SA(1, 0), a3, voffA);
;             PG8_WAIT_V(8); PG8_WAIT_L(0); PG8_BAR; PG8_MMA(1, 0, At, B0); PG8_MMA(1, 1, At, B1); PG8_BAR; PG8_SCHED;
	s_add_i32 s4, s79, s17
	v_lshl_add_u64 v[150:151], v[150:151], 0, s[22:23]
	s_mov_b32 m0, s4
	ds_read_b128 v[188:191], v158 offset:49152
	ds_read_b128 v[192:195], v158 offset:50176
	ds_read_b128 v[196:199], v158 offset:51200
	ds_read_b128 v[200:203], v158 offset:52224
	ds_read_b128 v[204:207], v158 offset:53248
	ds_read_b128 v[208:211], v158 offset:54272
	ds_read_b128 v[212:215], v158 offset:55296
	ds_read_b128 v[216:219], v158 offset:56320
	global_load_lds_dwordx4 v[150:151], off
	v_lshl_add_u64 v[150:151], v[220:221], 0, s[22:23]
	s_add_i32 m0, s4, 0x2000
	s_add_i32 s4, s80, s17
	global_load_lds_dwordx4 v[150:151], off
	v_lshl_add_u64 v[150:151], v[222:223], 0, s[22:23]
	s_mov_b32 m0, s4
	s_nop 0
	global_load_lds_dwordx4 v[150:151], off
	v_lshl_add_u64 v[150:151], v[224:225], 0, s[22:23]
	s_add_i32 m0, s4, 0x2000
	s_nop 0
	global_load_lds_dwordx4 v[150:151], off
	v_lshl_add_u64 v[150:151], v[226:227], 0, s[22:23]
	s_mov_b32 m0, s45
	s_nop 0
	global_load_lds_dwordx4 v[150:151], off
	v_lshl_add_u64 v[150:151], v[228:229], 0, s[22:23]
	s_mov_b32 m0, s50
	s_nop 0
	global_load_lds_dwordx4 v[150:151], off
	s_waitcnt vmcnt(8)
	s_waitcnt lgkmcnt(0)
	s_barrier
	s_setprio 1
	s_waitcnt lgkmcnt(0)
	v_mfma_f32_16x16x32_bf16 v[60:63], v[146:149], v[188:191], v[60:63]
	v_mfma_f32_16x16x32_bf16 v[56:59], v[164:167], v[188:191], v[56:59]
	v_mfma_f32_16x16x32_bf16 v[44:47], v[146:149], v[196:199], v[44:47]
	v_mfma_f32_16x16x32_bf16 v[40:43], v[164:167], v[196:199], v[40:43]
	v_mfma_f32_16x16x32_bf16 v[28:31], v[146:149], v[204:207], v[28:31]
	v_mfma_f32_16x16x32_bf16 v[24:27], v[164:167], v[204:207], v[24:27]
	v_mfma_f32_16x16x32_bf16 v[12:15], v[146:149], v[212:215], v[12:15]
	v_mfma_f32_16x16x32_bf16 v[8:11], v[164:167], v[212:215], v[8:11]
	v_mfma_f32_16x16x32_bf16 v[60:63], v[160:163], v[192:195], v[60:63]
	v_mfma_f32_16x16x32_bf16 v[56:59], v[168:171], v[192:195], v[56:59]
	v_mfma_f32_16x16x32_bf16 v[44:47], v[160:163], v[200:203], v[44:47]
	v_mfma_f32_16x16x32_bf16 v[40:43], v[168:171], v[200:203], v[40:43]
	v_mfma_f32_16x16x32_bf16 v[28:31], v[160:163], v[208:211], v[28:31]
	v_mfma_f32_16x16x32_bf16 v[24:27], v[168:171], v[208:211], v[24:27]
	v_mfma_f32_16x16x32_bf16 v[12:15], v[160:163], v[216:219], v[12:15]
	v_mfma_f32_16x16x32_bf16 v[8:11], v[168:171], v[216:219], v[8:11]
	s_setprio 0
	s_setprio 1
	v_mfma_f32_16x16x32_bf16 v[52:55], v[172:175], v[188:191], v[52:55]
	v_mfma_f32_16x16x32_bf16 v[48:51], v[180:183], v[188:191], v[48:51]
	v_mfma_f32_16x16x32_bf16 v[36:39], v[172:175], v[196:199], v[36:39]
	v_mfma_f32_16x16x32_bf16 v[32:35], v[180:183], v[196:199], v[32:35]
	v_mfma_f32_16x16x32_bf16 v[20:23], v[172:175], v[204:207], v[20:23]
	v_mfma_f32_16x16x32_bf16 v[16:19], v[180:183], v[204:207], v[16:19]
	v_mfma_f32_16x16x32_bf16 v[4:7], v[172:175], v[212:215], v[4:7]
	v_mfma_f32_16x16x32_bf16 v[0:3], v[180:183], v[212:215], v[0:3]
	v_mfma_f32_16x16x32_bf16 v[52:55], v[176:179], v[192:195], v[52:55]
	v_mfma_f32_16x16x32_bf16 v[48:51], v[184:187], v[192:195], v[48:51]
	v_mfma_f32_16x16x32_bf16 v[36:39], v[176:179], v[200:203], v[36:39]
	v_mfma_f32_16x16x32_bf16 v[32:35], v[184:187], v[200:203], v[32:35]
	v_mfma_f32_16x16x32_bf16 v[20:23], v[176:179], v[208:211], v[20:23]
	v_mfma_f32_16x16x32_bf16 v[16:19], v[184:187], v[208:211], v[16:19]
	v_mfma_f32_16x16x32_bf16 v[4:7], v[176:179], v[216:219], v[4:7]
	v_mfma_f32_16x16x32_bf16 v[0:3], v[184:187], v[216:219], v[0:3]
	s_setprio 0
	s_barrier
	s_add_u32 s0, s0, 0x100
	s_addc_u32 s1, s1, 0
	s_add_u32 s6, s6, 0x100
	s_addc_u32 s7, s7, 0
	s_cmp_ge_i32 s78, s51
	s_mov_b32 s4, s78
	s_cbranch_scc0 .LBB0_2052
	s_branch .Lpeel_x9

; #define PG8_STAGE(bufoff, gbase, voff) do { _Pragma("unroll") for (int _i = 0; _i < 2; ++_i) \
;         __builtin_amdgcn_global_load_lds((const unsigned*)((const char*)(gbase) + (voff)[_i]), (PG8_LAS unsigned*)(lds + (bufoff) + ldsw + _i * 8192), 16, 0, 0); } while (0)
; #define PG8_LDA(dst, b, h) do { _Pragma("unroll") for (int m = 0; m < 4; ++m) _Pragma("unroll") for (int k = 0; k < 2; ++k) dst[m][k] = *(const PG8_LAS bf16x8*)(lds + PG8_SA(b, h) + aoff + m * 2048 + k * 1024); } while (0)
; #define PG8_LDB(dst, b, h) do { _Pragma("unroll") for (int n = 0; n < 2; ++n) _Pragma("unroll") for (int k = 0; k < 2; ++k) dst[n][k] = *(const PG8_LAS bf16x8*)(lds + PG8_SB(b, h) + boff + n * 2048 + k * 1024); } while (0)
; #define PG8_MMA(ai, bj, At, Bt) do { __builtin_amdgcn_s_setprio(1); _Pragma("unroll") for (int m = 0; m < 4; ++m) _Pragma("unroll") for (int n = 0; n < 2; ++n) _Pragma("unroll") for (int k = 0; k < 2; ++k) \
;         acc[ai][bj][m][n] = __builtin_amdgcn_mfma_f32_16x16x32_bf16(Bt[n][k], At[m][k], acc[ai][bj][m][n], 0, 0, 0); __builtin_amdgcn_s_setprio(0); } while (0)
; #define PG8_WAIT_V(n) asm volatile("s_waitcnt vmcnt(" #n ")" ::: "memory")
; #define PG8_WAIT_L(n) asm volatile("s_waitcnt lgkmcnt(" #n ")" ::: "memory")
; #define PG8_BAR __builtin_amdgcn_s_barrier()
; #define PG8_SCHED __builtin_amdgcn_sched_barrier(0)
; template <class Epi, class Sched, bool ALIGN_EPI = false, bool SP2 = false>
; __device__ __forceinline__ void gemm_phase(PG8_LAS unsigned char* lds, const Gemm g, const Sched& S, const Epi& E) {
;     ...
;             const char* a1 = cA + (size_t)(t + 1) * kstep;
;             const char* a2 = last ? nA : cA + (size_t)(t + 2) * kstep; const char* b2 = last ? nB : cB + (size_t)(t + 2) * kstep;
;             const char* a3 = a2 + kstep; const char* b3 = b2 + kstep;
;             if (last && has_next) S.a_ready(nxt);
;             if constexpr (SP2) {
;             PG8_LDB(B0, 0, 0); PG8_LDB(B1, 0, 1); PG8_SCHED; PG8_LDA(At, 0, 0); PG8_STAGE(PG8_SA(1, 1), a1 + hstep, voffA);
;             PG8_WAIT_V(8); PG8_WAIT_L(0); PG8_BAR; PG8_MMA(0, 0, At, B0); PG8_MMA(0, 1, At, B1); PG8_BAR; PG8_SCHED;
;             PG8_LDA(At, 0, 1); PG8_STAGE(PG8_SB(0, 0), b2, voffB); PG8_STAGE(PG8_SB(0, 1), b2 + hstep, voffB); PG8_STAGE(PG8_SA(0, 0), a2, voffA);
.LBB0_2163:
	s_andn2_b64 vcc, exec, s[22:23]
	s_cbranch_vccnz .LBB0_2166
	s_add_u32 s30, s30, 0x80
	s_addc_u32 s31, s31, 0
	s_add_u32 s77, s34, 0x100
	s_addc_u32 s78, s35, 0
	s_mov_b32 s34, 0
	ds_read_b128 v[146:149], v152
	ds_read_b128 v[158:161], v152 offset:1024
	ds_read_b128 v[162:165], v152 offset:2048
	ds_read_b128 v[166:169], v152 offset:3072
	ds_read_b128 v[170:173], v153
	ds_read_b128 v[174:177], v153 offset:1024
	ds_read_b128 v[178:181], v153 offset:2048
	ds_read_b128 v[182:185], v153 offset:3072
	s_add_i32 s79, s34, 2
	s_add_u32 s80, s30, 0x80
	s_addc_u32 s35, s31, 0
	s_cmp_eq_u32 s50, s34
	s_cselect_b32 s34, s0, s80
	s_cselect_b32 s35, s1, s35
	s_cselect_b32 s81, s29, s78
	s_cselect_b32 s80, s28, s77
	v_lshl_add_u64 v[218:219], s[30:31], 0, v[138:139]
	s_add_i32 m0, s33, 0xc000
	ds_read_b128 v[186:189], v154
	ds_read_b128 v[190:193], v154 offset:1024
	ds_read_b128 v[194:197], v154 offset:2048
	ds_read_b128 v[198:201], v154 offset:3072
	ds_read_b128 v[202:205], v154 offset:4096
	ds_read_b128 v[206:209], v154 offset:5120
	ds_read_b128 v[210:213], v154 offset:6144
	ds_read_b128 v[214:217], v154 offset:7168
	global_load_lds_dwordx4 v[218:219], off
	v_lshl_add_u64 v[218:219], s[30:31], 0, v[140:141]
	s_add_i32 m0, s33, 0xe000
	s_nop 0
	global_load_lds_dwordx4 v[218:219], off
	s_waitcnt vmcnt(8)
	s_waitcnt lgkmcnt(0)
	s_barrier
	s_setprio 1
	s_waitcnt lgkmcnt(0)
	v_mfma_f32_16x16x32_bf16 v[120:123], v[146:149], v[186:189], 0
	v_mfma_f32_16x16x32_bf16 v[124:127], v[162:165], v[186:189], 0
	v_mfma_f32_16x16x32_bf16 v[108:111], v[146:149], v[194:197], 0
	v_mfma_f32_16x16x32_bf16 v[104:107], v[162:165], v[194:197], 0
	v_mfma_f32_16x16x32_bf16 v[92:95], v[146:149], v[202:205], 0
	v_mfma_f32_16x16x32_bf16 v[88:91], v[162:165], v[202:205], 0
	v_mfma_f32_16x16x32_bf16 v[76:79], v[146:149], v[210:213], 0
	v_mfma_f32_16x16x32_bf16 v[72:75], v[162:165], v[210:213], 0
	v_mfma_f32_16x16x32_bf16 v[120:123], v[158:161], v[190:193], v[120:123]
	v_mfma_f32_16x16x32_bf16 v[124:127], v[166:169], v[190:193], v[124:127]
	v_mfma_f32_16x16x32_bf16 v[108:111], v[158:161], v[198:201], v[108:111]
	v_mfma_f32_16x16x32_bf16 v[104:107], v[166:169], v[198:201], v[104:107]
	v_mfma_f32_16x16x32_bf16 v[92:95], v[158:161], v[206:209], v[92:95]
	v_mfma_f32_16x16x32_bf16 v[88:91], v[166:169], v[206:209], v[88:91]
	v_mfma_f32_16x16x32_bf16 v[76:79], v[158:161], v[214:217], v[76:79]
	v_mfma_f32_16x16x32_bf16 v[72:75], v[166:169], v[214:217], v[72:75]
	s_setprio 0
	s_setprio 1
	v_mfma_f32_16x16x32_bf16 v[116:119], v[170:173], v[186:189], 0
	v_mfma_f32_16x16x32_bf16 v[112:115], v[178:181], v[186:189], 0
	v_mfma_f32_16x16x32_bf16 v[100:103], v[170:173], v[194:197], 0
	v_mfma_f32_16x16x32_bf16 v[96:99], v[178:181], v[194:197], 0
	v_mfma_f32_16x16x32_bf16 v[84:87], v[170:173], v[202:205], 0
	v_mfma_f32_16x16x32_bf16 v[80:83], v[178:181], v[202:205], 0
	v_mfma_f32_16x16x32_bf16 v[68:71], v[170:173], v[210:213], 0
	v_mfma_f32_16x16x32_bf16 v[64:67], v[178:181], v[210:213], 0
	v_mfma_f32_16x16x32_bf16 v[116:119], v[174:177], v[190:193], v[116:119]
	v_mfma_f32_16x16x32_bf16 v[112:115], v[182:185], v[190:193], v[112:115]
	v_mfma_f32_16x16x32_bf16 v[100:103], v[174:177], v[198:201], v[100:103]
	v_mfma_f32_16x16x32_bf16 v[96:99], v[182:185], v[198:201], v[96:99]
	v_mfma_f32_16x16x32_bf16 v[84:87], v[174:177], v[206:209], v[84:87]
	v_mfma_f32_16x16x32_bf16 v[80:83], v[182:185], v[206:209], v[80:83]
	v_mfma_f32_16x16x32_bf16 v[68:71], v[174:177], v[214:217], v[68:71]
	v_mfma_f32_16x16x32_bf16 v[64:67], v[182:185], v[214:217], v[64:67]
	s_setprio 0
	s_barrier
	s_add_i32 s82, s59, s16
	v_lshl_add_u64 v[218:219], s[80:81], 0, v[130:131]
	s_mov_b32 m0, s82
	ds_read_b128 v[186:189], v154 offset:16384
	ds_read_b128 v[190:193], v154 offset:17408
	ds_read_b128 v[194:197], v154 offset:18432
	ds_read_b128 v[198:201], v154 offset:19456
	ds_read_b128 v[202:205], v154 offset:20480
	ds_read_b128 v[206:209], v154 offset:21504
	ds_read_b128 v[210:213], v154 offset:22528
	ds_read_b128 v[214:217], v154 offset:23552
	global_load_lds_dwordx4 v[218:219], off
	s_add_i32 m0, s82, 0x2000
	v_lshl_add_u64 v[220:221], s[80:81], 0, v[134:135]
	s_add_u32 s80, s80, s8
	s_addc_u32 s81, s81, s9
	s_add_i32 s82, s60, s16
	global_load_lds_dwordx4 v[220:221], off
	v_lshl_add_u64 v[222:223], s[80:81], 0, v[130:131]
	s_mov_b32 m0, s82
	v_lshl_add_u64 v[224:225], s[80:81], 0, v[134:135]
	global_load_lds_dwordx4 v[222:223], off
	s_add_i32 m0, s82, 0x2000
	v_lshl_add_u64 v[226:227], s[34:35], 0, v[128:129]
	global_load_lds_dwordx4 v[224:225], off
	s_mov_b32 m0, s33
	v_lshl_add_u64 v[228:229], s[34:35], 0, v[132:133]
	global_load_lds_dwordx4 v[226:227], off
	s_mov_b32 m0, s36
	s_nop 0
	global_load_lds_dwordx4 v[228:229], off
	s_waitcnt vmcnt(8)
	s_waitcnt lgkmcnt(0)
	s_barrier
; #define PG8_STAGE(bufoff, gbase, voff) do { _Pragma("unroll") for (int _i = 0; _i < 2; ++_i) \
;         __builtin_amdgcn_global_load_lds((const unsigned*)((const char*)(gbase) + (voff)[_i]), (PG8_LAS unsigned*)(lds + (bufoff) + ldsw + _i * 8192), 16, 0, 0); } while (0)
; #define PG8_LDA(dst, b, h) do { _Pragma("unroll") for (int m = 0; m < 4; ++m) _Pragma("unroll") for (int k = 0; k < 2; ++k) dst[m][k] = *(const PG8_LAS bf16x8*)(lds + PG8_SA(b, h) + aoff + m * 2048 + k * 1024); } while (0)
; #define PG8_LDB(dst, b, h) do { _Pragma("unroll") for (int n = 0; n < 2; ++n) _Pragma("unroll") for (int k = 0; k < 2; ++k) dst[n][k] = *(const PG8_LAS bf16x8*)(lds + PG8_SB(b, h) + boff + n * 2048 + k * 1024); } while (0)
; #define PG8_MMA(ai, bj, At, Bt) do { __builtin_amdgcn_s_setprio(1); _Pragma("unroll") for (int m = 0; m < 4; ++m) _Pragma("unroll") for (int n = 0; n < 2; ++n) _Pragma("unroll") for (int k = 0; k < 2; ++k) \
;         acc[ai][bj][m][n] = __builtin_amdgcn_mfma_f32_16x16x32_bf16(Bt[n][k], At[m][k], acc[ai][bj][m][n], 0, 0, 0); __builtin_amdgcn_s_setprio(0); } while (0)
; #define PG8_WAIT_V(n) asm volatile("s_waitcnt vmcnt(" #n ")" ::: "memory")
; #define PG8_WAIT_L(n) asm volatile("s_waitcnt lgkmcnt(" #n ")" ::: "memory")
; #define PG8_BAR __builtin_amdgcn_s_barrier()
; #define PG8_SCHED __builtin_amdgcn_sched_barrier(0)
; template <class Epi, class Sched, bool ALIGN_EPI = false, bool SP2 = false>
; __device__ __forceinline__ void gemm_phase(PG8_LAS unsigned char* lds, const Gemm g, const Sched& S, const Epi& E) {
;     ...
;             PG8_WAIT_V(8); PG8_WAIT_L(0); PG8_BAR; PG8_MMA(1, 0, At, B0); PG8_MMA(1, 1, At, B1); PG8_BAR; PG8_SCHED;
;             PG8_LDB(B0, 1, 0); PG8_LDB(B1, 1, 1); PG8_SCHED; PG8_LDA(At, 1, 0); PG8_STAGE(PG8_SA(0, 1), a2 + hstep, voffA);
;             PG8_WAIT_V(8); PG8_WAIT_L(0); PG8_BAR; PG8_MMA(0, 0, At, B0); PG8_MMA(0, 1, At, B1); PG8_BAR; PG8_SCHED;
	s_setprio 1
	s_waitcnt lgkmcnt(0)
	v_mfma_f32_16x16x32_bf16 v[60:63], v[146:149], v[186:189], 0
	v_mfma_f32_16x16x32_bf16 v[56:59], v[162:165], v[186:189], 0
	v_mfma_f32_16x16x32_bf16 v[44:47], v[146:149], v[194:197], 0
	v_mfma_f32_16x16x32_bf16 v[40:43], v[162:165], v[194:197], 0
	v_mfma_f32_16x16x32_bf16 v[28:31], v[146:149], v[202:205], 0
	v_mfma_f32_16x16x32_bf16 v[24:27], v[162:165], v[202:205], 0
	v_mfma_f32_16x16x32_bf16 v[12:15], v[146:149], v[210:213], 0
	v_mfma_f32_16x16x32_bf16 v[8:11], v[162:165], v[210:213], 0
	v_mfma_f32_16x16x32_bf16 v[60:63], v[158:161], v[190:193], v[60:63]
	v_mfma_f32_16x16x32_bf16 v[56:59], v[166:169], v[190:193], v[56:59]
	v_mfma_f32_16x16x32_bf16 v[44:47], v[158:161], v[198:201], v[44:47]
	v_mfma_f32_16x16x32_bf16 v[40:43], v[166:169], v[198:201], v[40:43]
	v_mfma_f32_16x16x32_bf16 v[28:31], v[158:161], v[206:209], v[28:31]
	v_mfma_f32_16x16x32_bf16 v[24:27], v[166:169], v[206:209], v[24:27]
	v_mfma_f32_16x16x32_bf16 v[12:15], v[158:161], v[214:217], v[12:15]
	v_mfma_f32_16x16x32_bf16 v[8:11], v[166:169], v[214:217], v[8:11]
	s_setprio 0
	s_setprio 1
	v_mfma_f32_16x16x32_bf16 v[52:55], v[170:173], v[186:189], 0
	v_mfma_f32_16x16x32_bf16 v[48:51], v[178:181], v[186:189], 0
	v_mfma_f32_16x16x32_bf16 v[36:39], v[170:173], v[194:197], 0
	v_mfma_f32_16x16x32_bf16 v[32:35], v[178:181], v[194:197], 0
	v_mfma_f32_16x16x32_bf16 v[20:23], v[170:173], v[202:205], 0
	v_mfma_f32_16x16x32_bf16 v[16:19], v[178:181], v[202:205], 0
	v_mfma_f32_16x16x32_bf16 v[4:7], v[170:173], v[210:213], 0
	v_mfma_f32_16x16x32_bf16 v[0:3], v[178:181], v[210:213], 0
	v_mfma_f32_16x16x32_bf16 v[52:55], v[174:177], v[190:193], v[52:55]
	v_mfma_f32_16x16x32_bf16 v[48:51], v[182:185], v[190:193], v[48:51]
	v_mfma_f32_16x16x32_bf16 v[36:39], v[174:177], v[198:201], v[36:39]
	v_mfma_f32_16x16x32_bf16 v[32:35], v[182:185], v[198:201], v[32:35]
	v_mfma_f32_16x16x32_bf16 v[20:23], v[174:177], v[206:209], v[20:23]
	v_mfma_f32_16x16x32_bf16 v[16:19], v[182:185], v[206:209], v[16:19]
	v_mfma_f32_16x16x32_bf16 v[4:7], v[174:177], v[214:217], v[4:7]
	v_mfma_f32_16x16x32_bf16 v[0:3], v[182:185], v[214:217], v[0:3]
	s_setprio 0
	s_barrier
	s_add_i32 s80, 0, 0x18000
	s_add_i32 s81, 0, 0x1c000
	v_add_u32_e32 v166, s80, v151
	v_add_u32_e32 v182, s81, v151
	ds_read_b128 v[146:149], v166
	ds_read_b128 v[158:161], v166 offset:1024
	ds_read_b128 v[162:165], v166 offset:2048
	ds_read_b128 v[166:169], v166 offset:3072
	ds_read_b128 v[170:173], v182
	ds_read_b128 v[174:177], v182 offset:1024
	ds_read_b128 v[178:181], v182 offset:2048
	ds_read_b128 v[182:185], v182 offset:3072
	s_add_u32 s34, s34, s8
	s_addc_u32 s35, s35, s9
	s_mov_b32 m0, s37
	v_lshl_add_u64 v[230:231], s[34:35], 0, v[128:129]
	ds_read_b128 v[186:189], v154 offset:32768
	ds_read_b128 v[190:193], v154 offset:33792
	ds_read_b128 v[194:197], v154 offset:34816
	ds_read_b128 v[198:201], v154 offset:35840
	ds_read_b128 v[202:205], v154 offset:36864
	ds_read_b128 v[206:209], v154 offset:37888
	ds_read_b128 v[210:213], v154 offset:38912
	ds_read_b128 v[214:217], v154 offset:39936
	global_load_lds_dwordx4 v[230:231], off
	v_lshl_add_u64 v[230:231], s[34:35], 0, v[132:133]
	s_mov_b32 m0, s38
	s_nop 0
	global_load_lds_dwordx4 v[230:231], off
	s_waitcnt vmcnt(8)
	s_waitcnt lgkmcnt(0)
	s_barrier
	s_setprio 1
	s_waitcnt lgkmcnt(0)
	v_mfma_f32_16x16x32_bf16 v[120:123], v[146:149], v[186:189], v[120:123]
	v_mfma_f32_16x16x32_bf16 v[124:127], v[162:165], v[186:189], v[124:127]
	v_mfma_f32_16x16x32_bf16 v[108:111], v[146:149], v[194:197], v[108:111]
	v_mfma_f32_16x16x32_bf16 v[104:107], v[162:165], v[194:197], v[104:107]
	v_mfma_f32_16x16x32_bf16 v[92:95], v[146:149], v[202:205], v[92:95]
	v_mfma_f32_16x16x32_bf16 v[88:91], v[162:165], v[202:205], v[88:91]
	v_mfma_f32_16x16x32_bf16 v[76:79], v[146:149], v[210:213], v[76:79]
	v_mfma_f32_16x16x32_bf16 v[72:75], v[162:165], v[210:213], v[72:75]
	v_mfma_f32_16x16x32_bf16 v[120:123], v[158:161], v[190:193], v[120:123]
	v_mfma_f32_16x16x32_bf16 v[124:127], v[166:169], v[190:193], v[124:127]
	v_mfma_f32_16x16x32_bf16 v[108:111], v[158:161], v[198:201], v[108:111]
	v_mfma_f32_16x16x32_bf16 v[104:107], v[166:169], v[198:201], v[104:107]
	v_mfma_f32_16x16x32_bf16 v[92:95], v[158:161], v[206:209], v[92:95]
	v_mfma_f32_16x16x32_bf16 v[88:91], v[166:169], v[206:209], v[88:91]
	v_mfma_f32_16x16x32_bf16 v[76:79], v[158:161], v[214:217], v[76:79]
	v_mfma_f32_16x16x32_bf16 v[72:75], v[166:169], v[214:217], v[72:75]
	s_setprio 0
	s_setprio 1
	v_mfma_f32_16x16x32_bf16 v[116:119], v[170:173], v[186:189], v[116:119]
	v_mfma_f32_16x16x32_bf16 v[112:115], v[178:181], v[186:189], v[112:115]
	v_mfma_f32_16x16x32_bf16 v[100:103], v[170:173], v[194:197], v[100:103]
	v_mfma_f32_16x16x32_bf16 v[96:99], v[178:181], v[194:197], v[96:99]
	v_mfma_f32_16x16x32_bf16 v[84:87], v[170:173], v[202:205], v[84:87]
	v_mfma_f32_16x16x32_bf16 v[80:83], v[178:181], v[202:205], v[80:83]
	v_mfma_f32_16x16x32_bf16 v[68:71], v[170:173], v[210:213], v[68:71]
	v_mfma_f32_16x16x32_bf16 v[64:67], v[178:181], v[210:213], v[64:67]
	v_mfma_f32_16x16x32_bf16 v[116:119], v[174:177], v[190:193], v[116:119]
	v_mfma_f32_16x16x32_bf16 v[112:115], v[182:185], v[190:193], v[112:115]
	v_mfma_f32_16x16x32_bf16 v[100:103], v[174:177], v[198:201], v[100:103]
	v_mfma_f32_16x16x32_bf16 v[96:99], v[182:185], v[198:201], v[96:99]
	v_mfma_f32_16x16x32_bf16 v[84:87], v[174:177], v[206:209], v[84:87]
	v_mfma_f32_16x16x32_bf16 v[80:83], v[182:185], v[206:209], v[80:83]
	v_mfma_f32_16x16x32_bf16 v[68:71], v[174:177], v[214:217], v[68:71]
	v_mfma_f32_16x16x32_bf16 v[64:67], v[182:185], v[214:217], v[64:67]
	s_setprio 0
	s_barrier
; #define PG8_STAGE(bufoff, gbase, voff) do { _Pragma("unroll") for (int _i = 0; _i < 2; ++_i) \
;         __builtin_amdgcn_global_load_lds((const unsigned*)((const char*)(gbase) + (voff)[_i]), (PG8_LAS unsigned*)(lds + (bufoff) + ldsw + _i * 8192), 16, 0, 0); } while (0)
; #define PG8_LDA(dst, b, h) do { _Pragma("unroll") for (int m = 0; m < 4; ++m) _Pragma("unroll") for (int k = 0; k < 2; ++k) dst[m][k] = *(const PG8_LAS bf16x8*)(lds + PG8_SA(b, h) + aoff + m * 2048 + k * 1024); } while (0)
; #define PG8_MMA(ai, bj, At, Bt) do { __builtin_amdgcn_s_setprio(1); _Pragma("unroll") for (int m = 0; m < 4; ++m) _Pragma("unroll") for (int n = 0; n < 2; ++n) _Pragma("unroll") for (int k = 0; k < 2; ++k) \
;         acc[ai][bj][m][n] = __builtin_amdgcn_mfma_f32_16x16x32_bf16(Bt[n][k], At[m][k], acc[ai][bj][m][n], 0, 0, 0); __builtin_amdgcn_s_setprio(0); } while (0)
; #define PG8_WAIT_V(n) asm volatile("s_waitcnt vmcnt(" #n ")" ::: "memory")
; #define PG8_WAIT_L(n) asm volatile("s_waitcnt lgkmcnt(" #n ")" ::: "memory")
; #define PG8_BAR __builtin_amdgcn_s_barrier()
; #define PG8_SCHED __builtin_amdgcn_sched_barrier(0)
; template <class Epi, class Sched, bool ALIGN_EPI = false, bool SP2 = false>
; __device__ __forceinline__ void gemm_phase(PG8_LAS unsigned char* lds, const Gemm g, const Sched& S, const Epi& E) {
;     ...
;             PG8_LDA(At, 1, 1); PG8_STAGE(PG8_SB(1, 0), b3, voffB); PG8_STAGE(PG8_SB(1, 1), b3 + hstep, voffB); PG8_STAGE(PG8_SA(1, 0), a3, voffA);
;             PG8_WAIT_V(8); PG8_WAIT_L(0); PG8_BAR; PG8_MMA(1, 0, At, B0); PG8_MMA(1, 1, At, B1); PG8_BAR; PG8_SCHED;
	s_add_i32 s34, s80, s16
	v_lshl_add_u64 v[218:219], v[218:219], 0, s[20:21]
	s_mov_b32 m0, s34
	ds_read_b128 v[186:189], v154 offset:49152
	ds_read_b128 v[190:193], v154 offset:50176
	ds_read_b128 v[194:197], v154 offset:51200
	ds_read_b128 v[198:201], v154 offset:52224
	ds_read_b128 v[202:205], v154 offset:53248
	ds_read_b128 v[206:209], v154 offset:54272
	ds_read_b128 v[210:213], v154 offset:55296
	ds_read_b128 v[214:217], v154 offset:56320
	global_load_lds_dwordx4 v[218:219], off
	v_lshl_add_u64 v[218:219], v[220:221], 0, s[20:21]
	s_add_i32 m0, s34, 0x2000
	s_add_i32 s34, s81, s16
	global_load_lds_dwordx4 v[218:219], off
	v_lshl_add_u64 v[218:219], v[222:223], 0, s[20:21]
	s_mov_b32 m0, s34
	s_nop 0
	global_load_lds_dwordx4 v[218:219], off
	v_lshl_add_u64 v[218:219], v[224:225], 0, s[20:21]
	s_add_i32 m0, s34, 0x2000
	s_nop 0
	global_load_lds_dwordx4 v[218:219], off
	v_lshl_add_u64 v[218:219], v[226:227], 0, s[20:21]
	s_mov_b32 m0, s44
	s_nop 0
	global_load_lds_dwordx4 v[218:219], off
	v_lshl_add_u64 v[218:219], v[228:229], 0, s[20:21]
	s_mov_b32 m0, s45
	s_nop 0
	global_load_lds_dwordx4 v[218:219], off
	s_waitcnt vmcnt(8)
	s_waitcnt lgkmcnt(0)
	s_barrier
	s_setprio 1
	s_waitcnt lgkmcnt(0)
	v_mfma_f32_16x16x32_bf16 v[60:63], v[146:149], v[186:189], v[60:63]
	v_mfma_f32_16x16x32_bf16 v[56:59], v[162:165], v[186:189], v[56:59]
	v_mfma_f32_16x16x32_bf16 v[44:47], v[146:149], v[194:197], v[44:47]
	v_mfma_f32_16x16x32_bf16 v[40:43], v[162:165], v[194:197], v[40:43]
	v_mfma_f32_16x16x32_bf16 v[28:31], v[146:149], v[202:205], v[28:31]
	v_mfma_f32_16x16x32_bf16 v[24:27], v[162:165], v[202:205], v[24:27]
	v_mfma_f32_16x16x32_bf16 v[12:15], v[146:149], v[210:213], v[12:15]
	v_mfma_f32_16x16x32_bf16 v[8:11], v[162:165], v[210:213], v[8:11]
	v_mfma_f32_16x16x32_bf16 v[60:63], v[158:161], v[190:193], v[60:63]
	v_mfma_f32_16x16x32_bf16 v[56:59], v[166:169], v[190:193], v[56:59]
	v_mfma_f32_16x16x32_bf16 v[44:47], v[158:161], v[198:201], v[44:47]
	v_mfma_f32_16x16x32_bf16 v[40:43], v[166:169], v[198:201], v[40:43]
	v_mfma_f32_16x16x32_bf16 v[28:31], v[158:161], v[206:209], v[28:31]
	v_mfma_f32_16x16x32_bf16 v[24:27], v[166:169], v[206:209], v[24:27]
	v_mfma_f32_16x16x32_bf16 v[12:15], v[158:161], v[214:217], v[12:15]
	v_mfma_f32_16x16x32_bf16 v[8:11], v[166:169], v[214:217], v[8:11]
	s_setprio 0
	s_setprio 1
	v_mfma_f32_16x16x32_bf16 v[52:55], v[170:173], v[186:189], v[52:55]
	v_mfma_f32_16x16x32_bf16 v[48:51], v[178:181], v[186:189], v[48:51]
	v_mfma_f32_16x16x32_bf16 v[36:39], v[170:173], v[194:197], v[36:39]
	v_mfma_f32_16x16x32_bf16 v[32:35], v[178:181], v[194:197], v[32:35]
	v_mfma_f32_16x16x32_bf16 v[20:23], v[170:173], v[202:205], v[20:23]
	v_mfma_f32_16x16x32_bf16 v[16:19], v[178:181], v[202:205], v[16:19]
	v_mfma_f32_16x16x32_bf16 v[4:7], v[170:173], v[210:213], v[4:7]
	v_mfma_f32_16x16x32_bf16 v[0:3], v[178:181], v[210:213], v[0:3]
	v_mfma_f32_16x16x32_bf16 v[52:55], v[174:177], v[190:193], v[52:55]
	v_mfma_f32_16x16x32_bf16 v[48:51], v[182:185], v[190:193], v[48:51]
	v_mfma_f32_16x16x32_bf16 v[36:39], v[174:177], v[198:201], v[36:39]
	v_mfma_f32_16x16x32_bf16 v[32:35], v[182:185], v[198:201], v[32:35]
	v_mfma_f32_16x16x32_bf16 v[20:23], v[174:177], v[206:209], v[20:23]
	v_mfma_f32_16x16x32_bf16 v[16:19], v[182:185], v[206:209], v[16:19]
	v_mfma_f32_16x16x32_bf16 v[4:7], v[174:177], v[214:217], v[4:7]
	v_mfma_f32_16x16x32_bf16 v[0:3], v[182:185], v[214:217], v[0:3]
	s_setprio 0
	s_barrier
	s_add_u32 s30, s30, 0x100
	s_addc_u32 s31, s31, 0
	s_add_u32 s77, s77, 0x100
	s_addc_u32 s78, s78, 0
	s_cmp_ge_i32 s79, s40
	s_mov_b32 s34, s79
	s_cbranch_scc0 .LBB0_2165
	s_branch .Lpeel_x10

; #define PG8_BAR __builtin_amdgcn_s_barrier()
; template <class Epi, class Sched, bool ALIGN_EPI = false, bool SP2 = false>
; __device__ __forceinline__ void gemm_phase(PG8_LAS unsigned char* lds, const Gemm g, const Sched& S, const Epi& E) {
;     ...
;         if constexpr (ALIGN_EPI) { if (wr == 0) PG8_BAR; }
.Lpeel_x10:
.LBB0_2166:
	s_and_b64 vcc, exec, s[24:25]
	s_cbranch_vccz .LBB0_2168
	s_barrier

; #define PG8_STAGE(bufoff, gbase, voff) do { _Pragma("unroll") for (int _i = 0; _i < 2; ++_i) \
;         __builtin_amdgcn_global_load_lds((const unsigned*)((const char*)(gbase) + (voff)[_i]), (PG8_LAS unsigned*)(lds + (bufoff) + ldsw + _i * 8192), 16, 0, 0); } while (0)
; #define PG8_LDA(dst, b, h) do { _Pragma("unroll") for (int m = 0; m < 4; ++m) _Pragma("unroll") for (int k = 0; k < 2; ++k) dst[m][k] = *(const PG8_LAS bf16x8*)(lds + PG8_SA(b, h) + aoff + m * 2048 + k * 1024); } while (0)
; #define PG8_LDB(dst, b, h) do { _Pragma("unroll") for (int n = 0; n < 2; ++n) _Pragma("unroll") for (int k = 0; k < 2; ++k) dst[n][k] = *(const PG8_LAS bf16x8*)(lds + PG8_SB(b, h) + boff + n * 2048 + k * 1024); } while (0)
; #define PG8_MMA(ai, bj, At, Bt) do { __builtin_amdgcn_s_setprio(1); _Pragma("unroll") for (int m = 0; m < 4; ++m) _Pragma("unroll") for (int n = 0; n < 2; ++n) _Pragma("unroll") for (int k = 0; k < 2; ++k) \
;         acc[ai][bj][m][n] = __builtin_amdgcn_mfma_f32_16x16x32_bf16(Bt[n][k], At[m][k], acc[ai][bj][m][n], 0, 0, 0); __builtin_amdgcn_s_setprio(0); } while (0)
; #define PG8_WAIT_V(n) asm volatile("s_waitcnt vmcnt(" #n ")" ::: "memory")
; #define PG8_WAIT_L(n) asm volatile("s_waitcnt lgkmcnt(" #n ")" ::: "memory")
; #define PG8_BAR __builtin_amdgcn_s_barrier()
; #define PG8_SCHED __builtin_amdgcn_sched_barrier(0)
; template <class Epi, class Sched, bool ALIGN_EPI = false, bool SP2 = false>
; __device__ __forceinline__ void gemm_phase(PG8_LAS unsigned char* lds, const Gemm g, const Sched& S, const Epi& E) {
;     ...
;             const char* a1 = cA + (size_t)(t + 1) * kstep;
;             const char* a2 = last ? nA : cA + (size_t)(t + 2) * kstep; const char* b2 = last ? nB : cB + (size_t)(t + 2) * kstep;
;             const char* a3 = a2 + kstep; const char* b3 = b2 + kstep;
;             if (last && has_next) S.a_ready(nxt);
;             if constexpr (SP2) {
;             PG8_LDB(B0, 0, 0); PG8_LDB(B1, 0, 1); PG8_SCHED; PG8_LDA(At, 0, 0); PG8_STAGE(PG8_SA(1, 1), a1 + hstep, voffA);
;             PG8_WAIT_V(8); PG8_WAIT_L(0); PG8_BAR; PG8_MMA(0, 0, At, B0); PG8_MMA(0, 1, At, B1); PG8_BAR; PG8_SCHED;
;             PG8_LDA(At, 0, 1); PG8_STAGE(PG8_SB(0, 0), b2, voffB); PG8_STAGE(PG8_SB(0, 1), b2 + hstep, voffB); PG8_STAGE(PG8_SA(0, 0), a2, voffA);
.LBB0_2384:
	s_andn2_b64 vcc, exec, s[24:25]
	s_waitcnt vmcnt(0)
	s_waitcnt lgkmcnt(0)
	s_cbranch_vccnz .LBB0_2387
	s_add_u32 s30, s30, 0x80
	s_addc_u32 s31, s31, 0
	s_add_u32 s61, s34, 0x100
	s_addc_u32 s62, s35, 0
	s_mov_b32 s34, 0
	ds_read_b128 v[144:147], v151
	ds_read_b128 v[156:159], v151 offset:1024
	ds_read_b128 v[160:163], v151 offset:2048
	ds_read_b128 v[164:167], v151 offset:3072
	ds_read_b128 v[168:171], v152
	ds_read_b128 v[172:175], v152 offset:1024
	ds_read_b128 v[176:179], v152 offset:2048
	ds_read_b128 v[180:183], v152 offset:3072
	s_add_i32 s63, s34, 2
	s_add_u32 s64, s30, 0x80
	s_addc_u32 s35, s31, 0
	s_cmp_eq_u32 s41, s34
	s_cselect_b32 s34, s0, s64
	s_cselect_b32 s35, s1, s35
	s_cselect_b32 s65, s29, s62
	s_cselect_b32 s64, s28, s61
	v_lshl_add_u64 v[216:217], s[30:31], 0, v[136:137]
	s_add_i32 m0, s17, 0xc000
	ds_read_b128 v[184:187], v153
	ds_read_b128 v[188:191], v153 offset:1024
	ds_read_b128 v[192:195], v153 offset:2048
	ds_read_b128 v[196:199], v153 offset:3072
	ds_read_b128 v[200:203], v153 offset:4096
	ds_read_b128 v[204:207], v153 offset:5120
	ds_read_b128 v[208:211], v153 offset:6144
	ds_read_b128 v[212:215], v153 offset:7168
	global_load_lds_dwordx4 v[216:217], off
	v_lshl_add_u64 v[216:217], s[30:31], 0, v[138:139]
	s_add_i32 m0, s17, 0xe000
	s_nop 0
	global_load_lds_dwordx4 v[216:217], off
	s_waitcnt vmcnt(8)
	s_waitcnt lgkmcnt(0)
	s_barrier
	s_setprio 1
	s_waitcnt lgkmcnt(0)
	v_mfma_f32_16x16x32_bf16 v[124:127], v[144:147], v[184:187], 0
	v_mfma_f32_16x16x32_bf16 v[120:123], v[160:163], v[184:187], 0
	v_mfma_f32_16x16x32_bf16 v[108:111], v[144:147], v[192:195], 0
	v_mfma_f32_16x16x32_bf16 v[104:107], v[160:163], v[192:195], 0
	v_mfma_f32_16x16x32_bf16 v[92:95], v[144:147], v[200:203], 0
	v_mfma_f32_16x16x32_bf16 v[88:91], v[160:163], v[200:203], 0
	v_mfma_f32_16x16x32_bf16 v[76:79], v[144:147], v[208:211], 0
	v_mfma_f32_16x16x32_bf16 v[72:75], v[160:163], v[208:211], 0
	v_mfma_f32_16x16x32_bf16 v[124:127], v[156:159], v[188:191], v[124:127]
	v_mfma_f32_16x16x32_bf16 v[120:123], v[164:167], v[188:191], v[120:123]
	v_mfma_f32_16x16x32_bf16 v[108:111], v[156:159], v[196:199], v[108:111]
	v_mfma_f32_16x16x32_bf16 v[104:107], v[164:167], v[196:199], v[104:107]
	v_mfma_f32_16x16x32_bf16 v[92:95], v[156:159], v[204:207], v[92:95]
	v_mfma_f32_16x16x32_bf16 v[88:91], v[164:167], v[204:207], v[88:91]
	v_mfma_f32_16x16x32_bf16 v[76:79], v[156:159], v[212:215], v[76:79]
	v_mfma_f32_16x16x32_bf16 v[72:75], v[164:167], v[212:215], v[72:75]
	s_setprio 0
	s_setprio 1
	v_mfma_f32_16x16x32_bf16 v[116:119], v[168:171], v[184:187], 0
	v_mfma_f32_16x16x32_bf16 v[112:115], v[176:179], v[184:187], 0
	v_mfma_f32_16x16x32_bf16 v[100:103], v[168:171], v[192:195], 0
	v_mfma_f32_16x16x32_bf16 v[96:99], v[176:179], v[192:195], 0
	v_mfma_f32_16x16x32_bf16 v[84:87], v[168:171], v[200:203], 0
	v_mfma_f32_16x16x32_bf16 v[80:83], v[176:179], v[200:203], 0
	v_mfma_f32_16x16x32_bf16 v[68:71], v[168:171], v[208:211], 0
	v_mfma_f32_16x16x32_bf16 v[64:67], v[176:179], v[208:211], 0
	v_mfma_f32_16x16x32_bf16 v[116:119], v[172:175], v[188:191], v[116:119]
	v_mfma_f32_16x16x32_bf16 v[112:115], v[180:183], v[188:191], v[112:115]
	v_mfma_f32_16x16x32_bf16 v[100:103], v[172:175], v[196:199], v[100:103]
	v_mfma_f32_16x16x32_bf16 v[96:99], v[180:183], v[196:199], v[96:99]
	v_mfma_f32_16x16x32_bf16 v[84:87], v[172:175], v[204:207], v[84:87]
	v_mfma_f32_16x16x32_bf16 v[80:83], v[180:183], v[204:207], v[80:83]
	v_mfma_f32_16x16x32_bf16 v[68:71], v[172:175], v[212:215], v[68:71]
	v_mfma_f32_16x16x32_bf16 v[64:67], v[180:183], v[212:215], v[64:67]
	s_setprio 0
	s_barrier
	s_add_i32 s66, s51, s16
	v_lshl_add_u64 v[216:217], s[64:65], 0, v[130:131]
	s_mov_b32 m0, s66
	ds_read_b128 v[184:187], v153 offset:16384
	ds_read_b128 v[188:191], v153 offset:17408
	ds_read_b128 v[192:195], v153 offset:18432
	ds_read_b128 v[196:199], v153 offset:19456
	ds_read_b128 v[200:203], v153 offset:20480
	ds_read_b128 v[204:207], v153 offset:21504
	ds_read_b128 v[208:211], v153 offset:22528
	ds_read_b128 v[212:215], v153 offset:23552
	global_load_lds_dwordx4 v[216:217], off
	s_add_i32 m0, s66, 0x2000
	v_lshl_add_u64 v[218:219], s[64:65], 0, v[134:135]
	s_add_u32 s64, s64, s6
	s_addc_u32 s65, s65, s7
	s_add_i32 s66, s56, s16
	global_load_lds_dwordx4 v[218:219], off
	v_lshl_add_u64 v[220:221], s[64:65], 0, v[130:131]
	s_mov_b32 m0, s66
	v_lshl_add_u64 v[222:223], s[64:65], 0, v[134:135]
	global_load_lds_dwordx4 v[220:221], off
	s_add_i32 m0, s66, 0x2000
	v_lshl_add_u64 v[224:225], s[34:35], 0, v[128:129]
	global_load_lds_dwordx4 v[222:223], off
	s_mov_b32 m0, s17
	v_lshl_add_u64 v[226:227], s[34:35], 0, v[132:133]
	global_load_lds_dwordx4 v[224:225], off
	s_mov_b32 m0, s19
	s_nop 0
	global_load_lds_dwordx4 v[226:227], off
	s_waitcnt vmcnt(8)
	s_waitcnt lgkmcnt(0)
	s_barrier
; #define PG8_STAGE(bufoff, gbase, voff) do { _Pragma("unroll") for (int _i = 0; _i < 2; ++_i) \
;         __builtin_amdgcn_global_load_lds((const unsigned*)((const char*)(gbase) + (voff)[_i]), (PG8_LAS unsigned*)(lds + (bufoff) + ldsw + _i * 8192), 16, 0, 0); } while (0)
; #define PG8_LDA(dst, b, h) do { _Pragma("unroll") for (int m = 0; m < 4; ++m) _Pragma("unroll") for (int k = 0; k < 2; ++k) dst[m][k] = *(const PG8_LAS bf16x8*)(lds + PG8_SA(b, h) + aoff + m * 2048 + k * 1024); } while (0)
; #define PG8_LDB(dst, b, h) do { _Pragma("unroll") for (int n = 0; n < 2; ++n) _Pragma("unroll") for (int k = 0; k < 2; ++k) dst[n][k] = *(const PG8_LAS bf16x8*)(lds + PG8_SB(b, h) + boff + n * 2048 + k * 1024); } while (0)
; #define PG8_MMA(ai, bj, At, Bt) do { __builtin_amdgcn_s_setprio(1); _Pragma("unroll") for (int m = 0; m < 4; ++m) _Pragma("unroll") for (int n = 0; n < 2; ++n) _Pragma("unroll") for (int k = 0; k < 2; ++k) \
;         acc[ai][bj][m][n] = __builtin_amdgcn_mfma_f32_16x16x32_bf16(Bt[n][k], At[m][k], acc[ai][bj][m][n], 0, 0, 0); __builtin_amdgcn_s_setprio(0); } while (0)
; #define PG8_WAIT_V(n) asm volatile("s_waitcnt vmcnt(" #n ")" ::: "memory")
; #define PG8_WAIT_L(n) asm volatile("s_waitcnt lgkmcnt(" #n ")" ::: "memory")
; #define PG8_BAR __builtin_amdgcn_s_barrier()
; #define PG8_SCHED __builtin_amdgcn_sched_barrier(0)
; template <class Epi, class Sched, bool ALIGN_EPI = false, bool SP2 = false>
; __device__ __forceinline__ void gemm_phase(PG8_LAS unsigned char* lds, const Gemm g, const Sched& S, const Epi& E) {
;     ...
;             PG8_WAIT_V(8); PG8_WAIT_L(0); PG8_BAR; PG8_MMA(1, 0, At, B0); PG8_MMA(1, 1, At, B1); PG8_BAR; PG8_SCHED;
;             PG8_LDB(B0, 1, 0); PG8_LDB(B1, 1, 1); PG8_SCHED; PG8_LDA(At, 1, 0); PG8_STAGE(PG8_SA(0, 1), a2 + hstep, voffA);
;             PG8_WAIT_V(8); PG8_WAIT_L(0); PG8_BAR; PG8_MMA(0, 0, At, B0); PG8_MMA(0, 1, At, B1); PG8_BAR; PG8_SCHED;
	s_setprio 1
	s_waitcnt lgkmcnt(0)
	v_mfma_f32_16x16x32_bf16 v[60:63], v[144:147], v[184:187], 0
	v_mfma_f32_16x16x32_bf16 v[56:59], v[160:163], v[184:187], 0
	v_mfma_f32_16x16x32_bf16 v[44:47], v[144:147], v[192:195], 0
	v_mfma_f32_16x16x32_bf16 v[40:43], v[160:163], v[192:195], 0
	v_mfma_f32_16x16x32_bf16 v[28:31], v[144:147], v[200:203], 0
	v_mfma_f32_16x16x32_bf16 v[24:27], v[160:163], v[200:203], 0
	v_mfma_f32_16x16x32_bf16 v[12:15], v[144:147], v[208:211], 0
	v_mfma_f32_16x16x32_bf16 v[8:11], v[160:163], v[208:211], 0
	v_mfma_f32_16x16x32_bf16 v[60:63], v[156:159], v[188:191], v[60:63]
	v_mfma_f32_16x16x32_bf16 v[56:59], v[164:167], v[188:191], v[56:59]
	v_mfma_f32_16x16x32_bf16 v[44:47], v[156:159], v[196:199], v[44:47]
	v_mfma_f32_16x16x32_bf16 v[40:43], v[164:167], v[196:199], v[40:43]
	v_mfma_f32_16x16x32_bf16 v[28:31], v[156:159], v[204:207], v[28:31]
	v_mfma_f32_16x16x32_bf16 v[24:27], v[164:167], v[204:207], v[24:27]
	v_mfma_f32_16x16x32_bf16 v[12:15], v[156:159], v[212:215], v[12:15]
	v_mfma_f32_16x16x32_bf16 v[8:11], v[164:167], v[212:215], v[8:11]
	s_setprio 0
	s_setprio 1
	v_mfma_f32_16x16x32_bf16 v[52:55], v[168:171], v[184:187], 0
	v_mfma_f32_16x16x32_bf16 v[48:51], v[176:179], v[184:187], 0
	v_mfma_f32_16x16x32_bf16 v[36:39], v[168:171], v[192:195], 0
	v_mfma_f32_16x16x32_bf16 v[32:35], v[176:179], v[192:195], 0
	v_mfma_f32_16x16x32_bf16 v[20:23], v[168:171], v[200:203], 0
	v_mfma_f32_16x16x32_bf16 v[16:19], v[176:179], v[200:203], 0
	v_mfma_f32_16x16x32_bf16 v[4:7], v[168:171], v[208:211], 0
	v_mfma_f32_16x16x32_bf16 v[0:3], v[176:179], v[208:211], 0
	v_mfma_f32_16x16x32_bf16 v[52:55], v[172:175], v[188:191], v[52:55]
	v_mfma_f32_16x16x32_bf16 v[48:51], v[180:183], v[188:191], v[48:51]
	v_mfma_f32_16x16x32_bf16 v[36:39], v[172:175], v[196:199], v[36:39]
	v_mfma_f32_16x16x32_bf16 v[32:35], v[180:183], v[196:199], v[32:35]
	v_mfma_f32_16x16x32_bf16 v[20:23], v[172:175], v[204:207], v[20:23]
	v_mfma_f32_16x16x32_bf16 v[16:19], v[180:183], v[204:207], v[16:19]
	v_mfma_f32_16x16x32_bf16 v[4:7], v[172:175], v[212:215], v[4:7]
	v_mfma_f32_16x16x32_bf16 v[0:3], v[180:183], v[212:215], v[0:3]
	s_setprio 0
	s_barrier
	s_add_i32 s64, 0, 0x18000
	v_add_u32_e32 v155, s64, v149
	s_add_i32 s65, 0, 0x1c000
	ds_read_b128 v[144:147], v155
	ds_read_b128 v[156:159], v155 offset:1024
	ds_read_b128 v[160:163], v155 offset:2048
	ds_read_b128 v[164:167], v155 offset:3072
	v_add_u32_e32 v155, s65, v149
	ds_read_b128 v[168:171], v155
	ds_read_b128 v[172:175], v155 offset:1024
	ds_read_b128 v[176:179], v155 offset:2048
	ds_read_b128 v[180:183], v155 offset:3072
	s_add_u32 s34, s34, s6
	s_addc_u32 s35, s35, s7
	s_mov_b32 m0, s33
	v_lshl_add_u64 v[228:229], s[34:35], 0, v[128:129]
	ds_read_b128 v[184:187], v153 offset:32768
	ds_read_b128 v[188:191], v153 offset:33792
	ds_read_b128 v[192:195], v153 offset:34816
	ds_read_b128 v[196:199], v153 offset:35840
	ds_read_b128 v[200:203], v153 offset:36864
	ds_read_b128 v[204:207], v153 offset:37888
	ds_read_b128 v[208:211], v153 offset:38912
	ds_read_b128 v[212:215], v153 offset:39936
	global_load_lds_dwordx4 v[228:229], off
	v_lshl_add_u64 v[228:229], s[34:35], 0, v[132:133]
	s_mov_b32 m0, s36
	s_nop 0
	global_load_lds_dwordx4 v[228:229], off
	s_waitcnt vmcnt(8)
	s_waitcnt lgkmcnt(0)
	s_barrier
	s_setprio 1
	s_waitcnt lgkmcnt(0)
	v_mfma_f32_16x16x32_bf16 v[124:127], v[144:147], v[184:187], v[124:127]
	v_mfma_f32_16x16x32_bf16 v[120:123], v[160:163], v[184:187], v[120:123]
	v_mfma_f32_16x16x32_bf16 v[108:111], v[144:147], v[192:195], v[108:111]
	v_mfma_f32_16x16x32_bf16 v[104:107], v[160:163], v[192:195], v[104:107]
	v_mfma_f32_16x16x32_bf16 v[92:95], v[144:147], v[200:203], v[92:95]
	v_mfma_f32_16x16x32_bf16 v[88:91], v[160:163], v[200:203], v[88:91]
	v_mfma_f32_16x16x32_bf16 v[76:79], v[144:147], v[208:211], v[76:79]
	v_mfma_f32_16x16x32_bf16 v[72:75], v[160:163], v[208:211], v[72:75]
	v_mfma_f32_16x16x32_bf16 v[124:127], v[156:159], v[188:191], v[124:127]
	v_mfma_f32_16x16x32_bf16 v[120:123], v[164:167], v[188:191], v[120:123]
	v_mfma_f32_16x16x32_bf16 v[108:111], v[156:159], v[196:199], v[108:111]
	v_mfma_f32_16x16x32_bf16 v[104:107], v[164:167], v[196:199], v[104:107]
	v_mfma_f32_16x16x32_bf16 v[92:95], v[156:159], v[204:207], v[92:95]
	v_mfma_f32_16x16x32_bf16 v[88:91], v[164:167], v[204:207], v[88:91]
	v_mfma_f32_16x16x32_bf16 v[76:79], v[156:159], v[212:215], v[76:79]
	v_mfma_f32_16x16x32_bf16 v[72:75], v[164:167], v[212:215], v[72:75]
	s_setprio 0
	s_setprio 1
	v_mfma_f32_16x16x32_bf16 v[116:119], v[168:171], v[184:187], v[116:119]
	v_mfma_f32_16x16x32_bf16 v[112:115], v[176:179], v[184:187], v[112:115]
	v_mfma_f32_16x16x32_bf16 v[100:103], v[168:171], v[192:195], v[100:103]
	v_mfma_f32_16x16x32_bf16 v[96:99], v[176:179], v[192:195], v[96:99]
	v_mfma_f32_16x16x32_bf16 v[84:87], v[168:171], v[200:203], v[84:87]
	v_mfma_f32_16x16x32_bf16 v[80:83], v[176:179], v[200:203], v[80:83]
	v_mfma_f32_16x16x32_bf16 v[68:71], v[168:171], v[208:211], v[68:71]
	v_mfma_f32_16x16x32_bf16 v[64:67], v[176:179], v[208:211], v[64:67]
	v_mfma_f32_16x16x32_bf16 v[116:119], v[172:175], v[188:191], v[116:119]
	v_mfma_f32_16x16x32_bf16 v[112:115], v[180:183], v[188:191], v[112:115]
	v_mfma_f32_16x16x32_bf16 v[100:103], v[172:175], v[196:199], v[100:103]
	v_mfma_f32_16x16x32_bf16 v[96:99], v[180:183], v[196:199], v[96:99]
	v_mfma_f32_16x16x32_bf16 v[84:87], v[172:175], v[204:207], v[84:87]
	v_mfma_f32_16x16x32_bf16 v[80:83], v[180:183], v[204:207], v[80:83]
	v_mfma_f32_16x16x32_bf16 v[68:71], v[172:175], v[212:215], v[68:71]
	v_mfma_f32_16x16x32_bf16 v[64:67], v[180:183], v[212:215], v[64:67]
	s_setprio 0
	s_barrier
; #define PG8_STAGE(bufoff, gbase, voff) do { _Pragma("unroll") for (int _i = 0; _i < 2; ++_i) \
;         __builtin_amdgcn_global_load_lds((const unsigned*)((const char*)(gbase) + (voff)[_i]), (PG8_LAS unsigned*)(lds + (bufoff) + ldsw + _i * 8192), 16, 0, 0); } while (0)
; #define PG8_LDA(dst, b, h) do { _Pragma("unroll") for (int m = 0; m < 4; ++m) _Pragma("unroll") for (int k = 0; k < 2; ++k) dst[m][k] = *(const PG8_LAS bf16x8*)(lds + PG8_SA(b, h) + aoff + m * 2048 + k * 1024); } while (0)
; #define PG8_MMA(ai, bj, At, Bt) do { __builtin_amdgcn_s_setprio(1); _Pragma("unroll") for (int m = 0; m < 4; ++m) _Pragma("unroll") for (int n = 0; n < 2; ++n) _Pragma("unroll") for (int k = 0; k < 2; ++k) \
;         acc[ai][bj][m][n] = __builtin_amdgcn_mfma_f32_16x16x32_bf16(Bt[n][k], At[m][k], acc[ai][bj][m][n], 0, 0, 0); __builtin_amdgcn_s_setprio(0); } while (0)
; #define PG8_WAIT_V(n) asm volatile("s_waitcnt vmcnt(" #n ")" ::: "memory")
; #define PG8_WAIT_L(n) asm volatile("s_waitcnt lgkmcnt(" #n ")" ::: "memory")
; #define PG8_BAR __builtin_amdgcn_s_barrier()
; #define PG8_SCHED __builtin_amdgcn_sched_barrier(0)
; template <class Epi, class Sched, bool ALIGN_EPI = false, bool SP2 = false>
; __device__ __forceinline__ void gemm_phase(PG8_LAS unsigned char* lds, const Gemm g, const Sched& S, const Epi& E) {
;     ...
;             PG8_LDA(At, 1, 1); PG8_STAGE(PG8_SB(1, 0), b3, voffB); PG8_STAGE(PG8_SB(1, 1), b3 + hstep, voffB); PG8_STAGE(PG8_SA(1, 0), a3, voffA);
;             PG8_WAIT_V(8); PG8_WAIT_L(0); PG8_BAR; PG8_MMA(1, 0, At, B0); PG8_MMA(1, 1, At, B1); PG8_BAR; PG8_SCHED;
	s_add_i32 s34, s64, s16
	v_lshl_add_u64 v[216:217], v[216:217], 0, s[22:23]
	s_mov_b32 m0, s34
	ds_read_b128 v[184:187], v153 offset:49152
	ds_read_b128 v[188:191], v153 offset:50176
	ds_read_b128 v[192:195], v153 offset:51200
	ds_read_b128 v[196:199], v153 offset:52224
	ds_read_b128 v[200:203], v153 offset:53248
	ds_read_b128 v[204:207], v153 offset:54272
	ds_read_b128 v[208:211], v153 offset:55296
	ds_read_b128 v[212:215], v153 offset:56320
	global_load_lds_dwordx4 v[216:217], off
	v_lshl_add_u64 v[216:217], v[218:219], 0, s[22:23]
	s_add_i32 m0, s34, 0x2000
	s_add_i32 s34, s65, s16
	global_load_lds_dwordx4 v[216:217], off
	v_lshl_add_u64 v[216:217], v[220:221], 0, s[22:23]
	s_mov_b32 m0, s34
	s_nop 0
	global_load_lds_dwordx4 v[216:217], off
	v_lshl_add_u64 v[216:217], v[222:223], 0, s[22:23]
	s_add_i32 m0, s34, 0x2000
	s_nop 0
	global_load_lds_dwordx4 v[216:217], off
	v_lshl_add_u64 v[216:217], v[224:225], 0, s[22:23]
	s_mov_b32 m0, s37
	s_nop 0
	global_load_lds_dwordx4 v[216:217], off
	v_lshl_add_u64 v[216:217], v[226:227], 0, s[22:23]
	s_mov_b32 m0, s38
	s_nop 0
	global_load_lds_dwordx4 v[216:217], off
	s_waitcnt vmcnt(8)
	s_waitcnt lgkmcnt(0)
	s_barrier
	s_setprio 1
	s_waitcnt lgkmcnt(0)
	v_mfma_f32_16x16x32_bf16 v[60:63], v[144:147], v[184:187], v[60:63]
	v_mfma_f32_16x16x32_bf16 v[56:59], v[160:163], v[184:187], v[56:59]
	v_mfma_f32_16x16x32_bf16 v[44:47], v[144:147], v[192:195], v[44:47]
	v_mfma_f32_16x16x32_bf16 v[40:43], v[160:163], v[192:195], v[40:43]
	v_mfma_f32_16x16x32_bf16 v[28:31], v[144:147], v[200:203], v[28:31]
	v_mfma_f32_16x16x32_bf16 v[24:27], v[160:163], v[200:203], v[24:27]
	v_mfma_f32_16x16x32_bf16 v[12:15], v[144:147], v[208:211], v[12:15]
	v_mfma_f32_16x16x32_bf16 v[8:11], v[160:163], v[208:211], v[8:11]
	v_mfma_f32_16x16x32_bf16 v[60:63], v[156:159], v[188:191], v[60:63]
	v_mfma_f32_16x16x32_bf16 v[56:59], v[164:167], v[188:191], v[56:59]
	v_mfma_f32_16x16x32_bf16 v[44:47], v[156:159], v[196:199], v[44:47]
	v_mfma_f32_16x16x32_bf16 v[40:43], v[164:167], v[196:199], v[40:43]
	v_mfma_f32_16x16x32_bf16 v[28:31], v[156:159], v[204:207], v[28:31]
	v_mfma_f32_16x16x32_bf16 v[24:27], v[164:167], v[204:207], v[24:27]
	v_mfma_f32_16x16x32_bf16 v[12:15], v[156:159], v[212:215], v[12:15]
	v_mfma_f32_16x16x32_bf16 v[8:11], v[164:167], v[212:215], v[8:11]
	s_setprio 0
	s_setprio 1
	v_mfma_f32_16x16x32_bf16 v[52:55], v[168:171], v[184:187], v[52:55]
	v_mfma_f32_16x16x32_bf16 v[48:51], v[176:179], v[184:187], v[48:51]
	v_mfma_f32_16x16x32_bf16 v[36:39], v[168:171], v[192:195], v[36:39]
	v_mfma_f32_16x16x32_bf16 v[32:35], v[176:179], v[192:195], v[32:35]
	v_mfma_f32_16x16x32_bf16 v[20:23], v[168:171], v[200:203], v[20:23]
	v_mfma_f32_16x16x32_bf16 v[16:19], v[176:179], v[200:203], v[16:19]
	v_mfma_f32_16x16x32_bf16 v[4:7], v[168:171], v[208:211], v[4:7]
	v_mfma_f32_16x16x32_bf16 v[0:3], v[176:179], v[208:211], v[0:3]
	v_mfma_f32_16x16x32_bf16 v[52:55], v[172:175], v[188:191], v[52:55]
	v_mfma_f32_16x16x32_bf16 v[48:51], v[180:183], v[188:191], v[48:51]
	v_mfma_f32_16x16x32_bf16 v[36:39], v[172:175], v[196:199], v[36:39]
	v_mfma_f32_16x16x32_bf16 v[32:35], v[180:183], v[196:199], v[32:35]
	v_mfma_f32_16x16x32_bf16 v[20:23], v[172:175], v[204:207], v[20:23]
	v_mfma_f32_16x16x32_bf16 v[16:19], v[180:183], v[204:207], v[16:19]
	v_mfma_f32_16x16x32_bf16 v[4:7], v[172:175], v[212:215], v[4:7]
	v_mfma_f32_16x16x32_bf16 v[0:3], v[180:183], v[212:215], v[0:3]
	s_setprio 0
	s_barrier
	s_add_u32 s30, s30, 0x100
	s_addc_u32 s31, s31, 0
	s_add_u32 s61, s61, 0x100
	s_addc_u32 s62, s62, 0
	s_cmp_ge_i32 s63, s40
	s_mov_b32 s34, s63
	s_cbranch_scc0 .LBB0_2386
	s_branch .Lpeel_x11

; #define PG8_STAGE(bufoff, gbase, voff) do { _Pragma("unroll") for (int _i = 0; _i < 2; ++_i) \
;         __builtin_amdgcn_global_load_lds((const unsigned*)((const char*)(gbase) + (voff)[_i]), (PG8_LAS unsigned*)(lds + (bufoff) + ldsw + _i * 8192), 16, 0, 0); } while (0)
; #define PG8_LDA(dst, b, h) do { _Pragma("unroll") for (int m = 0; m < 4; ++m) _Pragma("unroll") for (int k = 0; k < 2; ++k) dst[m][k] = *(const PG8_LAS bf16x8*)(lds + PG8_SA(b, h) + aoff + m * 2048 + k * 1024); } while (0)
; #define PG8_LDB(dst, b, h) do { _Pragma("unroll") for (int n = 0; n < 2; ++n) _Pragma("unroll") for (int k = 0; k < 2; ++k) dst[n][k] = *(const PG8_LAS bf16x8*)(lds + PG8_SB(b, h) + boff + n * 2048 + k * 1024); } while (0)
; #define PG8_MMA(ai, bj, At, Bt) do { __builtin_amdgcn_s_setprio(1); _Pragma("unroll") for (int m = 0; m < 4; ++m) _Pragma("unroll") for (int n = 0; n < 2; ++n) _Pragma("unroll") for (int k = 0; k < 2; ++k) \
;         acc[ai][bj][m][n] = __builtin_amdgcn_mfma_f32_16x16x32_bf16(Bt[n][k], At[m][k], acc[ai][bj][m][n], 0, 0, 0); __builtin_amdgcn_s_setprio(0); } while (0)
; #define PG8_WAIT_V(n) asm volatile("s_waitcnt vmcnt(" #n ")" ::: "memory")
; #define PG8_WAIT_L(n) asm volatile("s_waitcnt lgkmcnt(" #n ")" ::: "memory")
; #define PG8_BAR __builtin_amdgcn_s_barrier()
; #define PG8_SCHED __builtin_amdgcn_sched_barrier(0)
; template <class Epi, class Sched, bool ALIGN_EPI = false, bool SP2 = false>
; __device__ __forceinline__ void gemm_phase(PG8_LAS unsigned char* lds, const Gemm g, const Sched& S, const Epi& E) {
;     ...
;             const char* a1 = cA + (size_t)(t + 1) * kstep;
;             const char* a2 = last ? nA : cA + (size_t)(t + 2) * kstep; const char* b2 = last ? nB : cB + (size_t)(t + 2) * kstep;
;             const char* a3 = a2 + kstep; const char* b3 = b2 + kstep;
;             if (last && has_next) S.a_ready(nxt);
;             if constexpr (SP2) {
;             PG8_LDB(B0, 0, 0); PG8_LDB(B1, 0, 1); PG8_SCHED; PG8_LDA(At, 0, 0); PG8_STAGE(PG8_SA(1, 1), a1 + hstep, voffA);
;             PG8_WAIT_V(8); PG8_WAIT_L(0); PG8_BAR; PG8_MMA(0, 0, At, B0); PG8_MMA(0, 1, At, B1); PG8_BAR; PG8_SCHED;
;             PG8_LDA(At, 0, 1); PG8_STAGE(PG8_SB(0, 0), b2, voffB); PG8_STAGE(PG8_SB(0, 1), b2 + hstep, voffB); PG8_STAGE(PG8_SA(0, 0), a2, voffA);
.LBB0_2479:
	s_andn2_b64 vcc, exec, s[20:21]
	s_waitcnt vmcnt(0)
	s_cbranch_vccnz .LBB0_2482
	s_add_u32 s26, s26, 0x80
	s_addc_u32 s27, s27, 0
	s_add_u32 s60, s28, 0x100
	s_addc_u32 s61, s29, 0
	s_mov_b32 s28, 0
	ds_read_b128 v[154:157], v149
	ds_read_b128 v[158:161], v149 offset:1024
	ds_read_b128 v[162:165], v149 offset:2048
	ds_read_b128 v[166:169], v149 offset:3072
	ds_read_b128 v[170:173], v150
	ds_read_b128 v[174:177], v150 offset:1024
	ds_read_b128 v[178:181], v150 offset:2048
	ds_read_b128 v[182:185], v150 offset:3072
	s_add_i32 s62, s28, 2
	s_add_u32 s63, s26, 0x80
	s_addc_u32 s29, s27, 0
	s_cmp_eq_u32 s39, s28
	s_cselect_b32 s28, s0, s63
	s_cselect_b32 s29, s1, s29
	s_cselect_b32 s65, s25, s61
	s_cselect_b32 s64, s24, s60
	v_lshl_add_u64 v[144:145], s[26:27], 0, v[136:137]
	s_add_i32 m0, s30, 0xc000
	ds_read_b128 v[186:189], v151
	ds_read_b128 v[190:193], v151 offset:1024
	ds_read_b128 v[194:197], v151 offset:2048
	ds_read_b128 v[198:201], v151 offset:3072
	ds_read_b128 v[202:205], v151 offset:4096
	ds_read_b128 v[206:209], v151 offset:5120
	ds_read_b128 v[210:213], v151 offset:6144
	ds_read_b128 v[214:217], v151 offset:7168
	global_load_lds_dwordx4 v[144:145], off
	v_lshl_add_u64 v[144:145], s[26:27], 0, v[138:139]
	s_add_i32 m0, s30, 0xe000
	s_nop 0
	global_load_lds_dwordx4 v[144:145], off
	s_waitcnt vmcnt(8)
	s_waitcnt lgkmcnt(0)
	s_barrier
	s_setprio 1
	s_waitcnt lgkmcnt(0)
	v_mfma_f32_16x16x32_bf16 v[116:119], v[154:157], v[186:189], 0
	v_mfma_f32_16x16x32_bf16 v[112:115], v[162:165], v[186:189], 0
	v_mfma_f32_16x16x32_bf16 v[100:103], v[154:157], v[194:197], 0
	v_mfma_f32_16x16x32_bf16 v[96:99], v[162:165], v[194:197], 0
	v_mfma_f32_16x16x32_bf16 v[84:87], v[154:157], v[202:205], 0
	v_mfma_f32_16x16x32_bf16 v[80:83], v[162:165], v[202:205], 0
	v_mfma_f32_16x16x32_bf16 v[68:71], v[154:157], v[210:213], 0
	v_mfma_f32_16x16x32_bf16 v[64:67], v[162:165], v[210:213], 0
	v_mfma_f32_16x16x32_bf16 v[116:119], v[158:161], v[190:193], v[116:119]
	v_mfma_f32_16x16x32_bf16 v[112:115], v[166:169], v[190:193], v[112:115]
	v_mfma_f32_16x16x32_bf16 v[100:103], v[158:161], v[198:201], v[100:103]
	v_mfma_f32_16x16x32_bf16 v[96:99], v[166:169], v[198:201], v[96:99]
	v_mfma_f32_16x16x32_bf16 v[84:87], v[158:161], v[206:209], v[84:87]
	v_mfma_f32_16x16x32_bf16 v[80:83], v[166:169], v[206:209], v[80:83]
	v_mfma_f32_16x16x32_bf16 v[68:71], v[158:161], v[214:217], v[68:71]
	v_mfma_f32_16x16x32_bf16 v[64:67], v[166:169], v[214:217], v[64:67]
	s_setprio 0
	s_setprio 1
	v_mfma_f32_16x16x32_bf16 v[124:127], v[170:173], v[186:189], 0
	v_mfma_f32_16x16x32_bf16 v[120:123], v[178:181], v[186:189], 0
	v_mfma_f32_16x16x32_bf16 v[108:111], v[170:173], v[194:197], 0
	v_mfma_f32_16x16x32_bf16 v[104:107], v[178:181], v[194:197], 0
	v_mfma_f32_16x16x32_bf16 v[92:95], v[170:173], v[202:205], 0
	v_mfma_f32_16x16x32_bf16 v[88:91], v[178:181], v[202:205], 0
	v_mfma_f32_16x16x32_bf16 v[76:79], v[170:173], v[210:213], 0
	v_mfma_f32_16x16x32_bf16 v[72:75], v[178:181], v[210:213], 0
	v_mfma_f32_16x16x32_bf16 v[124:127], v[174:177], v[190:193], v[124:127]
	v_mfma_f32_16x16x32_bf16 v[120:123], v[182:185], v[190:193], v[120:123]
	v_mfma_f32_16x16x32_bf16 v[108:111], v[174:177], v[198:201], v[108:111]
	v_mfma_f32_16x16x32_bf16 v[104:107], v[182:185], v[198:201], v[104:107]
	v_mfma_f32_16x16x32_bf16 v[92:95], v[174:177], v[206:209], v[92:95]
	v_mfma_f32_16x16x32_bf16 v[88:91], v[182:185], v[206:209], v[88:91]
	v_mfma_f32_16x16x32_bf16 v[76:79], v[174:177], v[214:217], v[76:79]
	v_mfma_f32_16x16x32_bf16 v[72:75], v[182:185], v[214:217], v[72:75]
	s_setprio 0
	s_barrier
	s_add_i32 s63, s44, s16
	v_lshl_add_u64 v[144:145], s[64:65], 0, v[132:133]
	s_mov_b32 m0, s63
	ds_read_b128 v[186:189], v151 offset:16384
	ds_read_b128 v[190:193], v151 offset:17408
	ds_read_b128 v[194:197], v151 offset:18432
	ds_read_b128 v[198:201], v151 offset:19456
	ds_read_b128 v[202:205], v151 offset:20480
	ds_read_b128 v[206:209], v151 offset:21504
	ds_read_b128 v[210:213], v151 offset:22528
	ds_read_b128 v[214:217], v151 offset:23552
	global_load_lds_dwordx4 v[144:145], off
	s_add_i32 m0, s63, 0x2000
	v_lshl_add_u64 v[218:219], s[64:65], 0, v[128:129]
	s_add_u32 s64, s64, s8
	s_addc_u32 s65, s65, s9
	s_add_i32 s63, s45, s16
	global_load_lds_dwordx4 v[218:219], off
	v_lshl_add_u64 v[220:221], s[64:65], 0, v[132:133]
	s_mov_b32 m0, s63
	v_lshl_add_u64 v[222:223], s[64:65], 0, v[128:129]
	global_load_lds_dwordx4 v[220:221], off
	s_add_i32 m0, s63, 0x2000
	v_lshl_add_u64 v[224:225], s[28:29], 0, v[134:135]
	global_load_lds_dwordx4 v[222:223], off
	s_mov_b32 m0, s30
	v_lshl_add_u64 v[226:227], s[28:29], 0, v[130:131]
	global_load_lds_dwordx4 v[224:225], off
	s_mov_b32 m0, s31
	s_nop 0
	global_load_lds_dwordx4 v[226:227], off
	s_waitcnt vmcnt(8)
	s_waitcnt lgkmcnt(0)
	s_barrier
; #define PG8_STAGE(bufoff, gbase, voff) do { _Pragma("unroll") for (int _i = 0; _i < 2; ++_i) \
;         __builtin_amdgcn_global_load_lds((const unsigned*)((const char*)(gbase) + (voff)[_i]), (PG8_LAS unsigned*)(lds + (bufoff) + ldsw + _i * 8192), 16, 0, 0); } while (0)
; #define PG8_LDA(dst, b, h) do { _Pragma("unroll") for (int m = 0; m < 4; ++m) _Pragma("unroll") for (int k = 0; k < 2; ++k) dst[m][k] = *(const PG8_LAS bf16x8*)(lds + PG8_SA(b, h) + aoff + m * 2048 + k * 1024); } while (0)
; #define PG8_LDB(dst, b, h) do { _Pragma("unroll") for (int n = 0; n < 2; ++n) _Pragma("unroll") for (int k = 0; k < 2; ++k) dst[n][k] = *(const PG8_LAS bf16x8*)(lds + PG8_SB(b, h) + boff + n * 2048 + k * 1024); } while (0)
; #define PG8_MMA(ai, bj, At, Bt) do { __builtin_amdgcn_s_setprio(1); _Pragma("unroll") for (int m = 0; m < 4; ++m) _Pragma("unroll") for (int n = 0; n < 2; ++n) _Pragma("unroll") for (int k = 0; k < 2; ++k) \
;         acc[ai][bj][m][n] = __builtin_amdgcn_mfma_f32_16x16x32_bf16(Bt[n][k], At[m][k], acc[ai][bj][m][n], 0, 0, 0); __builtin_amdgcn_s_setprio(0); } while (0)
; #define PG8_WAIT_V(n) asm volatile("s_waitcnt vmcnt(" #n ")" ::: "memory")
; #define PG8_WAIT_L(n) asm volatile("s_waitcnt lgkmcnt(" #n ")" ::: "memory")
; #define PG8_BAR __builtin_amdgcn_s_barrier()
; #define PG8_SCHED __builtin_amdgcn_sched_barrier(0)
; template <class Epi, class Sched, bool ALIGN_EPI = false, bool SP2 = false>
; __device__ __forceinline__ void gemm_phase(PG8_LAS unsigned char* lds, const Gemm g, const Sched& S, const Epi& E) {
;     ...
;             PG8_WAIT_V(8); PG8_WAIT_L(0); PG8_BAR; PG8_MMA(1, 0, At, B0); PG8_MMA(1, 1, At, B1); PG8_BAR; PG8_SCHED;
;             PG8_LDB(B0, 1, 0); PG8_LDB(B1, 1, 1); PG8_SCHED; PG8_LDA(At, 1, 0); PG8_STAGE(PG8_SA(0, 1), a2 + hstep, voffA);
;             PG8_WAIT_V(8); PG8_WAIT_L(0); PG8_BAR; PG8_MMA(0, 0, At, B0); PG8_MMA(0, 1, At, B1); PG8_BAR; PG8_SCHED;
	s_setprio 1
	s_waitcnt lgkmcnt(0)
	v_mfma_f32_16x16x32_bf16 v[52:55], v[154:157], v[186:189], 0
	v_mfma_f32_16x16x32_bf16 v[48:51], v[162:165], v[186:189], 0
	v_mfma_f32_16x16x32_bf16 v[36:39], v[154:157], v[194:197], 0
	v_mfma_f32_16x16x32_bf16 v[32:35], v[162:165], v[194:197], 0
	v_mfma_f32_16x16x32_bf16 v[20:23], v[154:157], v[202:205], 0
	v_mfma_f32_16x16x32_bf16 v[16:19], v[162:165], v[202:205], 0
	v_mfma_f32_16x16x32_bf16 v[4:7], v[154:157], v[210:213], 0
	v_mfma_f32_16x16x32_bf16 v[0:3], v[162:165], v[210:213], 0
	v_mfma_f32_16x16x32_bf16 v[52:55], v[158:161], v[190:193], v[52:55]
	v_mfma_f32_16x16x32_bf16 v[48:51], v[166:169], v[190:193], v[48:51]
	v_mfma_f32_16x16x32_bf16 v[36:39], v[158:161], v[198:201], v[36:39]
	v_mfma_f32_16x16x32_bf16 v[32:35], v[166:169], v[198:201], v[32:35]
	v_mfma_f32_16x16x32_bf16 v[20:23], v[158:161], v[206:209], v[20:23]
	v_mfma_f32_16x16x32_bf16 v[16:19], v[166:169], v[206:209], v[16:19]
	v_mfma_f32_16x16x32_bf16 v[4:7], v[158:161], v[214:217], v[4:7]
	v_mfma_f32_16x16x32_bf16 v[0:3], v[166:169], v[214:217], v[0:3]
	s_setprio 0
	s_setprio 1
	v_mfma_f32_16x16x32_bf16 v[60:63], v[170:173], v[186:189], 0
	v_mfma_f32_16x16x32_bf16 v[56:59], v[178:181], v[186:189], 0
	v_mfma_f32_16x16x32_bf16 v[44:47], v[170:173], v[194:197], 0
	v_mfma_f32_16x16x32_bf16 v[40:43], v[178:181], v[194:197], 0
	v_mfma_f32_16x16x32_bf16 v[28:31], v[170:173], v[202:205], 0
	v_mfma_f32_16x16x32_bf16 v[24:27], v[178:181], v[202:205], 0
	v_mfma_f32_16x16x32_bf16 v[12:15], v[170:173], v[210:213], 0
	v_mfma_f32_16x16x32_bf16 v[8:11], v[178:181], v[210:213], 0
	v_mfma_f32_16x16x32_bf16 v[60:63], v[174:177], v[190:193], v[60:63]
	v_mfma_f32_16x16x32_bf16 v[56:59], v[182:185], v[190:193], v[56:59]
	v_mfma_f32_16x16x32_bf16 v[44:47], v[174:177], v[198:201], v[44:47]
	v_mfma_f32_16x16x32_bf16 v[40:43], v[182:185], v[198:201], v[40:43]
	v_mfma_f32_16x16x32_bf16 v[28:31], v[174:177], v[206:209], v[28:31]
	v_mfma_f32_16x16x32_bf16 v[24:27], v[182:185], v[206:209], v[24:27]
	v_mfma_f32_16x16x32_bf16 v[12:15], v[174:177], v[214:217], v[12:15]
	v_mfma_f32_16x16x32_bf16 v[8:11], v[182:185], v[214:217], v[8:11]
	s_setprio 0
	s_barrier
	s_add_i32 s63, 0, 0x18000
	v_add_u32_e32 v153, s63, v147
	s_add_i32 s64, 0, 0x1c000
	ds_read_b128 v[154:157], v153
	ds_read_b128 v[158:161], v153 offset:1024
	ds_read_b128 v[162:165], v153 offset:2048
	ds_read_b128 v[166:169], v153 offset:3072
	v_add_u32_e32 v153, s64, v147
	ds_read_b128 v[170:173], v153
	ds_read_b128 v[174:177], v153 offset:1024
	ds_read_b128 v[178:181], v153 offset:2048
	ds_read_b128 v[182:185], v153 offset:3072
	s_add_u32 s28, s28, s8
	s_addc_u32 s29, s29, s9
	s_mov_b32 m0, s33
	v_lshl_add_u64 v[228:229], s[28:29], 0, v[134:135]
	ds_read_b128 v[186:189], v151 offset:32768
	ds_read_b128 v[190:193], v151 offset:33792
	ds_read_b128 v[194:197], v151 offset:34816
	ds_read_b128 v[198:201], v151 offset:35840
	ds_read_b128 v[202:205], v151 offset:36864
	ds_read_b128 v[206:209], v151 offset:37888
	ds_read_b128 v[210:213], v151 offset:38912
	ds_read_b128 v[214:217], v151 offset:39936
	global_load_lds_dwordx4 v[228:229], off
	v_lshl_add_u64 v[228:229], s[28:29], 0, v[130:131]
	s_mov_b32 m0, s34
	s_nop 0
	global_load_lds_dwordx4 v[228:229], off
	s_waitcnt vmcnt(8)
	s_waitcnt lgkmcnt(0)
	s_barrier
	s_setprio 1
	s_waitcnt lgkmcnt(0)
	v_mfma_f32_16x16x32_bf16 v[116:119], v[154:157], v[186:189], v[116:119]
	v_mfma_f32_16x16x32_bf16 v[112:115], v[162:165], v[186:189], v[112:115]
	v_mfma_f32_16x16x32_bf16 v[100:103], v[154:157], v[194:197], v[100:103]
	v_mfma_f32_16x16x32_bf16 v[96:99], v[162:165], v[194:197], v[96:99]
	v_mfma_f32_16x16x32_bf16 v[84:87], v[154:157], v[202:205], v[84:87]
	v_mfma_f32_16x16x32_bf16 v[80:83], v[162:165], v[202:205], v[80:83]
	v_mfma_f32_16x16x32_bf16 v[68:71], v[154:157], v[210:213], v[68:71]
	v_mfma_f32_16x16x32_bf16 v[64:67], v[162:165], v[210:213], v[64:67]
	v_mfma_f32_16x16x32_bf16 v[116:119], v[158:161], v[190:193], v[116:119]
	v_mfma_f32_16x16x32_bf16 v[112:115], v[166:169], v[190:193], v[112:115]
	v_mfma_f32_16x16x32_bf16 v[100:103], v[158:161], v[198:201], v[100:103]
	v_mfma_f32_16x16x32_bf16 v[96:99], v[166:169], v[198:201], v[96:99]
	v_mfma_f32_16x16x32_bf16 v[84:87], v[158:161], v[206:209], v[84:87]
	v_mfma_f32_16x16x32_bf16 v[80:83], v[166:169], v[206:209], v[80:83]
	v_mfma_f32_16x16x32_bf16 v[68:71], v[158:161], v[214:217], v[68:71]
	v_mfma_f32_16x16x32_bf16 v[64:67], v[166:169], v[214:217], v[64:67]
	s_setprio 0
	s_setprio 1
	v_mfma_f32_16x16x32_bf16 v[124:127], v[170:173], v[186:189], v[124:127]
	v_mfma_f32_16x16x32_bf16 v[120:123], v[178:181], v[186:189], v[120:123]
	v_mfma_f32_16x16x32_bf16 v[108:111], v[170:173], v[194:197], v[108:111]
	v_mfma_f32_16x16x32_bf16 v[104:107], v[178:181], v[194:197], v[104:107]
	v_mfma_f32_16x16x32_bf16 v[92:95], v[170:173], v[202:205], v[92:95]
	v_mfma_f32_16x16x32_bf16 v[88:91], v[178:181], v[202:205], v[88:91]
	v_mfma_f32_16x16x32_bf16 v[76:79], v[170:173], v[210:213], v[76:79]
	v_mfma_f32_16x16x32_bf16 v[72:75], v[178:181], v[210:213], v[72:75]
	v_mfma_f32_16x16x32_bf16 v[124:127], v[174:177], v[190:193], v[124:127]
	v_mfma_f32_16x16x32_bf16 v[120:123], v[182:185], v[190:193], v[120:123]
	v_mfma_f32_16x16x32_bf16 v[108:111], v[174:177], v[198:201], v[108:111]
	v_mfma_f32_16x16x32_bf16 v[104:107], v[182:185], v[198:201], v[104:107]
	v_mfma_f32_16x16x32_bf16 v[92:95], v[174:177], v[206:209], v[92:95]
	v_mfma_f32_16x16x32_bf16 v[88:91], v[182:185], v[206:209], v[88:91]
	v_mfma_f32_16x16x32_bf16 v[76:79], v[174:177], v[214:217], v[76:79]
	v_mfma_f32_16x16x32_bf16 v[72:75], v[182:185], v[214:217], v[72:75]
	s_setprio 0
	s_barrier
; #define PG8_STAGE(bufoff, gbase, voff) do { _Pragma("unroll") for (int _i = 0; _i < 2; ++_i) \
;         __builtin_amdgcn_global_load_lds((const unsigned*)((const char*)(gbase) + (voff)[_i]), (PG8_LAS unsigned*)(lds + (bufoff) + ldsw + _i * 8192), 16, 0, 0); } while (0)
; #define PG8_LDA(dst, b, h) do { _Pragma("unroll") for (int m = 0; m < 4; ++m) _Pragma("unroll") for (int k = 0; k < 2; ++k) dst[m][k] = *(const PG8_LAS bf16x8*)(lds + PG8_SA(b, h) + aoff + m * 2048 + k * 1024); } while (0)
; #define PG8_MMA(ai, bj, At, Bt) do { __builtin_amdgcn_s_setprio(1); _Pragma("unroll") for (int m = 0; m < 4; ++m) _Pragma("unroll") for (int n = 0; n < 2; ++n) _Pragma("unroll") for (int k = 0; k < 2; ++k) \
;         acc[ai][bj][m][n] = __builtin_amdgcn_mfma_f32_16x16x32_bf16(Bt[n][k], At[m][k], acc[ai][bj][m][n], 0, 0, 0); __builtin_amdgcn_s_setprio(0); } while (0)
; #define PG8_WAIT_V(n) asm volatile("s_waitcnt vmcnt(" #n ")" ::: "memory")
; #define PG8_WAIT_L(n) asm volatile("s_waitcnt lgkmcnt(" #n ")" ::: "memory")
; #define PG8_BAR __builtin_amdgcn_s_barrier()
; #define PG8_SCHED __builtin_amdgcn_sched_barrier(0)
; template <class Epi, class Sched, bool ALIGN_EPI = false, bool SP2 = false>
; __device__ __forceinline__ void gemm_phase(PG8_LAS unsigned char* lds, const Gemm g, const Sched& S, const Epi& E) {
;     ...
;             PG8_LDA(At, 1, 1); PG8_STAGE(PG8_SB(1, 0), b3, voffB); PG8_STAGE(PG8_SB(1, 1), b3 + hstep, voffB); PG8_STAGE(PG8_SA(1, 0), a3, voffA);
;             PG8_WAIT_V(8); PG8_WAIT_L(0); PG8_BAR; PG8_MMA(1, 0, At, B0); PG8_MMA(1, 1, At, B1); PG8_BAR; PG8_SCHED;
	s_add_i32 s28, s63, s16
	v_lshl_add_u64 v[144:145], v[144:145], 0, s[14:15]
	s_mov_b32 m0, s28
	ds_read_b128 v[186:189], v151 offset:49152
	ds_read_b128 v[190:193], v151 offset:50176
	ds_read_b128 v[194:197], v151 offset:51200
	ds_read_b128 v[198:201], v151 offset:52224
	ds_read_b128 v[202:205], v151 offset:53248
	ds_read_b128 v[206:209], v151 offset:54272
	ds_read_b128 v[210:213], v151 offset:55296
	ds_read_b128 v[214:217], v151 offset:56320
	global_load_lds_dwordx4 v[144:145], off
	v_lshl_add_u64 v[144:145], v[218:219], 0, s[14:15]
	s_add_i32 m0, s28, 0x2000
	s_add_i32 s28, s64, s16
	global_load_lds_dwordx4 v[144:145], off
	v_lshl_add_u64 v[144:145], v[220:221], 0, s[14:15]
	s_mov_b32 m0, s28
	s_nop 0
	global_load_lds_dwordx4 v[144:145], off
	v_lshl_add_u64 v[144:145], v[222:223], 0, s[14:15]
	s_add_i32 m0, s28, 0x2000
	s_nop 0
	global_load_lds_dwordx4 v[144:145], off
	v_lshl_add_u64 v[144:145], v[224:225], 0, s[14:15]
	s_mov_b32 m0, s36
	s_nop 0
	global_load_lds_dwordx4 v[144:145], off
	v_lshl_add_u64 v[144:145], v[226:227], 0, s[14:15]
	s_mov_b32 m0, s37
	s_nop 0
	global_load_lds_dwordx4 v[144:145], off
	s_waitcnt vmcnt(8)
	s_waitcnt lgkmcnt(0)
	s_barrier
	s_setprio 1
	s_waitcnt lgkmcnt(0)
	v_mfma_f32_16x16x32_bf16 v[52:55], v[154:157], v[186:189], v[52:55]
	v_mfma_f32_16x16x32_bf16 v[48:51], v[162:165], v[186:189], v[48:51]
	v_mfma_f32_16x16x32_bf16 v[36:39], v[154:157], v[194:197], v[36:39]
	v_mfma_f32_16x16x32_bf16 v[32:35], v[162:165], v[194:197], v[32:35]
	v_mfma_f32_16x16x32_bf16 v[20:23], v[154:157], v[202:205], v[20:23]
	v_mfma_f32_16x16x32_bf16 v[16:19], v[162:165], v[202:205], v[16:19]
	v_mfma_f32_16x16x32_bf16 v[4:7], v[154:157], v[210:213], v[4:7]
	v_mfma_f32_16x16x32_bf16 v[0:3], v[162:165], v[210:213], v[0:3]
	v_mfma_f32_16x16x32_bf16 v[52:55], v[158:161], v[190:193], v[52:55]
	v_mfma_f32_16x16x32_bf16 v[48:51], v[166:169], v[190:193], v[48:51]
	v_mfma_f32_16x16x32_bf16 v[36:39], v[158:161], v[198:201], v[36:39]
	v_mfma_f32_16x16x32_bf16 v[32:35], v[166:169], v[198:201], v[32:35]
	v_mfma_f32_16x16x32_bf16 v[20:23], v[158:161], v[206:209], v[20:23]
	v_mfma_f32_16x16x32_bf16 v[16:19], v[166:169], v[206:209], v[16:19]
	v_mfma_f32_16x16x32_bf16 v[4:7], v[158:161], v[214:217], v[4:7]
	v_mfma_f32_16x16x32_bf16 v[0:3], v[166:169], v[214:217], v[0:3]
	s_setprio 0
	s_setprio 1
	v_mfma_f32_16x16x32_bf16 v[60:63], v[170:173], v[186:189], v[60:63]
	v_mfma_f32_16x16x32_bf16 v[56:59], v[178:181], v[186:189], v[56:59]
	v_mfma_f32_16x16x32_bf16 v[44:47], v[170:173], v[194:197], v[44:47]
	v_mfma_f32_16x16x32_bf16 v[40:43], v[178:181], v[194:197], v[40:43]
	v_mfma_f32_16x16x32_bf16 v[28:31], v[170:173], v[202:205], v[28:31]
	v_mfma_f32_16x16x32_bf16 v[24:27], v[178:181], v[202:205], v[24:27]
	v_mfma_f32_16x16x32_bf16 v[12:15], v[170:173], v[210:213], v[12:15]
	v_mfma_f32_16x16x32_bf16 v[8:11], v[178:181], v[210:213], v[8:11]
	v_mfma_f32_16x16x32_bf16 v[60:63], v[174:177], v[190:193], v[60:63]
	v_mfma_f32_16x16x32_bf16 v[56:59], v[182:185], v[190:193], v[56:59]
	v_mfma_f32_16x16x32_bf16 v[44:47], v[174:177], v[198:201], v[44:47]
	v_mfma_f32_16x16x32_bf16 v[40:43], v[182:185], v[198:201], v[40:43]
	v_mfma_f32_16x16x32_bf16 v[28:31], v[174:177], v[206:209], v[28:31]
	v_mfma_f32_16x16x32_bf16 v[24:27], v[182:185], v[206:209], v[24:27]
	v_mfma_f32_16x16x32_bf16 v[12:15], v[174:177], v[214:217], v[12:15]
	v_mfma_f32_16x16x32_bf16 v[8:11], v[182:185], v[214:217], v[8:11]
	s_setprio 0
	s_barrier
	s_add_u32 s26, s26, 0x100
	s_addc_u32 s27, s27, 0
	s_add_u32 s60, s60, 0x100
	s_addc_u32 s61, s61, 0
	s_cmp_ge_i32 s62, s38
	s_mov_b32 s28, s62
	s_cbranch_scc0 .LBB0_2481
	s_branch .Lpeel_x12

; #define PG8_STAGE(bufoff, gbase, voff) do { _Pragma("unroll") for (int _i = 0; _i < 2; ++_i) \
;         __builtin_amdgcn_global_load_lds((const unsigned*)((const char*)(gbase) + (voff)[_i]), (PG8_LAS unsigned*)(lds + (bufoff) + ldsw + _i * 8192), 16, 0, 0); } while (0)
; #define PG8_LDA(dst, b, h) do { _Pragma("unroll") for (int m = 0; m < 4; ++m) _Pragma("unroll") for (int k = 0; k < 2; ++k) dst[m][k] = *(const PG8_LAS bf16x8*)(lds + PG8_SA(b, h) + aoff + m * 2048 + k * 1024); } while (0)
; #define PG8_LDB(dst, b, h) do { _Pragma("unroll") for (int n = 0; n < 2; ++n) _Pragma("unroll") for (int k = 0; k < 2; ++k) dst[n][k] = *(const PG8_LAS bf16x8*)(lds + PG8_SB(b, h) + boff + n * 2048 + k * 1024); } while (0)
; #define PG8_MMA(ai, bj, At, Bt) do { __builtin_amdgcn_s_setprio(1); _Pragma("unroll") for (int m = 0; m < 4; ++m) _Pragma("unroll") for (int n = 0; n < 2; ++n) _Pragma("unroll") for (int k = 0; k < 2; ++k) \
;         acc[ai][bj][m][n] = __builtin_amdgcn_mfma_f32_16x16x32_bf16(Bt[n][k], At[m][k], acc[ai][bj][m][n], 0, 0, 0); __builtin_amdgcn_s_setprio(0); } while (0)
; #define PG8_WAIT_V(n) asm volatile("s_waitcnt vmcnt(" #n ")" ::: "memory")
; #define PG8_WAIT_L(n) asm volatile("s_waitcnt lgkmcnt(" #n ")" ::: "memory")
; #define PG8_BAR __builtin_amdgcn_s_barrier()
; #define PG8_SCHED __builtin_amdgcn_sched_barrier(0)
; template <class Epi, class Sched, bool ALIGN_EPI = false, bool SP2 = false>
; __device__ __forceinline__ void gemm_phase(PG8_LAS unsigned char* lds, const Gemm g, const Sched& S, const Epi& E) {
;     ...
;         for (int t = 0; t < nt; t += 2) {
;             const bool last = (t == nt - 2);
;             const char* a1 = cA + (size_t)(t + 1) * kstep;
;             const char* a2 = last ? nA : cA + (size_t)(t + 2) * kstep; const char* b2 = last ? nB : cB + (size_t)(t + 2) * kstep;
;             const char* a3 = a2 + kstep; const char* b3 = b2 + kstep;
;             if (last && has_next) S.a_ready(nxt);
;             if constexpr (SP2) {
;             PG8_LDB(B0, 0, 0); PG8_LDB(B1, 0, 1); PG8_SCHED; PG8_LDA(At, 0, 0); PG8_STAGE(PG8_SA(1, 1), a1 + hstep, voffA);
;             PG8_WAIT_V(8); PG8_WAIT_L(0); PG8_BAR; PG8_MMA(0, 0, At, B0); PG8_MMA(0, 1, At, B1); PG8_BAR; PG8_SCHED;
;             PG8_LDA(At, 0, 1); PG8_STAGE(PG8_SB(0, 0), b2, voffB); PG8_STAGE(PG8_SB(0, 1), b2 + hstep, voffB); PG8_STAGE(PG8_SA(0, 0), a2, voffA);
.LBB0_2573:
	v_mov_b32_e32 v151, 0
	s_andn2_b64 vcc, exec, s[24:25]
	v_mov_b32_e32 v150, 0
	v_mov_b32_e32 v155, 0
	v_mov_b32_e32 v154, 0
	v_mov_b32_e32 v153, 0
	v_mov_b32_e32 v152, 0
	v_mov_b32_e32 v149, 0
	v_mov_b32_e32 v148, 0
	s_waitcnt vmcnt(0)
	v_mov_b32_e32 v145, 0
	v_mov_b32_e32 v144, 0
	v_mov_b32_e32 v147, 0
	v_mov_b32_e32 v146, 0
	s_waitcnt lgkmcnt(0)
	s_cbranch_vccnz .LBB0_2577
	s_add_u32 s30, s30, 0x80
	s_addc_u32 s31, s31, 0
	s_add_u32 s61, s34, 0x100
	s_addc_u32 s62, s35, 0
	s_mov_b32 s34, 0
	ds_read_b128 v[144:147], v159
	ds_read_b128 v[148:151], v159 offset:1024
	ds_read_b128 v[152:155], v159 offset:2048
	ds_read_b128 v[164:167], v159 offset:3072
	ds_read_b128 v[168:171], v160
	ds_read_b128 v[172:175], v160 offset:1024
	ds_read_b128 v[176:179], v160 offset:2048
	ds_read_b128 v[180:183], v160 offset:3072
	s_add_i32 s63, s34, 2
	s_add_u32 s64, s30, 0x80
	s_addc_u32 s35, s31, 0
	s_cmp_eq_u32 s41, s34
	s_cselect_b32 s34, s0, s64
	s_cselect_b32 s35, s1, s35
	s_cselect_b32 s65, s29, s62
	s_cselect_b32 s64, s28, s61
	v_lshl_add_u64 v[216:217], s[30:31], 0, v[136:137]
	s_add_i32 m0, s17, 0xc000
	ds_read_b128 v[184:187], v161
	ds_read_b128 v[188:191], v161 offset:1024
	ds_read_b128 v[192:195], v161 offset:2048
	ds_read_b128 v[196:199], v161 offset:3072
	ds_read_b128 v[200:203], v161 offset:4096
	ds_read_b128 v[204:207], v161 offset:5120
	ds_read_b128 v[208:211], v161 offset:6144
	ds_read_b128 v[212:215], v161 offset:7168
	global_load_lds_dwordx4 v[216:217], off
	v_lshl_add_u64 v[216:217], s[30:31], 0, v[138:139]
	s_add_i32 m0, s17, 0xe000
	s_nop 0
	global_load_lds_dwordx4 v[216:217], off
	s_waitcnt vmcnt(8)
	s_waitcnt lgkmcnt(0)
	s_barrier
	s_setprio 1
	s_waitcnt lgkmcnt(0)
	v_mfma_f32_16x16x32_bf16 v[124:127], v[144:147], v[184:187], 0
	v_mfma_f32_16x16x32_bf16 v[120:123], v[152:155], v[184:187], 0
	v_mfma_f32_16x16x32_bf16 v[116:119], v[144:147], v[192:195], 0
	v_mfma_f32_16x16x32_bf16 v[112:115], v[152:155], v[192:195], 0
	v_mfma_f32_16x16x32_bf16 v[104:107], v[144:147], v[200:203], 0
	v_mfma_f32_16x16x32_bf16 v[96:99], v[152:155], v[200:203], 0
	v_mfma_f32_16x16x32_bf16 v[88:91], v[144:147], v[208:211], 0
	v_mfma_f32_16x16x32_bf16 v[80:83], v[152:155], v[208:211], 0
	v_mfma_f32_16x16x32_bf16 v[124:127], v[148:151], v[188:191], v[124:127]
	v_mfma_f32_16x16x32_bf16 v[120:123], v[164:167], v[188:191], v[120:123]
	v_mfma_f32_16x16x32_bf16 v[116:119], v[148:151], v[196:199], v[116:119]
	v_mfma_f32_16x16x32_bf16 v[112:115], v[164:167], v[196:199], v[112:115]
	v_mfma_f32_16x16x32_bf16 v[104:107], v[148:151], v[204:207], v[104:107]
	v_mfma_f32_16x16x32_bf16 v[96:99], v[164:167], v[204:207], v[96:99]
	v_mfma_f32_16x16x32_bf16 v[88:91], v[148:151], v[212:215], v[88:91]
	v_mfma_f32_16x16x32_bf16 v[80:83], v[164:167], v[212:215], v[80:83]
	s_setprio 0
	s_setprio 1
	v_mfma_f32_16x16x32_bf16 v[108:111], v[168:171], v[184:187], 0
	v_mfma_f32_16x16x32_bf16 v[100:103], v[176:179], v[184:187], 0
	v_mfma_f32_16x16x32_bf16 v[92:95], v[168:171], v[192:195], 0
	v_mfma_f32_16x16x32_bf16 v[84:87], v[176:179], v[192:195], 0
	v_mfma_f32_16x16x32_bf16 v[76:79], v[168:171], v[200:203], 0
	v_mfma_f32_16x16x32_bf16 v[72:75], v[176:179], v[200:203], 0
	v_mfma_f32_16x16x32_bf16 v[68:71], v[168:171], v[208:211], 0
	v_mfma_f32_16x16x32_bf16 v[64:67], v[176:179], v[208:211], 0
	v_mfma_f32_16x16x32_bf16 v[108:111], v[172:175], v[188:191], v[108:111]
	v_mfma_f32_16x16x32_bf16 v[100:103], v[180:183], v[188:191], v[100:103]
	v_mfma_f32_16x16x32_bf16 v[92:95], v[172:175], v[196:199], v[92:95]
	v_mfma_f32_16x16x32_bf16 v[84:87], v[180:183], v[196:199], v[84:87]
	v_mfma_f32_16x16x32_bf16 v[76:79], v[172:175], v[204:207], v[76:79]
	v_mfma_f32_16x16x32_bf16 v[72:75], v[180:183], v[204:207], v[72:75]
	v_mfma_f32_16x16x32_bf16 v[68:71], v[172:175], v[212:215], v[68:71]
	v_mfma_f32_16x16x32_bf16 v[64:67], v[180:183], v[212:215], v[64:67]
	s_setprio 0
	s_barrier
	s_add_i32 s66, s51, s16
	v_lshl_add_u64 v[216:217], s[64:65], 0, v[130:131]
	s_mov_b32 m0, s66
	ds_read_b128 v[184:187], v161 offset:16384
	ds_read_b128 v[188:191], v161 offset:17408
	ds_read_b128 v[192:195], v161 offset:18432
	ds_read_b128 v[196:199], v161 offset:19456
	ds_read_b128 v[200:203], v161 offset:20480
	ds_read_b128 v[204:207], v161 offset:21504
	ds_read_b128 v[208:211], v161 offset:22528
	ds_read_b128 v[212:215], v161 offset:23552
	global_load_lds_dwordx4 v[216:217], off
	s_add_i32 m0, s66, 0x2000
	v_lshl_add_u64 v[218:219], s[64:65], 0, v[134:135]
	s_add_u32 s64, s64, s6
	s_addc_u32 s65, s65, s7
	s_add_i32 s66, s56, s16
	global_load_lds_dwordx4 v[218:219], off
	v_lshl_add_u64 v[220:221], s[64:65], 0, v[130:131]
	s_mov_b32 m0, s66
	v_lshl_add_u64 v[222:223], s[64:65], 0, v[134:135]
	global_load_lds_dwordx4 v[220:221], off
	s_add_i32 m0, s66, 0x2000
	v_lshl_add_u64 v[224:225], s[34:35], 0, v[128:129]
	global_load_lds_dwordx4 v[222:223], off
	s_mov_b32 m0, s17
	v_lshl_add_u64 v[226:227], s[34:35], 0, v[132:133]
	global_load_lds_dwordx4 v[224:225], off
	s_mov_b32 m0, s19
	s_nop 0
	global_load_lds_dwordx4 v[226:227], off
	s_waitcnt vmcnt(8)
	s_waitcnt lgkmcnt(0)
	s_barrier
; #define PG8_STAGE(bufoff, gbase, voff) do { _Pragma("unroll") for (int _i = 0; _i < 2; ++_i) \
;         __builtin_amdgcn_global_load_lds((const unsigned*)((const char*)(gbase) + (voff)[_i]), (PG8_LAS unsigned*)(lds + (bufoff) + ldsw + _i * 8192), 16, 0, 0); } while (0)
; #define PG8_LDA(dst, b, h) do { _Pragma("unroll") for (int m = 0; m < 4; ++m) _Pragma("unroll") for (int k = 0; k < 2; ++k) dst[m][k] = *(const PG8_LAS bf16x8*)(lds + PG8_SA(b, h) + aoff + m * 2048 + k * 1024); } while (0)
; #define PG8_LDB(dst, b, h) do { _Pragma("unroll") for (int n = 0; n < 2; ++n) _Pragma("unroll") for (int k = 0; k < 2; ++k) dst[n][k] = *(const PG8_LAS bf16x8*)(lds + PG8_SB(b, h) + boff + n * 2048 + k * 1024); } while (0)
; #define PG8_MMA(ai, bj, At, Bt) do { __builtin_amdgcn_s_setprio(1); _Pragma("unroll") for (int m = 0; m < 4; ++m) _Pragma("unroll") for (int n = 0; n < 2; ++n) _Pragma("unroll") for (int k = 0; k < 2; ++k) \
;         acc[ai][bj][m][n] = __builtin_amdgcn_mfma_f32_16x16x32_bf16(Bt[n][k], At[m][k], acc[ai][bj][m][n], 0, 0, 0); __builtin_amdgcn_s_setprio(0); } while (0)
; #define PG8_WAIT_V(n) asm volatile("s_waitcnt vmcnt(" #n ")" ::: "memory")
; #define PG8_WAIT_L(n) asm volatile("s_waitcnt lgkmcnt(" #n ")" ::: "memory")
; #define PG8_BAR __builtin_amdgcn_s_barrier()
; #define PG8_SCHED __builtin_amdgcn_sched_barrier(0)
; template <class Epi, class Sched, bool ALIGN_EPI = false, bool SP2 = false>
; __device__ __forceinline__ void gemm_phase(PG8_LAS unsigned char* lds, const Gemm g, const Sched& S, const Epi& E) {
;     ...
;             PG8_WAIT_V(8); PG8_WAIT_L(0); PG8_BAR; PG8_MMA(1, 0, At, B0); PG8_MMA(1, 1, At, B1); PG8_BAR; PG8_SCHED;
;             PG8_LDB(B0, 1, 0); PG8_LDB(B1, 1, 1); PG8_SCHED; PG8_LDA(At, 1, 0); PG8_STAGE(PG8_SA(0, 1), a2 + hstep, voffA);
;             PG8_WAIT_V(8); PG8_WAIT_L(0); PG8_BAR; PG8_MMA(0, 0, At, B0); PG8_MMA(0, 1, At, B1); PG8_BAR; PG8_SCHED;
	s_setprio 1
	s_waitcnt lgkmcnt(0)
	v_mfma_f32_16x16x32_bf16 v[60:63], v[144:147], v[184:187], 0
	v_mfma_f32_16x16x32_bf16 v[56:59], v[152:155], v[184:187], 0
	v_mfma_f32_16x16x32_bf16 v[52:55], v[144:147], v[192:195], 0
	v_mfma_f32_16x16x32_bf16 v[48:51], v[152:155], v[192:195], 0
	v_mfma_f32_16x16x32_bf16 v[40:43], v[144:147], v[200:203], 0
	v_mfma_f32_16x16x32_bf16 v[32:35], v[152:155], v[200:203], 0
	v_mfma_f32_16x16x32_bf16 v[24:27], v[144:147], v[208:211], 0
	v_mfma_f32_16x16x32_bf16 v[16:19], v[152:155], v[208:211], 0
	v_mfma_f32_16x16x32_bf16 v[60:63], v[148:151], v[188:191], v[60:63]
	v_mfma_f32_16x16x32_bf16 v[56:59], v[164:167], v[188:191], v[56:59]
	v_mfma_f32_16x16x32_bf16 v[52:55], v[148:151], v[196:199], v[52:55]
	v_mfma_f32_16x16x32_bf16 v[48:51], v[164:167], v[196:199], v[48:51]
	v_mfma_f32_16x16x32_bf16 v[40:43], v[148:151], v[204:207], v[40:43]
	v_mfma_f32_16x16x32_bf16 v[32:35], v[164:167], v[204:207], v[32:35]
	v_mfma_f32_16x16x32_bf16 v[24:27], v[148:151], v[212:215], v[24:27]
	v_mfma_f32_16x16x32_bf16 v[16:19], v[164:167], v[212:215], v[16:19]
	s_setprio 0
	s_setprio 1
	v_mfma_f32_16x16x32_bf16 v[44:47], v[168:171], v[184:187], 0
	v_mfma_f32_16x16x32_bf16 v[36:39], v[176:179], v[184:187], 0
	v_mfma_f32_16x16x32_bf16 v[28:31], v[168:171], v[192:195], 0
	v_mfma_f32_16x16x32_bf16 v[20:23], v[176:179], v[192:195], 0
	v_mfma_f32_16x16x32_bf16 v[12:15], v[168:171], v[200:203], 0
	v_mfma_f32_16x16x32_bf16 v[8:11], v[176:179], v[200:203], 0
	v_mfma_f32_16x16x32_bf16 v[4:7], v[168:171], v[208:211], 0
	v_mfma_f32_16x16x32_bf16 v[0:3], v[176:179], v[208:211], 0
	v_mfma_f32_16x16x32_bf16 v[44:47], v[172:175], v[188:191], v[44:47]
	v_mfma_f32_16x16x32_bf16 v[36:39], v[180:183], v[188:191], v[36:39]
	v_mfma_f32_16x16x32_bf16 v[28:31], v[172:175], v[196:199], v[28:31]
	v_mfma_f32_16x16x32_bf16 v[20:23], v[180:183], v[196:199], v[20:23]
	v_mfma_f32_16x16x32_bf16 v[12:15], v[172:175], v[204:207], v[12:15]
	v_mfma_f32_16x16x32_bf16 v[8:11], v[180:183], v[204:207], v[8:11]
	v_mfma_f32_16x16x32_bf16 v[4:7], v[172:175], v[212:215], v[4:7]
	v_mfma_f32_16x16x32_bf16 v[0:3], v[180:183], v[212:215], v[0:3]
	s_setprio 0
	s_barrier
	s_add_i32 s64, 0, 0x18000
	v_add_u32_e32 v163, s64, v157
	s_add_i32 s65, 0, 0x1c000
	ds_read_b128 v[144:147], v163
	ds_read_b128 v[148:151], v163 offset:1024
	ds_read_b128 v[152:155], v163 offset:2048
	ds_read_b128 v[164:167], v163 offset:3072
	v_add_u32_e32 v163, s65, v157
	ds_read_b128 v[168:171], v163
	ds_read_b128 v[172:175], v163 offset:1024
	ds_read_b128 v[176:179], v163 offset:2048
	ds_read_b128 v[180:183], v163 offset:3072
	s_add_u32 s34, s34, s6
	s_addc_u32 s35, s35, s7
	s_mov_b32 m0, s33
	v_lshl_add_u64 v[228:229], s[34:35], 0, v[128:129]
	ds_read_b128 v[184:187], v161 offset:32768
	ds_read_b128 v[188:191], v161 offset:33792
	ds_read_b128 v[192:195], v161 offset:34816
	ds_read_b128 v[196:199], v161 offset:35840
	ds_read_b128 v[200:203], v161 offset:36864
	ds_read_b128 v[204:207], v161 offset:37888
	ds_read_b128 v[208:211], v161 offset:38912
	ds_read_b128 v[212:215], v161 offset:39936
	global_load_lds_dwordx4 v[228:229], off
	v_lshl_add_u64 v[228:229], s[34:35], 0, v[132:133]
	s_mov_b32 m0, s36
	s_nop 0
	global_load_lds_dwordx4 v[228:229], off
	s_waitcnt vmcnt(8)
	s_waitcnt lgkmcnt(0)
	s_barrier
	s_setprio 1
	s_waitcnt lgkmcnt(0)
	v_mfma_f32_16x16x32_bf16 v[124:127], v[144:147], v[184:187], v[124:127]
	v_mfma_f32_16x16x32_bf16 v[120:123], v[152:155], v[184:187], v[120:123]
	v_mfma_f32_16x16x32_bf16 v[116:119], v[144:147], v[192:195], v[116:119]
	v_mfma_f32_16x16x32_bf16 v[112:115], v[152:155], v[192:195], v[112:115]
	v_mfma_f32_16x16x32_bf16 v[104:107], v[144:147], v[200:203], v[104:107]
	v_mfma_f32_16x16x32_bf16 v[96:99], v[152:155], v[200:203], v[96:99]
	v_mfma_f32_16x16x32_bf16 v[88:91], v[144:147], v[208:211], v[88:91]
	v_mfma_f32_16x16x32_bf16 v[80:83], v[152:155], v[208:211], v[80:83]
	v_mfma_f32_16x16x32_bf16 v[124:127], v[148:151], v[188:191], v[124:127]
	v_mfma_f32_16x16x32_bf16 v[120:123], v[164:167], v[188:191], v[120:123]
	v_mfma_f32_16x16x32_bf16 v[116:119], v[148:151], v[196:199], v[116:119]
	v_mfma_f32_16x16x32_bf16 v[112:115], v[164:167], v[196:199], v[112:115]
	v_mfma_f32_16x16x32_bf16 v[104:107], v[148:151], v[204:207], v[104:107]
	v_mfma_f32_16x16x32_bf16 v[96:99], v[164:167], v[204:207], v[96:99]
	v_mfma_f32_16x16x32_bf16 v[88:91], v[148:151], v[212:215], v[88:91]
	v_mfma_f32_16x16x32_bf16 v[80:83], v[164:167], v[212:215], v[80:83]
	s_setprio 0
	s_setprio 1
	v_mfma_f32_16x16x32_bf16 v[108:111], v[168:171], v[184:187], v[108:111]
	v_mfma_f32_16x16x32_bf16 v[100:103], v[176:179], v[184:187], v[100:103]
	v_mfma_f32_16x16x32_bf16 v[92:95], v[168:171], v[192:195], v[92:95]
	v_mfma_f32_16x16x32_bf16 v[84:87], v[176:179], v[192:195], v[84:87]
	v_mfma_f32_16x16x32_bf16 v[76:79], v[168:171], v[200:203], v[76:79]
	v_mfma_f32_16x16x32_bf16 v[72:75], v[176:179], v[200:203], v[72:75]
	v_mfma_f32_16x16x32_bf16 v[68:71], v[168:171], v[208:211], v[68:71]
	v_mfma_f32_16x16x32_bf16 v[64:67], v[176:179], v[208:211], v[64:67]
	v_mfma_f32_16x16x32_bf16 v[108:111], v[172:175], v[188:191], v[108:111]
	v_mfma_f32_16x16x32_bf16 v[100:103], v[180:183], v[188:191], v[100:103]
	v_mfma_f32_16x16x32_bf16 v[92:95], v[172:175], v[196:199], v[92:95]
	v_mfma_f32_16x16x32_bf16 v[84:87], v[180:183], v[196:199], v[84:87]
	v_mfma_f32_16x16x32_bf16 v[76:79], v[172:175], v[204:207], v[76:79]
	v_mfma_f32_16x16x32_bf16 v[72:75], v[180:183], v[204:207], v[72:75]
	v_mfma_f32_16x16x32_bf16 v[68:71], v[172:175], v[212:215], v[68:71]
	v_mfma_f32_16x16x32_bf16 v[64:67], v[180:183], v[212:215], v[64:67]
	s_setprio 0
	s_barrier
; #define PG8_STAGE(bufoff, gbase, voff) do { _Pragma("unroll") for (int _i = 0; _i < 2; ++_i) \
;         __builtin_amdgcn_global_load_lds((const unsigned*)((const char*)(gbase) + (voff)[_i]), (PG8_LAS unsigned*)(lds + (bufoff) + ldsw + _i * 8192), 16, 0, 0); } while (0)
; #define PG8_LDA(dst, b, h) do { _Pragma("unroll") for (int m = 0; m < 4; ++m) _Pragma("unroll") for (int k = 0; k < 2; ++k) dst[m][k] = *(const PG8_LAS bf16x8*)(lds + PG8_SA(b, h) + aoff + m * 2048 + k * 1024); } while (0)
; #define PG8_MMA(ai, bj, At, Bt) do { __builtin_amdgcn_s_setprio(1); _Pragma("unroll") for (int m = 0; m < 4; ++m) _Pragma("unroll") for (int n = 0; n < 2; ++n) _Pragma("unroll") for (int k = 0; k < 2; ++k) \
;         acc[ai][bj][m][n] = __builtin_amdgcn_mfma_f32_16x16x32_bf16(Bt[n][k], At[m][k], acc[ai][bj][m][n], 0, 0, 0); __builtin_amdgcn_s_setprio(0); } while (0)
; #define PG8_WAIT_V(n) asm volatile("s_waitcnt vmcnt(" #n ")" ::: "memory")
; #define PG8_WAIT_L(n) asm volatile("s_waitcnt lgkmcnt(" #n ")" ::: "memory")
; #define PG8_BAR __builtin_amdgcn_s_barrier()
; #define PG8_SCHED __builtin_amdgcn_sched_barrier(0)
; template <class Epi, class Sched, bool ALIGN_EPI = false, bool SP2 = false>
; __device__ __forceinline__ void gemm_phase(PG8_LAS unsigned char* lds, const Gemm g, const Sched& S, const Epi& E) {
;     ...
;         for (int t = 0; t < nt; t += 2) {
;             const bool last = (t == nt - 2);
;             const char* a1 = cA + (size_t)(t + 1) * kstep;
;             const char* a2 = last ? nA : cA + (size_t)(t + 2) * kstep; const char* b2 = last ? nB : cB + (size_t)(t + 2) * kstep;
;             const char* a3 = a2 + kstep; const char* b3 = b2 + kstep;
;     ...
;             PG8_LDA(At, 1, 1); PG8_STAGE(PG8_SB(1, 0), b3, voffB); PG8_STAGE(PG8_SB(1, 1), b3 + hstep, voffB); PG8_STAGE(PG8_SA(1, 0), a3, voffA);
;             PG8_WAIT_V(8); PG8_WAIT_L(0); PG8_BAR; PG8_MMA(1, 0, At, B0); PG8_MMA(1, 1, At, B1); PG8_BAR; PG8_SCHED;
	s_add_i32 s34, s64, s16
	v_lshl_add_u64 v[216:217], v[216:217], 0, s[22:23]
	s_mov_b32 m0, s34
	ds_read_b128 v[184:187], v161 offset:49152
	ds_read_b128 v[188:191], v161 offset:50176
	ds_read_b128 v[192:195], v161 offset:51200
	ds_read_b128 v[196:199], v161 offset:52224
	ds_read_b128 v[200:203], v161 offset:53248
	ds_read_b128 v[204:207], v161 offset:54272
	ds_read_b128 v[208:211], v161 offset:55296
	ds_read_b128 v[212:215], v161 offset:56320
	global_load_lds_dwordx4 v[216:217], off
	v_lshl_add_u64 v[216:217], v[218:219], 0, s[22:23]
	s_add_i32 m0, s34, 0x2000
	s_add_i32 s34, s65, s16
	global_load_lds_dwordx4 v[216:217], off
	v_lshl_add_u64 v[216:217], v[220:221], 0, s[22:23]
	s_mov_b32 m0, s34
	s_nop 0
	global_load_lds_dwordx4 v[216:217], off
	v_lshl_add_u64 v[216:217], v[222:223], 0, s[22:23]
	s_add_i32 m0, s34, 0x2000
	s_nop 0
	global_load_lds_dwordx4 v[216:217], off
	v_lshl_add_u64 v[216:217], v[224:225], 0, s[22:23]
	s_mov_b32 m0, s37
	s_nop 0
	global_load_lds_dwordx4 v[216:217], off
	v_lshl_add_u64 v[216:217], v[226:227], 0, s[22:23]
	s_mov_b32 m0, s38
	s_nop 0
	global_load_lds_dwordx4 v[216:217], off
	s_waitcnt vmcnt(8)
	s_waitcnt lgkmcnt(0)
	s_barrier
	s_setprio 1
	s_waitcnt lgkmcnt(0)
	v_mfma_f32_16x16x32_bf16 v[60:63], v[144:147], v[184:187], v[60:63]
	v_mfma_f32_16x16x32_bf16 v[56:59], v[152:155], v[184:187], v[56:59]
	v_mfma_f32_16x16x32_bf16 v[52:55], v[144:147], v[192:195], v[52:55]
	v_mfma_f32_16x16x32_bf16 v[48:51], v[152:155], v[192:195], v[48:51]
	v_mfma_f32_16x16x32_bf16 v[40:43], v[144:147], v[200:203], v[40:43]
	v_mfma_f32_16x16x32_bf16 v[32:35], v[152:155], v[200:203], v[32:35]
	v_mfma_f32_16x16x32_bf16 v[24:27], v[144:147], v[208:211], v[24:27]
	v_mfma_f32_16x16x32_bf16 v[16:19], v[152:155], v[208:211], v[16:19]
	v_mfma_f32_16x16x32_bf16 v[60:63], v[148:151], v[188:191], v[60:63]
	v_mfma_f32_16x16x32_bf16 v[56:59], v[164:167], v[188:191], v[56:59]
	v_mfma_f32_16x16x32_bf16 v[52:55], v[148:151], v[196:199], v[52:55]
	v_mfma_f32_16x16x32_bf16 v[48:51], v[164:167], v[196:199], v[48:51]
	v_mfma_f32_16x16x32_bf16 v[40:43], v[148:151], v[204:207], v[40:43]
	v_mfma_f32_16x16x32_bf16 v[32:35], v[164:167], v[204:207], v[32:35]
	v_mfma_f32_16x16x32_bf16 v[24:27], v[148:151], v[212:215], v[24:27]
	v_mfma_f32_16x16x32_bf16 v[16:19], v[164:167], v[212:215], v[16:19]
	s_setprio 0
	s_setprio 1
	v_mfma_f32_16x16x32_bf16 v[44:47], v[168:171], v[184:187], v[44:47]
	v_mfma_f32_16x16x32_bf16 v[36:39], v[176:179], v[184:187], v[36:39]
	v_mfma_f32_16x16x32_bf16 v[28:31], v[168:171], v[192:195], v[28:31]
	v_mfma_f32_16x16x32_bf16 v[20:23], v[176:179], v[192:195], v[20:23]
	v_mfma_f32_16x16x32_bf16 v[12:15], v[168:171], v[200:203], v[12:15]
	v_mfma_f32_16x16x32_bf16 v[8:11], v[176:179], v[200:203], v[8:11]
	v_mfma_f32_16x16x32_bf16 v[4:7], v[168:171], v[208:211], v[4:7]
	v_mfma_f32_16x16x32_bf16 v[0:3], v[176:179], v[208:211], v[0:3]
	v_mfma_f32_16x16x32_bf16 v[44:47], v[172:175], v[188:191], v[44:47]
	v_mfma_f32_16x16x32_bf16 v[36:39], v[180:183], v[188:191], v[36:39]
	v_mfma_f32_16x16x32_bf16 v[28:31], v[172:175], v[196:199], v[28:31]
	v_mfma_f32_16x16x32_bf16 v[20:23], v[180:183], v[196:199], v[20:23]
	v_mfma_f32_16x16x32_bf16 v[12:15], v[172:175], v[204:207], v[12:15]
	v_mfma_f32_16x16x32_bf16 v[8:11], v[180:183], v[204:207], v[8:11]
	v_mfma_f32_16x16x32_bf16 v[4:7], v[172:175], v[212:215], v[4:7]
	v_mfma_f32_16x16x32_bf16 v[0:3], v[180:183], v[212:215], v[0:3]
	s_setprio 0
	s_barrier
	s_add_u32 s30, s30, 0x100
	s_addc_u32 s31, s31, 0
	s_add_u32 s61, s61, 0x100
	s_addc_u32 s62, s62, 0
	s_cmp_ge_i32 s63, s40
	s_mov_b32 s34, s63
	s_cbranch_scc0 .LBB0_2575
	s_branch .Lpeel_x13
